# BO3 + mid-block priority window widened: s_setprio 0, two MFMAs, s_setprio 1
# speedup vs baseline: 1.0000x; 1.0000x over previous
; #define PG8_SB(B) __builtin_amdgcn_rcpf(1.f + expneg(B))
; #define PG8_SB(B) __builtin_amdgcn_rcpf(1.f + expneg(B))
; #define PG8_STAGE(bufoff, gbase, voff) do { _Pragma("unroll") for (int _i = 0; _i < 2; ++_i) \
;         __builtin_amdgcn_global_load_lds((const unsigned*)((const char*)(gbase) + (size_t)_i * qstep + (voff)[0]), (PG8_LAS unsigned*)(lds + (bufoff) + ldsw + _i * 8192), 16, 0, 0); } while (0)
; #define PG8_LDA(dst, b, h) do { _Pragma("unroll") for (int m = 0; m < 4; ++m) _Pragma("unroll") for (int k = 0; k < 2; ++k) dst[m][k] = *(const PG8_LAS bf16x8*)(lds + PG8_SA(b, h) + aoff + m * 2048 + k * 1024); } while (0)
; #define PG8_MMA(ai, bj, At, Bt) do { __builtin_amdgcn_s_setprio(1); _Pragma("unroll") for (int m = 0; m < 4; ++m) _Pragma("unroll") for (int n = 0; n < 2; ++n) _Pragma("unroll") for (int k = 0; k < 2; ++k) \
;         acc[ai][bj][m][n] = __builtin_amdgcn_mfma_f32_16x16x32_bf16(Bt[n][k], At[m][k], acc[ai][bj][m][n], 0, 0, 0); __builtin_amdgcn_s_setprio(0); } while (0)
; #define PG8_WAIT_V89() do { if constexpr (SLIVER) PG8_WAIT_V(9); else PG8_WAIT_V(8); } while (0)
; #define PG8_LDS_S(b) do { if constexpr (SLIVER) { Sf[0] = *(const PG8_LAS bf16x8*)(lds + STAGE_BYTES + (b) * 2048 + soff0); Sf[1] = *(const PG8_LAS bf16x8*)(lds + STAGE_BYTES + (b) * 2048 + (soff0 ^ 64)); } } while (0)
; #define PG8_WAIT_L(n) asm volatile("s_waitcnt lgkmcnt(" #n ")" ::: "memory")
; #define PG8_BAR __builtin_amdgcn_s_barrier()
; #define PG8_SCHED __builtin_amdgcn_sched_barrier(0)
; template <class Epi, class Sched, bool ALIGN_EPI = false, bool SP2 = false, bool SLIVER = false>
; __device__ __forceinline__ void gemm_phase(PG8_LAS unsigned char* lds, const Gemm g, const Sched& S, const Epi& E) {
;     ...
;             PG8_WAIT_V89(); PG8_WAIT_L(0); PG8_BAR; PG8_MMA(0, 0, At, B0); PG8_MMA(0, 1, At, B1); PG8_BAR; PG8_SCHED;
;             PG8_LDA(At, 0, 1); PG8_LDS_S(0); PG8_STAGE(PG8_SB(0, 0), b2, voffB); PG8_STAGE(PG8_SB(0, 1), b2 + hstep, voffB); PG8_STAGE(PG8_SA(0, 0), a2, voffA);
;             PG8_WAIT_V89(); PG8_WAIT_L(0); PG8_BAR; PG8_MMA(1, 0, At, B0); PG8_MMA(1, 1, At, B1); PG8_MMA_S(); PG8_BAR; PG8_SCHED;
.Lgin_skipw0:
	s_waitcnt lgkmcnt(0)
	s_setprio 1
	s_barrier
	v_mfma_f32_16x16x32_bf16 v[126:129], v[136:139], v[174:177], v[126:129]
	v_mfma_f32_16x16x32_bf16 v[126:129], v[140:143], v[180:183], v[126:129]
	v_mfma_f32_16x16x32_bf16 v[122:125], v[154:157], v[180:183], v[122:125]
	v_mfma_f32_16x16x32_bf16 v[122:125], v[150:153], v[174:177], v[122:125]
	v_mfma_f32_16x16x32_bf16 v[106:109], v[150:153], v[184:187], v[106:109]
	v_mfma_f32_16x16x32_bf16 v[106:109], v[154:157], v[188:191], v[106:109]
	v_mfma_f32_16x16x32_bf16 v[114:117], v[140:143], v[188:191], v[114:117]
	v_mfma_f32_16x16x32_bf16 v[114:117], v[136:139], v[184:187], v[114:117]
	v_mfma_f32_16x16x32_bf16 v[98:101], v[136:139], v[192:195], v[98:101]
	v_mfma_f32_16x16x32_bf16 v[98:101], v[140:143], v[196:199], v[98:101]
	v_mfma_f32_16x16x32_bf16 v[90:93], v[154:157], v[196:199], v[90:93]
	v_mfma_f32_16x16x32_bf16 v[90:93], v[150:153], v[192:195], v[90:93]
	v_mfma_f32_16x16x32_bf16 v[74:77], v[150:153], v[200:203], v[74:77]
	v_mfma_f32_16x16x32_bf16 v[74:77], v[154:157], v[210:213], v[74:77]
	v_mfma_f32_16x16x32_bf16 v[82:85], v[140:143], v[210:213], v[82:85]
	v_mfma_f32_16x16x32_bf16 v[82:85], v[136:139], v[200:203], v[82:85]
	s_setprio 0
	v_mfma_f32_16x16x32_bf16 v[66:69], v[166:169], v[200:203], v[66:69]
	v_mfma_f32_16x16x32_bf16 v[66:69], v[170:173], v[210:213], v[66:69]
	s_setprio 1
	v_mfma_f32_16x16x32_bf16 v[110:113], v[170:173], v[180:183], v[110:113]
	v_mfma_f32_16x16x32_bf16 v[110:113], v[166:169], v[174:177], v[110:113]
	v_mfma_f32_16x16x32_bf16 v[118:121], v[158:161], v[174:177], v[118:121]
	v_mfma_f32_16x16x32_bf16 v[118:121], v[162:165], v[180:183], v[118:121]
	v_mfma_f32_16x16x32_bf16 v[102:105], v[162:165], v[188:191], v[102:105]
	v_mfma_f32_16x16x32_bf16 v[102:105], v[158:161], v[184:187], v[102:105]
	v_mfma_f32_16x16x32_bf16 v[94:97], v[166:169], v[184:187], v[94:97]
	v_mfma_f32_16x16x32_bf16 v[94:97], v[170:173], v[188:191], v[94:97]
	v_mfma_f32_16x16x32_bf16 v[78:81], v[170:173], v[196:199], v[78:81]
	v_mfma_f32_16x16x32_bf16 v[78:81], v[166:169], v[192:195], v[78:81]
	v_mfma_f32_16x16x32_bf16 v[86:89], v[158:161], v[192:195], v[86:89]
	v_mfma_f32_16x16x32_bf16 v[86:89], v[162:165], v[196:199], v[86:89]
	v_mfma_f32_16x16x32_bf16 v[70:73], v[162:165], v[210:213], v[70:73]
	v_mfma_f32_16x16x32_bf16 v[70:73], v[158:161], v[200:203], v[70:73]
	s_barrier
	s_setprio 0
	s_add_i32 s77, s77, s53
	s_mov_b32 m0, s77
	ds_read_b128 v[174:177], v149 offset:16384
	ds_read_b128 v[180:183], v149 offset:17408
	ds_read_b128 v[184:187], v149 offset:18432
	ds_read_b128 v[188:191], v149 offset:19456
	ds_read_b128 v[192:195], v149 offset:20480
	ds_read_b128 v[196:199], v149 offset:21504
	ds_read_b128 v[200:203], v149 offset:22528
	ds_read_b128 v[210:213], v149 offset:23552
	global_load_lds_dwordx4 v132, s[78:79]
	s_add_i32 m0, s77, 0x2000
	s_add_i32 s77, s80, s53
	s_add_u32 s58, s78, 0x40000
	s_addc_u32 s59, s79, 0
	global_load_lds_dwordx4 v132, s[58:59]
	s_mov_b32 m0, s77
	s_nop 0
	s_add_u32 s60, s78, 0x80000
	s_addc_u32 s61, s79, 0
	global_load_lds_dwordx4 v132, s[60:61]
	s_add_i32 m0, s77, 0x2000
	s_nop 0
	s_add_u32 s36, s78, 0xc0000
	s_addc_u32 s37, s79, 0
	global_load_lds_dwordx4 v132, s[36:37]
	s_mov_b64 s[46:47], s[62:63]
	s_mov_b32 m0, s91
	s_nop 0
	global_load_lds_dwordx4 v130, s[46:47]
	s_mov_b32 m0, s50
	s_nop 0
	s_add_u32 s58, s46, 0x40000
	s_addc_u32 s59, s47, 0
	global_load_lds_dwordx4 v130, s[58:59]
	s_cmp_eq_u32 s76, s101
	s_cbranch_scc1 .Lgin_skipw1
	s_waitcnt vmcnt(8)
.Lgin_skipw1:
	s_waitcnt lgkmcnt(0)
	s_setprio 1
	s_barrier
	v_mfma_f32_16x16x32_bf16 v[62:65], v[136:139], v[174:177], v[62:65]
	v_mfma_f32_16x16x32_bf16 v[62:65], v[140:143], v[180:183], v[62:65]
	v_mfma_f32_16x16x32_bf16 v[58:61], v[154:157], v[180:183], v[58:61]
	v_mfma_f32_16x16x32_bf16 v[58:61], v[150:153], v[174:177], v[58:61]
	v_mfma_f32_16x16x32_bf16 v[42:45], v[150:153], v[184:187], v[42:45]
	v_mfma_f32_16x16x32_bf16 v[42:45], v[154:157], v[188:191], v[42:45]
	v_mfma_f32_16x16x32_bf16 v[50:53], v[140:143], v[188:191], v[50:53]
	v_mfma_f32_16x16x32_bf16 v[50:53], v[136:139], v[184:187], v[50:53]
	v_mfma_f32_16x16x32_bf16 v[34:37], v[136:139], v[192:195], v[34:37]
	v_mfma_f32_16x16x32_bf16 v[34:37], v[140:143], v[196:199], v[34:37]
	v_mfma_f32_16x16x32_bf16 v[26:29], v[154:157], v[196:199], v[26:29]
	v_mfma_f32_16x16x32_bf16 v[26:29], v[150:153], v[192:195], v[26:29]
	v_mfma_f32_16x16x32_bf16 v[10:13], v[150:153], v[200:203], v[10:13]
	v_mfma_f32_16x16x32_bf16 v[10:13], v[154:157], v[210:213], v[10:13]
	v_mfma_f32_16x16x32_bf16 v[18:21], v[140:143], v[210:213], v[18:21]
	v_mfma_f32_16x16x32_bf16 v[18:21], v[136:139], v[200:203], v[18:21]
	s_setprio 0
	v_mfma_f32_16x16x32_bf16 v[2:5], v[166:169], v[200:203], v[2:5]
	v_mfma_f32_16x16x32_bf16 v[2:5], v[170:173], v[210:213], v[2:5]
	s_setprio 1
	v_mfma_f32_16x16x32_bf16 v[46:49], v[170:173], v[180:183], v[46:49]
	v_mfma_f32_16x16x32_bf16 v[46:49], v[166:169], v[174:177], v[46:49]
	v_mfma_f32_16x16x32_bf16 v[54:57], v[158:161], v[174:177], v[54:57]
	v_mfma_f32_16x16x32_bf16 v[54:57], v[162:165], v[180:183], v[54:57]
	v_mfma_f32_16x16x32_bf16 v[38:41], v[162:165], v[188:191], v[38:41]
	v_mfma_f32_16x16x32_bf16 v[38:41], v[158:161], v[184:187], v[38:41]
	v_mfma_f32_16x16x32_bf16 v[30:33], v[166:169], v[184:187], v[30:33]
	v_mfma_f32_16x16x32_bf16 v[30:33], v[170:173], v[188:191], v[30:33]
	v_mfma_f32_16x16x32_bf16 v[14:17], v[170:173], v[196:199], v[14:17]
	v_mfma_f32_16x16x32_bf16 v[14:17], v[166:169], v[192:195], v[14:17]
	v_mfma_f32_16x16x32_bf16 v[22:25], v[158:161], v[192:195], v[22:25]
	v_mfma_f32_16x16x32_bf16 v[22:25], v[162:165], v[196:199], v[22:25]
	v_mfma_f32_16x16x32_bf16 v[6:9], v[162:165], v[210:213], v[6:9]
	v_mfma_f32_16x16x32_bf16 v[6:9], v[158:161], v[200:203], v[6:9]
	s_barrier
; #define PG8_STAGE(bufoff, gbase, voff) do { _Pragma("unroll") for (int _i = 0; _i < 2; ++_i) \
;         __builtin_amdgcn_global_load_lds((const unsigned*)((const char*)(gbase) + (size_t)_i * qstep + (voff)[0]), (PG8_LAS unsigned*)(lds + (bufoff) + ldsw + _i * 8192), 16, 0, 0); } while (0)
; #define PG8_LDA(dst, b, h) do { _Pragma("unroll") for (int m = 0; m < 4; ++m) _Pragma("unroll") for (int k = 0; k < 2; ++k) dst[m][k] = *(const PG8_LAS bf16x8*)(lds + PG8_SA(b, h) + aoff + m * 2048 + k * 1024); } while (0)
; #define PG8_LDB(dst, b, h) do { _Pragma("unroll") for (int n = 0; n < 2; ++n) _Pragma("unroll") for (int k = 0; k < 2; ++k) dst[n][k] = *(const PG8_LAS bf16x8*)(lds + PG8_SB(b, h) + boff + n * 2048 + k * 1024); } while (0)
; #define PG8_MMA(ai, bj, At, Bt) do { __builtin_amdgcn_s_setprio(1); _Pragma("unroll") for (int m = 0; m < 4; ++m) _Pragma("unroll") for (int n = 0; n < 2; ++n) _Pragma("unroll") for (int k = 0; k < 2; ++k) \
;         acc[ai][bj][m][n] = __builtin_amdgcn_mfma_f32_16x16x32_bf16(Bt[n][k], At[m][k], acc[ai][bj][m][n], 0, 0, 0); __builtin_amdgcn_s_setprio(0); } while (0)
; #define PG8_WAIT_V89() do { if constexpr (SLIVER) PG8_WAIT_V(9); else PG8_WAIT_V(8); } while (0)
; #define PG8_STAGE_S(b, gbase) do { if constexpr (SLIVER) __builtin_amdgcn_global_load_lds((const unsigned*)((const char*)(gbase) + voffS), (PG8_LAS unsigned*)(lds + STAGE_BYTES + (b) * 2048 + wid * 256), 4, 0, 0); } while (0)
; #define PG8_WAIT_L(n) asm volatile("s_waitcnt lgkmcnt(" #n ")" ::: "memory")
; #define PG8_BAR __builtin_amdgcn_s_barrier()
; #define PG8_SCHED __builtin_amdgcn_sched_barrier(0)
; template <class Epi, class Sched, bool ALIGN_EPI = false, bool SP2 = false, bool SLIVER = false>
; __device__ __forceinline__ void gemm_phase(PG8_LAS unsigned char* lds, const Gemm g, const Sched& S, const Epi& E) {
;     ...
;             PG8_LDB(B0, 1, 0); PG8_LDB(B1, 1, 1); PG8_SCHED; PG8_LDA(At, 1, 0); PG8_STAGE(PG8_SA(0, 1), a2 + hstep, voffA); PG8_STAGE_S(0, s2);
;             PG8_WAIT_V89(); PG8_WAIT_L(0); PG8_BAR; PG8_MMA(0, 0, At, B0); PG8_MMA(0, 1, At, B1); PG8_BAR; PG8_SCHED;
	s_setprio 0
	s_add_i32 s62, 0, 0x18000
	v_add_u32_e32 v144, s62, v145
	s_add_i32 s63, 0, 0x1c000
	ds_read_b128 v[136:139], v144
	ds_read_b128 v[140:143], v144 offset:1024
	ds_read_b128 v[150:153], v144 offset:2048
	ds_read_b128 v[154:157], v144 offset:3072
	v_add_u32_e32 v144, s63, v145
	ds_read_b128 v[158:161], v144
	ds_read_b128 v[162:165], v144 offset:1024
	ds_read_b128 v[166:169], v144 offset:2048
	ds_read_b128 v[170:173], v144 offset:3072
	s_mov_b32 m0, s51
	ds_read_b128 v[174:177], v149 offset:32768
	ds_read_b128 v[180:183], v149 offset:33792
	ds_read_b128 v[184:187], v149 offset:34816
	ds_read_b128 v[188:191], v149 offset:35840
	ds_read_b128 v[192:195], v149 offset:36864
	ds_read_b128 v[196:199], v149 offset:37888
	ds_read_b128 v[200:203], v149 offset:38912
	ds_read_b128 v[210:213], v149 offset:39936
	s_add_u32 s60, s46, 0x80000
	s_addc_u32 s61, s47, 0
	global_load_lds_dwordx4 v130, s[60:61]
	s_mov_b32 m0, s54
	s_nop 0
	s_add_u32 s36, s46, 0xc0000
	s_addc_u32 s37, s47, 0
	global_load_lds_dwordx4 v130, s[36:37]
	s_waitcnt vmcnt(8)
	s_waitcnt lgkmcnt(0)
	s_setprio 1
	s_barrier
	v_mfma_f32_16x16x32_bf16 v[126:129], v[136:139], v[174:177], v[126:129]
	v_mfma_f32_16x16x32_bf16 v[126:129], v[140:143], v[180:183], v[126:129]
	v_mfma_f32_16x16x32_bf16 v[122:125], v[154:157], v[180:183], v[122:125]
	v_mfma_f32_16x16x32_bf16 v[122:125], v[150:153], v[174:177], v[122:125]
	v_mfma_f32_16x16x32_bf16 v[106:109], v[150:153], v[184:187], v[106:109]
	v_mfma_f32_16x16x32_bf16 v[106:109], v[154:157], v[188:191], v[106:109]
	v_mfma_f32_16x16x32_bf16 v[114:117], v[140:143], v[188:191], v[114:117]
	v_mfma_f32_16x16x32_bf16 v[114:117], v[136:139], v[184:187], v[114:117]
	v_mfma_f32_16x16x32_bf16 v[98:101], v[136:139], v[192:195], v[98:101]
	v_mfma_f32_16x16x32_bf16 v[98:101], v[140:143], v[196:199], v[98:101]
	v_mfma_f32_16x16x32_bf16 v[90:93], v[154:157], v[196:199], v[90:93]
	v_mfma_f32_16x16x32_bf16 v[90:93], v[150:153], v[192:195], v[90:93]
	v_mfma_f32_16x16x32_bf16 v[74:77], v[150:153], v[200:203], v[74:77]
	v_mfma_f32_16x16x32_bf16 v[74:77], v[154:157], v[210:213], v[74:77]
	v_mfma_f32_16x16x32_bf16 v[82:85], v[140:143], v[210:213], v[82:85]
	v_mfma_f32_16x16x32_bf16 v[82:85], v[136:139], v[200:203], v[82:85]
	s_setprio 0
	v_mfma_f32_16x16x32_bf16 v[66:69], v[166:169], v[200:203], v[66:69]
	v_mfma_f32_16x16x32_bf16 v[66:69], v[170:173], v[210:213], v[66:69]
	s_setprio 1
	v_mfma_f32_16x16x32_bf16 v[110:113], v[170:173], v[180:183], v[110:113]
	v_mfma_f32_16x16x32_bf16 v[110:113], v[166:169], v[174:177], v[110:113]
	v_mfma_f32_16x16x32_bf16 v[118:121], v[158:161], v[174:177], v[118:121]
	v_mfma_f32_16x16x32_bf16 v[118:121], v[162:165], v[180:183], v[118:121]
	v_mfma_f32_16x16x32_bf16 v[102:105], v[162:165], v[188:191], v[102:105]
	v_mfma_f32_16x16x32_bf16 v[102:105], v[158:161], v[184:187], v[102:105]
	v_mfma_f32_16x16x32_bf16 v[94:97], v[166:169], v[184:187], v[94:97]
	v_mfma_f32_16x16x32_bf16 v[94:97], v[170:173], v[188:191], v[94:97]
	v_mfma_f32_16x16x32_bf16 v[78:81], v[170:173], v[196:199], v[78:81]
	v_mfma_f32_16x16x32_bf16 v[78:81], v[166:169], v[192:195], v[78:81]
	v_mfma_f32_16x16x32_bf16 v[86:89], v[158:161], v[192:195], v[86:89]
	v_mfma_f32_16x16x32_bf16 v[86:89], v[162:165], v[196:199], v[86:89]
	v_mfma_f32_16x16x32_bf16 v[70:73], v[162:165], v[210:213], v[70:73]
	v_mfma_f32_16x16x32_bf16 v[70:73], v[158:161], v[200:203], v[70:73]
	s_barrier
; #define PG8_SB(B) __builtin_amdgcn_rcpf(1.f + expneg(B))
; #define PG8_SB(B) __builtin_amdgcn_rcpf(1.f + expneg(B))
; #define PG8_STAGE(bufoff, gbase, voff) do { _Pragma("unroll") for (int _i = 0; _i < 2; ++_i) \
;         __builtin_amdgcn_global_load_lds((const unsigned*)((const char*)(gbase) + (size_t)_i * qstep + (voff)[0]), (PG8_LAS unsigned*)(lds + (bufoff) + ldsw + _i * 8192), 16, 0, 0); } while (0)
; #define PG8_LDA(dst, b, h) do { _Pragma("unroll") for (int m = 0; m < 4; ++m) _Pragma("unroll") for (int k = 0; k < 2; ++k) dst[m][k] = *(const PG8_LAS bf16x8*)(lds + PG8_SA(b, h) + aoff + m * 2048 + k * 1024); } while (0)
; #define PG8_MMA(ai, bj, At, Bt) do { __builtin_amdgcn_s_setprio(1); _Pragma("unroll") for (int m = 0; m < 4; ++m) _Pragma("unroll") for (int n = 0; n < 2; ++n) _Pragma("unroll") for (int k = 0; k < 2; ++k) \
;         acc[ai][bj][m][n] = __builtin_amdgcn_mfma_f32_16x16x32_bf16(Bt[n][k], At[m][k], acc[ai][bj][m][n], 0, 0, 0); __builtin_amdgcn_s_setprio(0); } while (0)
; #define PG8_WAIT_V89() do { if constexpr (SLIVER) PG8_WAIT_V(9); else PG8_WAIT_V(8); } while (0)
; #define PG8_LDS_S(b) do { if constexpr (SLIVER) { Sf[0] = *(const PG8_LAS bf16x8*)(lds + STAGE_BYTES + (b) * 2048 + soff0); Sf[1] = *(const PG8_LAS bf16x8*)(lds + STAGE_BYTES + (b) * 2048 + (soff0 ^ 64)); } } while (0)
; #define PG8_WAIT_L(n) asm volatile("s_waitcnt lgkmcnt(" #n ")" ::: "memory")
; #define PG8_BAR __builtin_amdgcn_s_barrier()
; #define PG8_SCHED __builtin_amdgcn_sched_barrier(0)
; template <class Epi, class Sched, bool ALIGN_EPI = false, bool SP2 = false, bool SLIVER = false>
; __device__ __forceinline__ void gemm_phase(PG8_LAS unsigned char* lds, const Gemm g, const Sched& S, const Epi& E) {
;     ...
;             PG8_LDA(At, 1, 1); PG8_LDS_S(1); PG8_STAGE(PG8_SB(1, 0), b3, voffB); PG8_STAGE(PG8_SB(1, 1), b3 + hstep, voffB); PG8_STAGE(PG8_SA(1, 0), a3, voffA);
;             PG8_WAIT_V89(); PG8_WAIT_L(0); PG8_BAR; PG8_MMA(1, 0, At, B0); PG8_MMA(1, 1, At, B1); PG8_MMA_S(); PG8_BAR; PG8_SCHED;
	s_setprio 0
	s_add_i32 s62, s62, s53
	s_mov_b32 m0, s62
	ds_read_b128 v[174:177], v149 offset:49152
	ds_read_b128 v[180:183], v149 offset:50176
	ds_read_b128 v[184:187], v149 offset:51200
	ds_read_b128 v[188:191], v149 offset:52224
	ds_read_b128 v[192:195], v149 offset:53248
	ds_read_b128 v[196:199], v149 offset:54272
	ds_read_b128 v[200:203], v149 offset:55296
	ds_read_b128 v[210:213], v149 offset:56320
	s_add_u32 s58, s78, 0x80
	s_addc_u32 s59, s79, 0
	global_load_lds_dwordx4 v132, s[58:59]
	s_add_i32 m0, s62, 0x2000
	s_add_i32 s62, s63, s53
	s_add_u32 s60, s78, 0x40080
	s_addc_u32 s61, s79, 0
	global_load_lds_dwordx4 v132, s[60:61]
	s_mov_b32 m0, s62
	s_add_u32 s36, s78, 0x80080
	s_addc_u32 s37, s79, 0
	global_load_lds_dwordx4 v132, s[36:37]
	s_add_i32 m0, s62, 0x2000
	s_nop 0
	s_add_u32 s58, s78, 0xc0080
	s_addc_u32 s59, s79, 0
	global_load_lds_dwordx4 v132, s[58:59]
	s_mov_b32 m0, s10
	s_nop 0
	s_add_u32 s60, s46, 0x80
	s_addc_u32 s61, s47, 0
	global_load_lds_dwordx4 v130, s[60:61]
	s_mov_b32 m0, s55
	s_nop 0
	s_add_u32 s36, s46, 0x40080
	s_addc_u32 s37, s47, 0
	global_load_lds_dwordx4 v130, s[36:37]
	s_waitcnt vmcnt(8)
	s_waitcnt lgkmcnt(0)
	s_setprio 1
	s_barrier
	v_mfma_f32_16x16x32_bf16 v[62:65], v[136:139], v[174:177], v[62:65]
	v_mfma_f32_16x16x32_bf16 v[62:65], v[140:143], v[180:183], v[62:65]
	v_mfma_f32_16x16x32_bf16 v[58:61], v[154:157], v[180:183], v[58:61]
	v_mfma_f32_16x16x32_bf16 v[58:61], v[150:153], v[174:177], v[58:61]
	v_mfma_f32_16x16x32_bf16 v[42:45], v[150:153], v[184:187], v[42:45]
	v_mfma_f32_16x16x32_bf16 v[42:45], v[154:157], v[188:191], v[42:45]
	v_mfma_f32_16x16x32_bf16 v[50:53], v[140:143], v[188:191], v[50:53]
	v_mfma_f32_16x16x32_bf16 v[50:53], v[136:139], v[184:187], v[50:53]
	v_mfma_f32_16x16x32_bf16 v[34:37], v[136:139], v[192:195], v[34:37]
	v_mfma_f32_16x16x32_bf16 v[34:37], v[140:143], v[196:199], v[34:37]
	v_mfma_f32_16x16x32_bf16 v[26:29], v[154:157], v[196:199], v[26:29]
	v_mfma_f32_16x16x32_bf16 v[26:29], v[150:153], v[192:195], v[26:29]
	v_mfma_f32_16x16x32_bf16 v[10:13], v[150:153], v[200:203], v[10:13]
	v_mfma_f32_16x16x32_bf16 v[10:13], v[154:157], v[210:213], v[10:13]
	v_mfma_f32_16x16x32_bf16 v[18:21], v[140:143], v[210:213], v[18:21]
	v_mfma_f32_16x16x32_bf16 v[18:21], v[136:139], v[200:203], v[18:21]
	s_setprio 0
	v_mfma_f32_16x16x32_bf16 v[2:5], v[166:169], v[200:203], v[2:5]
	v_mfma_f32_16x16x32_bf16 v[2:5], v[170:173], v[210:213], v[2:5]
	s_setprio 1
	v_mfma_f32_16x16x32_bf16 v[46:49], v[170:173], v[180:183], v[46:49]
	v_mfma_f32_16x16x32_bf16 v[46:49], v[166:169], v[174:177], v[46:49]
	v_mfma_f32_16x16x32_bf16 v[54:57], v[158:161], v[174:177], v[54:57]
	v_mfma_f32_16x16x32_bf16 v[54:57], v[162:165], v[180:183], v[54:57]
	v_mfma_f32_16x16x32_bf16 v[38:41], v[162:165], v[188:191], v[38:41]
	v_mfma_f32_16x16x32_bf16 v[38:41], v[158:161], v[184:187], v[38:41]
	v_mfma_f32_16x16x32_bf16 v[30:33], v[166:169], v[184:187], v[30:33]
	v_mfma_f32_16x16x32_bf16 v[30:33], v[170:173], v[188:191], v[30:33]
	v_mfma_f32_16x16x32_bf16 v[14:17], v[170:173], v[196:199], v[14:17]
	v_mfma_f32_16x16x32_bf16 v[14:17], v[166:169], v[192:195], v[14:17]
	v_mfma_f32_16x16x32_bf16 v[22:25], v[158:161], v[192:195], v[22:25]
	v_mfma_f32_16x16x32_bf16 v[22:25], v[162:165], v[196:199], v[22:25]
	v_mfma_f32_16x16x32_bf16 v[6:9], v[162:165], v[210:213], v[6:9]
	v_mfma_f32_16x16x32_bf16 v[6:9], v[158:161], v[200:203], v[6:9]
	s_barrier
	s_setprio 0
	s_add_i32 s76, s76, 2
	s_add_u32 s40, s40, 0x100
	s_addc_u32 s41, s41, 0
	s_add_u32 s68, s68, 0x100
	s_addc_u32 s69, s69, 0
	s_cmp_gt_u32 s76, 29
	s_cbranch_scc0 .LBB0_153
	s_and_b64 vcc, exec, s[48:49]
	s_cbranch_vccz .LBB0_156
	s_barrier

; #define PG8_STAGE(bufoff, gbase, voff) do { _Pragma("unroll") for (int _i = 0; _i < 2; ++_i) \
;         __builtin_amdgcn_global_load_lds((const unsigned*)((const char*)(gbase) + (size_t)_i * qstep + (voff)[0]), (PG8_LAS unsigned*)(lds + (bufoff) + ldsw + _i * 8192), 16, 0, 0); } while (0)
; #define PG8_LDA(dst, b, h) do { _Pragma("unroll") for (int m = 0; m < 4; ++m) _Pragma("unroll") for (int k = 0; k < 2; ++k) dst[m][k] = *(const PG8_LAS bf16x8*)(lds + PG8_SA(b, h) + aoff + m * 2048 + k * 1024); } while (0)
; #define PG8_LDB(dst, b, h) do { _Pragma("unroll") for (int n = 0; n < 2; ++n) _Pragma("unroll") for (int k = 0; k < 2; ++k) dst[n][k] = *(const PG8_LAS bf16x8*)(lds + PG8_SB(b, h) + boff + n * 2048 + k * 1024); } while (0)
; #define PG8_MMA(ai, bj, At, Bt) do { __builtin_amdgcn_s_setprio(1); _Pragma("unroll") for (int m = 0; m < 4; ++m) _Pragma("unroll") for (int n = 0; n < 2; ++n) _Pragma("unroll") for (int k = 0; k < 2; ++k) \
;         acc[ai][bj][m][n] = __builtin_amdgcn_mfma_f32_16x16x32_bf16(Bt[n][k], At[m][k], acc[ai][bj][m][n], 0, 0, 0); __builtin_amdgcn_s_setprio(0); } while (0)
; #define PG8_WAIT_V89() do { if constexpr (SLIVER) PG8_WAIT_V(9); else PG8_WAIT_V(8); } while (0)
; #define PG8_WAIT_L(n) asm volatile("s_waitcnt lgkmcnt(" #n ")" ::: "memory")
; #define PG8_BAR __builtin_amdgcn_s_barrier()
; #define PG8_SCHED __builtin_amdgcn_sched_barrier(0)
; template <class Epi, class Sched, bool ALIGN_EPI = false, bool SP2 = false, bool SLIVER = false>
; __device__ __forceinline__ void gemm_phase(PG8_LAS unsigned char* lds, const Gemm g, const Sched& S, const Epi& E) {
;     ...
;             const bool last = (t == nt - 2);
;             const char* a1 = cA + (size_t)(t + 1) * kstep;
;             const char* a2 = last ? nA : cA + (size_t)(t + 2) * kstep; const char* b2 = last ? nB : cB + (size_t)(t + 2) * kstep;
;             const char* a3 = a2 + kstep; const char* b3 = b2 + kstep;
;             const char* s1 = cS + (size_t)(t + 1) * kstep; const char* s2 = last ? nS : cS + (size_t)(t + 2) * kstep;
;             if (last && has_next) S.a_ready(nxt);
;             if constexpr (SP2) {
;             PG8_LDB(B0, 0, 0); PG8_LDB(B1, 0, 1); PG8_SCHED; PG8_LDA(At, 0, 0); PG8_STAGE(PG8_SA(1, 1), a1 + hstep, voffA); PG8_STAGE_S(1, s1);
;             PG8_WAIT_V89(); PG8_WAIT_L(0); PG8_BAR; PG8_MMA(0, 0, At, B0); PG8_MMA(0, 1, At, B1); PG8_BAR; PG8_SCHED;
.LBB0_498:
	s_cmp_eq_u32 s66, s80
	s_cselect_b64 s[86:87], -1, 0
	s_add_u32 s40, s16, s80
	s_addc_u32 s41, s17, s81
	s_add_u32 s68, s40, 0x100
	s_addc_u32 s69, s41, 0
	s_and_b64 s[40:41], s[86:87], exec
	s_cselect_b32 s41, s55, s69
	s_cselect_b32 s40, s54, s68
	s_add_u32 s76, s12, s80
	s_addc_u32 s77, s13, s81
	s_add_i32 s78, 0, 0x10000
	s_and_b64 s[68:69], s[86:87], exec
	v_add_u32_e32 v138, s78, v239
	s_cselect_b32 s69, s83, s77
	s_cselect_b32 s68, s82, s76
	s_add_i32 s76, 0, 0x14000
	ds_read_b128 v[146:149], v138
	ds_read_b128 v[150:153], v138 offset:1024
	ds_read_b128 v[154:157], v138 offset:2048
	ds_read_b128 v[158:161], v138 offset:3072
	v_add_u32_e32 v138, s76, v239
	ds_read_b128 v[166:169], v138
	ds_read_b128 v[170:173], v138 offset:1024
	ds_read_b128 v[174:177], v138 offset:2048
	ds_read_b128 v[162:165], v138 offset:3072
	v_lshl_add_u64 v[208:209], v[188:189], 0, s[80:81]
	v_lshl_add_u64 v[224:225], v[208:209], 0, s[34:35]
	s_add_i32 m0, s96, 0xc000
	s_mov_b64 s[88:89], 0x120080
	ds_read_b128 v[138:141], v242
	ds_read_b128 v[142:145], v242 offset:1024
	ds_read_b128 v[180:183], v242 offset:2048
	ds_read_b128 v[184:187], v242 offset:3072
	ds_read_b128 v[192:195], v242 offset:4096
	ds_read_b128 v[196:199], v242 offset:5120
	ds_read_b128 v[200:203], v242 offset:6144
	ds_read_b128 v[220:223], v242 offset:7168
	global_load_lds_dwordx4 v[224:225], off
	v_lshl_add_u64 v[208:209], v[208:209], 0, s[88:89]
	s_add_i32 m0, s96, 0xe000
	s_nop 0
	global_load_lds_dwordx4 v[208:209], off
	v_lshl_add_u64 v[208:209], v[190:191], 0, s[80:81]
	s_add_i32 m0, s94, 0x20800
	s_nop 0
	global_load_lds_dword v[208:209], off
	s_waitcnt vmcnt(9)
	s_waitcnt lgkmcnt(0)
	s_setprio 1
	s_barrier
	v_mfma_f32_16x16x32_bf16 v[134:137], v[146:149], v[138:141], v[134:137]
	v_mfma_f32_16x16x32_bf16 v[134:137], v[150:153], v[142:145], v[134:137]
	v_mfma_f32_16x16x32_bf16 v[130:133], v[158:161], v[142:145], v[130:133]
	v_mfma_f32_16x16x32_bf16 v[130:133], v[154:157], v[138:141], v[130:133]
	v_mfma_f32_16x16x32_bf16 v[122:125], v[154:157], v[180:183], v[122:125]
	v_mfma_f32_16x16x32_bf16 v[122:125], v[158:161], v[184:187], v[122:125]
	v_mfma_f32_16x16x32_bf16 v[126:129], v[150:153], v[184:187], v[126:129]
	v_mfma_f32_16x16x32_bf16 v[126:129], v[146:149], v[180:183], v[126:129]
	v_mfma_f32_16x16x32_bf16 v[118:121], v[146:149], v[192:195], v[118:121]
	v_mfma_f32_16x16x32_bf16 v[118:121], v[150:153], v[196:199], v[118:121]
	v_mfma_f32_16x16x32_bf16 v[114:117], v[158:161], v[196:199], v[114:117]
	v_mfma_f32_16x16x32_bf16 v[114:117], v[154:157], v[192:195], v[114:117]
	v_mfma_f32_16x16x32_bf16 v[106:109], v[154:157], v[200:203], v[106:109]
	v_mfma_f32_16x16x32_bf16 v[106:109], v[158:161], v[220:223], v[106:109]
	v_mfma_f32_16x16x32_bf16 v[110:113], v[150:153], v[220:223], v[110:113]
	v_mfma_f32_16x16x32_bf16 v[110:113], v[146:149], v[200:203], v[110:113]
	s_setprio 0
	v_mfma_f32_16x16x32_bf16 v[66:69], v[174:177], v[200:203], v[66:69]
	v_mfma_f32_16x16x32_bf16 v[66:69], v[162:165], v[220:223], v[66:69]
	s_setprio 1
	v_mfma_f32_16x16x32_bf16 v[98:101], v[162:165], v[142:145], v[98:101]
	v_mfma_f32_16x16x32_bf16 v[98:101], v[174:177], v[138:141], v[98:101]
	v_mfma_f32_16x16x32_bf16 v[102:105], v[166:169], v[138:141], v[102:105]
	v_mfma_f32_16x16x32_bf16 v[102:105], v[170:173], v[142:145], v[102:105]
	v_mfma_f32_16x16x32_bf16 v[90:93], v[170:173], v[184:187], v[90:93]
	v_mfma_f32_16x16x32_bf16 v[90:93], v[166:169], v[180:183], v[90:93]
	v_mfma_f32_16x16x32_bf16 v[86:89], v[174:177], v[180:183], v[86:89]
	v_mfma_f32_16x16x32_bf16 v[86:89], v[162:165], v[184:187], v[86:89]
	v_mfma_f32_16x16x32_bf16 v[74:77], v[162:165], v[196:199], v[74:77]
	v_mfma_f32_16x16x32_bf16 v[74:77], v[174:177], v[192:195], v[74:77]
	v_mfma_f32_16x16x32_bf16 v[78:81], v[166:169], v[192:195], v[78:81]
	v_mfma_f32_16x16x32_bf16 v[78:81], v[170:173], v[196:199], v[78:81]
	v_mfma_f32_16x16x32_bf16 v[70:73], v[170:173], v[220:223], v[70:73]
	v_mfma_f32_16x16x32_bf16 v[70:73], v[166:169], v[200:203], v[70:73]
	s_barrier
; #define PG8_SB(B) __builtin_amdgcn_rcpf(1.f + expneg(B))
; #define PG8_SB(B) __builtin_amdgcn_rcpf(1.f + expneg(B))
; #define PG8_STAGE(bufoff, gbase, voff) do { _Pragma("unroll") for (int _i = 0; _i < 2; ++_i) \
;         __builtin_amdgcn_global_load_lds((const unsigned*)((const char*)(gbase) + (size_t)_i * qstep + (voff)[0]), (PG8_LAS unsigned*)(lds + (bufoff) + ldsw + _i * 8192), 16, 0, 0); } while (0)
; #define PG8_LDA(dst, b, h) do { _Pragma("unroll") for (int m = 0; m < 4; ++m) _Pragma("unroll") for (int k = 0; k < 2; ++k) dst[m][k] = *(const PG8_LAS bf16x8*)(lds + PG8_SA(b, h) + aoff + m * 2048 + k * 1024); } while (0)
; #define PG8_MMA(ai, bj, At, Bt) do { __builtin_amdgcn_s_setprio(1); _Pragma("unroll") for (int m = 0; m < 4; ++m) _Pragma("unroll") for (int n = 0; n < 2; ++n) _Pragma("unroll") for (int k = 0; k < 2; ++k) \
;         acc[ai][bj][m][n] = __builtin_amdgcn_mfma_f32_16x16x32_bf16(Bt[n][k], At[m][k], acc[ai][bj][m][n], 0, 0, 0); __builtin_amdgcn_s_setprio(0); } while (0)
; #define PG8_WAIT_V89() do { if constexpr (SLIVER) PG8_WAIT_V(9); else PG8_WAIT_V(8); } while (0)
; #define PG8_LDS_S(b) do { if constexpr (SLIVER) { Sf[0] = *(const PG8_LAS bf16x8*)(lds + STAGE_BYTES + (b) * 2048 + soff0); Sf[1] = *(const PG8_LAS bf16x8*)(lds + STAGE_BYTES + (b) * 2048 + (soff0 ^ 64)); } } while (0)
; #define PG8_WAIT_L(n) asm volatile("s_waitcnt lgkmcnt(" #n ")" ::: "memory")
; #define PG8_BAR __builtin_amdgcn_s_barrier()
; #define PG8_SCHED __builtin_amdgcn_sched_barrier(0)
; template <class Epi, class Sched, bool ALIGN_EPI = false, bool SP2 = false, bool SLIVER = false>
; __device__ __forceinline__ void gemm_phase(PG8_LAS unsigned char* lds, const Gemm g, const Sched& S, const Epi& E) {
;     ...
;             PG8_LDA(At, 0, 1); PG8_LDS_S(0); PG8_STAGE(PG8_SB(0, 0), b2, voffB); PG8_STAGE(PG8_SB(0, 1), b2 + hstep, voffB); PG8_STAGE(PG8_SA(0, 0), a2, voffA);
;             PG8_WAIT_V89(); PG8_WAIT_L(0); PG8_BAR; PG8_MMA(1, 0, At, B0); PG8_MMA(1, 1, At, B1); PG8_MMA_S(); PG8_BAR; PG8_SCHED;
	s_setprio 0
	s_add_i32 s77, 0, 0x20000
	v_lshl_add_u64 v[192:193], s[68:69], 0, v[212:213]
	s_add_i32 s68, s78, s95
	v_add_u32_e32 v178, s77, v240
	v_add_u32_e32 v184, s77, v241
	s_mov_b32 m0, s68
	s_mov_b64 s[88:89], 0x60000
	ds_read_b128 v[138:141], v242 offset:16384
	ds_read_b128 v[142:145], v242 offset:17408
	ds_read_b128 v[196:199], v242 offset:18432
	ds_read_b128 v[200:203], v242 offset:19456
	ds_read_b128 v[220:223], v242 offset:20480
	ds_read_b128 v[224:227], v242 offset:21504
	ds_read_b128 v[228:231], v242 offset:22528
	ds_read_b128 v[232:235], v242 offset:23552
	ds_read_b128 v[180:183], v178
	ds_read_b128 v[184:187], v184
	global_load_lds_dwordx4 v[192:193], off
	v_lshl_add_u64 v[194:195], v[192:193], 0, s[88:89]
	s_add_i32 m0, s68, 0x2000
	s_add_i32 s68, s76, s95
	global_load_lds_dwordx4 v[194:195], off
	v_lshl_add_u64 v[194:195], v[192:193], 0, s[24:25]
	s_mov_b32 m0, s68
	s_nop 0
	global_load_lds_dwordx4 v[194:195], off
	v_lshl_add_u64 v[194:195], v[192:193], 0, s[14:15]
	s_add_i32 m0, s68, 0x2000
	s_nop 0
	global_load_lds_dwordx4 v[194:195], off
	v_lshl_add_u64 v[194:195], s[40:41], 0, v[210:211]
	s_mov_b32 m0, s96
	v_lshl_add_u64 v[208:209], v[194:195], 0, s[88:89]
	global_load_lds_dwordx4 v[194:195], off
	s_mov_b32 m0, s19
	s_nop 0
	global_load_lds_dwordx4 v[208:209], off
	s_waitcnt vmcnt(9)
	s_waitcnt lgkmcnt(0)
	s_setprio 1
	s_barrier
	v_mfma_f32_16x16x32_bf16 v[62:65], v[146:149], v[138:141], v[62:65]
	v_mfma_f32_16x16x32_bf16 v[62:65], v[150:153], v[142:145], v[62:65]
	v_mfma_f32_16x16x32_bf16 v[58:61], v[158:161], v[142:145], v[58:61]
	v_mfma_f32_16x16x32_bf16 v[58:61], v[154:157], v[138:141], v[58:61]
	v_mfma_f32_16x16x32_bf16 v[50:53], v[154:157], v[196:199], v[50:53]
	v_mfma_f32_16x16x32_bf16 v[50:53], v[158:161], v[200:203], v[50:53]
	v_mfma_f32_16x16x32_bf16 v[54:57], v[150:153], v[200:203], v[54:57]
	v_mfma_f32_16x16x32_bf16 v[54:57], v[146:149], v[196:199], v[54:57]
	v_mfma_f32_16x16x32_bf16 v[46:49], v[146:149], v[220:223], v[46:49]
	v_mfma_f32_16x16x32_bf16 v[46:49], v[150:153], v[224:227], v[46:49]
	v_mfma_f32_16x16x32_bf16 v[42:45], v[158:161], v[224:227], v[42:45]
	v_mfma_f32_16x16x32_bf16 v[42:45], v[154:157], v[220:223], v[42:45]
	v_mfma_f32_16x16x32_bf16 v[34:37], v[154:157], v[228:231], v[34:37]
	v_mfma_f32_16x16x32_bf16 v[34:37], v[158:161], v[232:235], v[34:37]
	v_mfma_f32_16x16x32_bf16 v[38:41], v[150:153], v[232:235], v[38:41]
	v_mfma_f32_16x16x32_bf16 v[38:41], v[146:149], v[228:231], v[38:41]
	s_setprio 0
	v_mfma_f32_16x16x32_bf16 v[2:5], v[174:177], v[228:231], v[2:5]
	v_mfma_f32_16x16x32_bf16 v[2:5], v[162:165], v[232:235], v[2:5]
	s_setprio 1
	v_mfma_f32_16x16x32_bf16 v[26:29], v[162:165], v[142:145], v[26:29]
	v_mfma_f32_16x16x32_bf16 v[26:29], v[174:177], v[138:141], v[26:29]
	v_mfma_f32_16x16x32_bf16 v[30:33], v[166:169], v[138:141], v[30:33]
	v_mfma_f32_16x16x32_bf16 v[30:33], v[170:173], v[142:145], v[30:33]
	v_mfma_f32_16x16x32_bf16 v[22:25], v[170:173], v[200:203], v[22:25]
	v_mfma_f32_16x16x32_bf16 v[22:25], v[166:169], v[196:199], v[22:25]
	v_mfma_f32_16x16x32_bf16 v[18:21], v[174:177], v[196:199], v[18:21]
	v_mfma_f32_16x16x32_bf16 v[18:21], v[162:165], v[200:203], v[18:21]
	v_mfma_f32_16x16x32_bf16 v[10:13], v[162:165], v[224:227], v[10:13]
	v_mfma_f32_16x16x32_bf16 v[10:13], v[174:177], v[220:223], v[10:13]
	v_mfma_f32_16x16x32_bf16 v[14:17], v[166:169], v[220:223], v[14:17]
	v_mfma_f32_16x16x32_bf16 v[14:17], v[170:173], v[224:227], v[14:17]
	v_mfma_f32_16x16x32_bf16 v[6:9], v[170:173], v[232:235], v[6:9]
	v_mfma_f32_16x16x32_bf16 v[6:9], v[166:169], v[228:231], v[6:9]
	s_setprio 0
	s_setprio 1
	s_and_b64 vcc, exec, s[52:53]
	s_cbranch_vccz .Lslv_b0
	v_mfma_f32_16x16x32_bf16 v[138:141], v[166:169], v[180:183], v[82:85]
	v_mfma_f32_16x16x32_bf16 v[142:145], v[174:177], v[180:183], v[94:97]
	v_mfma_f32_16x16x32_bf16 v[138:141], v[170:173], v[184:187], v[138:141]
	v_mfma_f32_16x16x32_bf16 v[142:145], v[162:165], v[184:187], v[142:145]
	s_branch .LBB0_502

; #define PG8_STAGE(bufoff, gbase, voff) do { _Pragma("unroll") for (int _i = 0; _i < 2; ++_i) \
;         __builtin_amdgcn_global_load_lds((const unsigned*)((const char*)(gbase) + (size_t)_i * qstep + (voff)[0]), (PG8_LAS unsigned*)(lds + (bufoff) + ldsw + _i * 8192), 16, 0, 0); } while (0)
; #define PG8_LDA(dst, b, h) do { _Pragma("unroll") for (int m = 0; m < 4; ++m) _Pragma("unroll") for (int k = 0; k < 2; ++k) dst[m][k] = *(const PG8_LAS bf16x8*)(lds + PG8_SA(b, h) + aoff + m * 2048 + k * 1024); } while (0)
; #define PG8_LDB(dst, b, h) do { _Pragma("unroll") for (int n = 0; n < 2; ++n) _Pragma("unroll") for (int k = 0; k < 2; ++k) dst[n][k] = *(const PG8_LAS bf16x8*)(lds + PG8_SB(b, h) + boff + n * 2048 + k * 1024); } while (0)
; #define PG8_MMA(ai, bj, At, Bt) do { __builtin_amdgcn_s_setprio(1); _Pragma("unroll") for (int m = 0; m < 4; ++m) _Pragma("unroll") for (int n = 0; n < 2; ++n) _Pragma("unroll") for (int k = 0; k < 2; ++k) \
;         acc[ai][bj][m][n] = __builtin_amdgcn_mfma_f32_16x16x32_bf16(Bt[n][k], At[m][k], acc[ai][bj][m][n], 0, 0, 0); __builtin_amdgcn_s_setprio(0); } while (0)
; #define PG8_WAIT_V89() do { if constexpr (SLIVER) PG8_WAIT_V(9); else PG8_WAIT_V(8); } while (0)
; #define PG8_STAGE_S(b, gbase) do { if constexpr (SLIVER) __builtin_amdgcn_global_load_lds((const unsigned*)((const char*)(gbase) + voffS), (PG8_LAS unsigned*)(lds + STAGE_BYTES + (b) * 2048 + wid * 256), 4, 0, 0); } while (0)
; #define PG8_WAIT_L(n) asm volatile("s_waitcnt lgkmcnt(" #n ")" ::: "memory")
; #define PG8_BAR __builtin_amdgcn_s_barrier()
; #define PG8_SCHED __builtin_amdgcn_sched_barrier(0)
; template <class Epi, class Sched, bool ALIGN_EPI = false, bool SP2 = false, bool SLIVER = false>
; __device__ __forceinline__ void gemm_phase(PG8_LAS unsigned char* lds, const Gemm g, const Sched& S, const Epi& E) {
;     ...
;             PG8_WAIT_V89(); PG8_WAIT_L(0); PG8_BAR; PG8_MMA(1, 0, At, B0); PG8_MMA(1, 1, At, B1); PG8_MMA_S(); PG8_BAR; PG8_SCHED;
;             PG8_LDB(B0, 1, 0); PG8_LDB(B1, 1, 1); PG8_SCHED; PG8_LDA(At, 1, 0); PG8_STAGE(PG8_SA(0, 1), a2 + hstep, voffA); PG8_STAGE_S(0, s2);
;             PG8_WAIT_V89(); PG8_WAIT_L(0); PG8_BAR; PG8_MMA(0, 0, At, B0); PG8_MMA(0, 1, At, B1); PG8_BAR; PG8_SCHED;
.LBB0_502:
	s_barrier
	s_setprio 0
	s_add_u32 s68, s62, s80
	s_addc_u32 s69, s63, s81
	s_add_u32 s76, s68, 0x100
	s_addc_u32 s77, s69, 0
	s_and_b64 s[68:69], s[86:87], exec
	s_cselect_b32 s69, s85, s77
	s_cselect_b32 s68, s84, s76
	s_add_i32 s76, 0, 0x18000
	v_add_u32_e32 v82, s76, v239
	s_add_i32 s77, 0, 0x1c000
	ds_read_b128 v[146:149], v82
	ds_read_b128 v[150:153], v82 offset:1024
	ds_read_b128 v[154:157], v82 offset:2048
	ds_read_b128 v[158:161], v82 offset:3072
	v_add_u32_e32 v82, s77, v239
	ds_read_b128 v[166:169], v82
	ds_read_b128 v[170:173], v82 offset:1024
	ds_read_b128 v[174:177], v82 offset:2048
	ds_read_b128 v[162:165], v82 offset:3072
	s_mov_b32 m0, s91
	v_lshl_add_u64 v[208:209], v[194:195], 0, s[24:25]
	ds_read_b128 v[82:85], v242 offset:32768
	ds_read_b128 v[94:97], v242 offset:33792
	ds_read_b128 v[180:183], v242 offset:34816
	ds_read_b128 v[184:187], v242 offset:35840
	ds_read_b128 v[196:199], v242 offset:36864
	ds_read_b128 v[200:203], v242 offset:37888
	ds_read_b128 v[220:223], v242 offset:38912
	ds_read_b128 v[224:227], v242 offset:39936
	global_load_lds_dwordx4 v[208:209], off
	v_lshl_add_u64 v[208:209], v[194:195], 0, s[14:15]
	s_mov_b32 m0, s92
	s_nop 0
	global_load_lds_dwordx4 v[208:209], off
	v_lshl_add_u64 v[208:209], s[68:69], 0, v[214:215]
	s_mov_b32 m0, s93
	s_nop 0
	global_load_lds_dword v[208:209], off
	s_waitcnt vmcnt(9)
	s_waitcnt lgkmcnt(0)
	s_setprio 1
	s_barrier
	v_mfma_f32_16x16x32_bf16 v[134:137], v[146:149], v[82:85], v[134:137]
	v_mfma_f32_16x16x32_bf16 v[134:137], v[150:153], v[94:97], v[134:137]
	v_mfma_f32_16x16x32_bf16 v[130:133], v[158:161], v[94:97], v[130:133]
	v_mfma_f32_16x16x32_bf16 v[130:133], v[154:157], v[82:85], v[130:133]
	v_mfma_f32_16x16x32_bf16 v[122:125], v[154:157], v[180:183], v[122:125]
	v_mfma_f32_16x16x32_bf16 v[122:125], v[158:161], v[184:187], v[122:125]
	v_mfma_f32_16x16x32_bf16 v[126:129], v[150:153], v[184:187], v[126:129]
	v_mfma_f32_16x16x32_bf16 v[126:129], v[146:149], v[180:183], v[126:129]
	v_mfma_f32_16x16x32_bf16 v[118:121], v[146:149], v[196:199], v[118:121]
	v_mfma_f32_16x16x32_bf16 v[118:121], v[150:153], v[200:203], v[118:121]
	v_mfma_f32_16x16x32_bf16 v[114:117], v[158:161], v[200:203], v[114:117]
	v_mfma_f32_16x16x32_bf16 v[114:117], v[154:157], v[196:199], v[114:117]
	v_mfma_f32_16x16x32_bf16 v[106:109], v[154:157], v[220:223], v[106:109]
	v_mfma_f32_16x16x32_bf16 v[106:109], v[158:161], v[224:227], v[106:109]
	v_mfma_f32_16x16x32_bf16 v[110:113], v[150:153], v[224:227], v[110:113]
	v_mfma_f32_16x16x32_bf16 v[110:113], v[146:149], v[220:223], v[110:113]
	s_setprio 0
	v_mfma_f32_16x16x32_bf16 v[102:105], v[166:169], v[82:85], v[102:105]
	v_mfma_f32_16x16x32_bf16 v[102:105], v[170:173], v[94:97], v[102:105]
	s_setprio 1
	v_mfma_f32_16x16x32_bf16 v[82:85], v[174:177], v[82:85], v[98:101]
	v_mfma_f32_16x16x32_bf16 v[98:101], v[162:165], v[94:97], v[82:85]
	v_mfma_f32_16x16x32_bf16 v[82:85], v[166:169], v[180:183], v[90:93]
	v_mfma_f32_16x16x32_bf16 v[90:93], v[170:173], v[184:187], v[82:85]
	v_mfma_f32_16x16x32_bf16 v[82:85], v[174:177], v[180:183], v[86:89]
	v_mfma_f32_16x16x32_bf16 v[86:89], v[162:165], v[184:187], v[82:85]
	v_mfma_f32_16x16x32_bf16 v[78:81], v[166:169], v[196:199], v[78:81]
	v_mfma_f32_16x16x32_bf16 v[78:81], v[170:173], v[200:203], v[78:81]
	v_mfma_f32_16x16x32_bf16 v[74:77], v[174:177], v[196:199], v[74:77]
	v_mfma_f32_16x16x32_bf16 v[74:77], v[162:165], v[200:203], v[74:77]
	v_mfma_f32_16x16x32_bf16 v[70:73], v[166:169], v[220:223], v[70:73]
	v_mfma_f32_16x16x32_bf16 v[70:73], v[170:173], v[224:227], v[70:73]
	v_mfma_f32_16x16x32_bf16 v[66:69], v[174:177], v[220:223], v[66:69]
	v_mfma_f32_16x16x32_bf16 v[66:69], v[162:165], v[224:227], v[66:69]
	s_barrier
; #define PG8_SB(B) __builtin_amdgcn_rcpf(1.f + expneg(B))
; #define PG8_SB(B) __builtin_amdgcn_rcpf(1.f + expneg(B))
; #define PG8_STAGE(bufoff, gbase, voff) do { _Pragma("unroll") for (int _i = 0; _i < 2; ++_i) \
;         __builtin_amdgcn_global_load_lds((const unsigned*)((const char*)(gbase) + (size_t)_i * qstep + (voff)[0]), (PG8_LAS unsigned*)(lds + (bufoff) + ldsw + _i * 8192), 16, 0, 0); } while (0)
; #define PG8_LDA(dst, b, h) do { _Pragma("unroll") for (int m = 0; m < 4; ++m) _Pragma("unroll") for (int k = 0; k < 2; ++k) dst[m][k] = *(const PG8_LAS bf16x8*)(lds + PG8_SA(b, h) + aoff + m * 2048 + k * 1024); } while (0)
; #define PG8_MMA(ai, bj, At, Bt) do { __builtin_amdgcn_s_setprio(1); _Pragma("unroll") for (int m = 0; m < 4; ++m) _Pragma("unroll") for (int n = 0; n < 2; ++n) _Pragma("unroll") for (int k = 0; k < 2; ++k) \
;         acc[ai][bj][m][n] = __builtin_amdgcn_mfma_f32_16x16x32_bf16(Bt[n][k], At[m][k], acc[ai][bj][m][n], 0, 0, 0); __builtin_amdgcn_s_setprio(0); } while (0)
; #define PG8_WAIT_V89() do { if constexpr (SLIVER) PG8_WAIT_V(9); else PG8_WAIT_V(8); } while (0)
; #define PG8_LDS_S(b) do { if constexpr (SLIVER) { Sf[0] = *(const PG8_LAS bf16x8*)(lds + STAGE_BYTES + (b) * 2048 + soff0); Sf[1] = *(const PG8_LAS bf16x8*)(lds + STAGE_BYTES + (b) * 2048 + (soff0 ^ 64)); } } while (0)
; #define PG8_WAIT_L(n) asm volatile("s_waitcnt lgkmcnt(" #n ")" ::: "memory")
; #define PG8_BAR __builtin_amdgcn_s_barrier()
; #define PG8_SCHED __builtin_amdgcn_sched_barrier(0)
; template <class Epi, class Sched, bool ALIGN_EPI = false, bool SP2 = false, bool SLIVER = false>
; __device__ __forceinline__ void gemm_phase(PG8_LAS unsigned char* lds, const Gemm g, const Sched& S, const Epi& E) {
;     ...
;             PG8_LDA(At, 1, 1); PG8_LDS_S(1); PG8_STAGE(PG8_SB(1, 0), b3, voffB); PG8_STAGE(PG8_SB(1, 1), b3 + hstep, voffB); PG8_STAGE(PG8_SA(1, 0), a3, voffA);
;             PG8_WAIT_V89(); PG8_WAIT_L(0); PG8_BAR; PG8_MMA(1, 0, At, B0); PG8_MMA(1, 1, At, B1); PG8_MMA_S(); PG8_BAR; PG8_SCHED;
	s_setprio 0
	s_add_i32 s68, 0, 0x20800
	v_add_u32_e32 v178, s68, v240
	v_add_u32_e32 v184, s68, v241
	s_add_i32 s68, s76, s95
	v_lshl_add_u64 v[208:209], v[192:193], 0, s[26:27]
	s_mov_b32 m0, s68
	ds_read_b128 v[82:85], v242 offset:49152
	ds_read_b128 v[94:97], v242 offset:50176
	ds_read_b128 v[196:199], v242 offset:51200
	ds_read_b128 v[200:203], v242 offset:52224
	ds_read_b128 v[220:223], v242 offset:53248
	ds_read_b128 v[224:227], v242 offset:54272
	ds_read_b128 v[228:231], v242 offset:55296
	ds_read_b128 v[232:235], v242 offset:56320
	ds_read_b128 v[180:183], v178
	ds_read_b128 v[184:187], v184
	global_load_lds_dwordx4 v[208:209], off
	v_lshl_add_u64 v[208:209], v[192:193], 0, s[72:73]
	s_add_i32 m0, s68, 0x2000
	s_add_i32 s68, s77, s95
	global_load_lds_dwordx4 v[208:209], off
	v_lshl_add_u64 v[208:209], v[192:193], 0, s[34:35]
	s_mov_b32 m0, s68
	s_mov_b64 s[76:77], 0x120080
	global_load_lds_dwordx4 v[208:209], off
	v_lshl_add_u64 v[192:193], v[192:193], 0, s[76:77]
	s_add_i32 m0, s68, 0x2000
	s_nop 0
	global_load_lds_dwordx4 v[192:193], off
	v_lshl_add_u64 v[192:193], v[194:195], 0, s[26:27]
	s_mov_b32 m0, s97
	s_nop 0
	global_load_lds_dwordx4 v[192:193], off
	v_lshl_add_u64 v[192:193], v[194:195], 0, s[72:73]
	s_mov_b32 m0, s18
	s_nop 0
	global_load_lds_dwordx4 v[192:193], off
	s_waitcnt vmcnt(9)
	s_waitcnt lgkmcnt(0)
	s_setprio 1
	s_barrier
	v_mfma_f32_16x16x32_bf16 v[62:65], v[146:149], v[82:85], v[62:65]
	v_mfma_f32_16x16x32_bf16 v[62:65], v[150:153], v[94:97], v[62:65]
	v_mfma_f32_16x16x32_bf16 v[58:61], v[158:161], v[94:97], v[58:61]
	v_mfma_f32_16x16x32_bf16 v[58:61], v[154:157], v[82:85], v[58:61]
	v_mfma_f32_16x16x32_bf16 v[50:53], v[154:157], v[196:199], v[50:53]
	v_mfma_f32_16x16x32_bf16 v[50:53], v[158:161], v[200:203], v[50:53]
	v_mfma_f32_16x16x32_bf16 v[54:57], v[150:153], v[200:203], v[54:57]
	v_mfma_f32_16x16x32_bf16 v[54:57], v[146:149], v[196:199], v[54:57]
	v_mfma_f32_16x16x32_bf16 v[46:49], v[146:149], v[220:223], v[46:49]
	v_mfma_f32_16x16x32_bf16 v[46:49], v[150:153], v[224:227], v[46:49]
	v_mfma_f32_16x16x32_bf16 v[42:45], v[158:161], v[224:227], v[42:45]
	v_mfma_f32_16x16x32_bf16 v[42:45], v[154:157], v[220:223], v[42:45]
	v_mfma_f32_16x16x32_bf16 v[34:37], v[154:157], v[228:231], v[34:37]
	v_mfma_f32_16x16x32_bf16 v[34:37], v[158:161], v[232:235], v[34:37]
	v_mfma_f32_16x16x32_bf16 v[38:41], v[150:153], v[232:235], v[38:41]
	v_mfma_f32_16x16x32_bf16 v[38:41], v[146:149], v[228:231], v[38:41]
	s_setprio 0
	v_mfma_f32_16x16x32_bf16 v[2:5], v[174:177], v[228:231], v[2:5]
	v_mfma_f32_16x16x32_bf16 v[2:5], v[162:165], v[232:235], v[2:5]
	s_setprio 1
	v_mfma_f32_16x16x32_bf16 v[26:29], v[162:165], v[94:97], v[26:29]
	v_mfma_f32_16x16x32_bf16 v[26:29], v[174:177], v[82:85], v[26:29]
	v_mfma_f32_16x16x32_bf16 v[30:33], v[166:169], v[82:85], v[30:33]
	v_mfma_f32_16x16x32_bf16 v[30:33], v[170:173], v[94:97], v[30:33]
	v_mfma_f32_16x16x32_bf16 v[22:25], v[170:173], v[200:203], v[22:25]
	v_mfma_f32_16x16x32_bf16 v[22:25], v[166:169], v[196:199], v[22:25]
	v_mfma_f32_16x16x32_bf16 v[18:21], v[174:177], v[196:199], v[18:21]
	v_mfma_f32_16x16x32_bf16 v[18:21], v[162:165], v[200:203], v[18:21]
	v_mfma_f32_16x16x32_bf16 v[10:13], v[162:165], v[224:227], v[10:13]
	v_mfma_f32_16x16x32_bf16 v[10:13], v[174:177], v[220:223], v[10:13]
	v_mfma_f32_16x16x32_bf16 v[14:17], v[166:169], v[220:223], v[14:17]
	v_mfma_f32_16x16x32_bf16 v[14:17], v[170:173], v[224:227], v[14:17]
	v_mfma_f32_16x16x32_bf16 v[6:9], v[170:173], v[232:235], v[6:9]
	v_mfma_f32_16x16x32_bf16 v[6:9], v[166:169], v[228:231], v[6:9]
	s_setprio 0
	s_setprio 1
	s_and_b64 vcc, exec, s[52:53]
	s_cbranch_vccz .Lslv_c0
	v_mfma_f32_16x16x32_bf16 v[82:85], v[166:169], v[180:183], v[138:141]
	v_mfma_f32_16x16x32_bf16 v[94:97], v[174:177], v[180:183], v[142:145]
	v_mfma_f32_16x16x32_bf16 v[82:85], v[170:173], v[184:187], v[82:85]
	v_mfma_f32_16x16x32_bf16 v[94:97], v[162:165], v[184:187], v[94:97]
	s_branch .LBB0_497

; #define PG8_STAGE(bufoff, gbase, voff) do { _Pragma("unroll") for (int _i = 0; _i < 2; ++_i) \
;         __builtin_amdgcn_global_load_lds((const unsigned*)((const char*)(gbase) + (size_t)_i * qstep + (voff)[0]), (PG8_LAS unsigned*)(lds + (bufoff) + ldsw + _i * 8192), 16, 0, 0); } while (0)
; #define PG8_LDA(dst, b, h) do { _Pragma("unroll") for (int m = 0; m < 4; ++m) _Pragma("unroll") for (int k = 0; k < 2; ++k) dst[m][k] = *(const PG8_LAS bf16x8*)(lds + PG8_SA(b, h) + aoff + m * 2048 + k * 1024); } while (0)
; #define PG8_LDB(dst, b, h) do { _Pragma("unroll") for (int n = 0; n < 2; ++n) _Pragma("unroll") for (int k = 0; k < 2; ++k) dst[n][k] = *(const PG8_LAS bf16x8*)(lds + PG8_SB(b, h) + boff + n * 2048 + k * 1024); } while (0)
; #define PG8_MMA(ai, bj, At, Bt) do { __builtin_amdgcn_s_setprio(1); _Pragma("unroll") for (int m = 0; m < 4; ++m) _Pragma("unroll") for (int n = 0; n < 2; ++n) _Pragma("unroll") for (int k = 0; k < 2; ++k) \
;         acc[ai][bj][m][n] = __builtin_amdgcn_mfma_f32_16x16x32_bf16(Bt[n][k], At[m][k], acc[ai][bj][m][n], 0, 0, 0); __builtin_amdgcn_s_setprio(0); } while (0)
; #define PG8_WAIT_V89() do { if constexpr (SLIVER) PG8_WAIT_V(9); else PG8_WAIT_V(8); } while (0)
; #define PG8_WAIT_L(n) asm volatile("s_waitcnt lgkmcnt(" #n ")" ::: "memory")
; #define PG8_BAR __builtin_amdgcn_s_barrier()
; #define PG8_SCHED __builtin_amdgcn_sched_barrier(0)
; template <class Epi, class Sched, bool ALIGN_EPI = false, bool SP2 = false, bool SLIVER = false>
; __device__ __forceinline__ void gemm_phase(PG8_LAS unsigned char* lds, const Gemm g, const Sched& S, const Epi& E) {
;     ...
;             const bool last = (t == nt - 2);
;             const char* a1 = cA + (size_t)(t + 1) * kstep;
;             const char* a2 = last ? nA : cA + (size_t)(t + 2) * kstep; const char* b2 = last ? nB : cB + (size_t)(t + 2) * kstep;
;             const char* a3 = a2 + kstep; const char* b3 = b2 + kstep;
;             const char* s1 = cS + (size_t)(t + 1) * kstep; const char* s2 = last ? nS : cS + (size_t)(t + 2) * kstep;
;             if (last && has_next) S.a_ready(nxt);
;             if constexpr (SP2) {
;             PG8_LDB(B0, 0, 0); PG8_LDB(B1, 0, 1); PG8_SCHED; PG8_LDA(At, 0, 0); PG8_STAGE(PG8_SA(1, 1), a1 + hstep, voffA); PG8_STAGE_S(1, s1);
;             PG8_WAIT_V89(); PG8_WAIT_L(0); PG8_BAR; PG8_MMA(0, 0, At, B0); PG8_MMA(0, 1, At, B1); PG8_BAR; PG8_SCHED;
.LBB0_598:
	s_add_u32 s40, s92, s62
	s_addc_u32 s41, s93, s63
	s_add_u32 s77, s40, 0x100
	s_addc_u32 s78, s41, 0
	s_add_u32 s83, s68, s62
	s_addc_u32 s79, s69, s63
	s_add_i32 s96, 0, 0x10000
	s_cmpk_eq_i32 s62, 0xf00
	s_cselect_b64 s[80:81], -1, 0
	s_and_b64 s[40:41], s[80:81], exec
	s_cselect_b32 s41, s12, s78
	s_cselect_b32 s40, s13, s77
	v_add_u32_e32 v138, s96, v212
	s_cselect_b32 s79, s17, s79
	s_cselect_b32 s78, s55, s83
	s_add_i32 s77, 0, 0x14000
	ds_read_b128 v[146:149], v138
	ds_read_b128 v[150:153], v138 offset:1024
	ds_read_b128 v[154:157], v138 offset:2048
	ds_read_b128 v[158:161], v138 offset:3072
	v_add_u32_e32 v138, s77, v212
	ds_read_b128 v[166:169], v138
	ds_read_b128 v[170:173], v138 offset:1024
	ds_read_b128 v[174:177], v138 offset:2048
	ds_read_b128 v[162:165], v138 offset:3072
	v_lshl_add_u64 v[202:203], v[200:201], 0, s[62:63]
	v_lshl_add_u64 v[208:209], v[202:203], 0, s[30:31]
	s_add_i32 m0, s85, 0xc000
	ds_read_b128 v[138:141], v215
	ds_read_b128 v[142:145], v215 offset:1024
	ds_read_b128 v[180:183], v215 offset:2048
	ds_read_b128 v[184:187], v215 offset:3072
	ds_read_b128 v[216:219], v215 offset:4096
	ds_read_b128 v[220:223], v215 offset:5120
	ds_read_b128 v[224:227], v215 offset:6144
	ds_read_b128 v[228:231], v215 offset:7168
	global_load_lds_dwordx4 v[208:209], off
	v_lshl_add_u64 v[202:203], v[202:203], 0, s[34:35]
	s_add_i32 m0, s85, 0xe000
	s_nop 0
	global_load_lds_dwordx4 v[202:203], off
	v_lshl_add_u64 v[202:203], v[198:199], 0, s[62:63]
	s_add_i32 m0, s45, 0x20800
	s_nop 0
	global_load_lds_dword v[202:203], off
	s_waitcnt vmcnt(9)
	s_waitcnt lgkmcnt(0)
	s_setprio 1
	s_barrier
	v_mfma_f32_16x16x32_bf16 v[134:137], v[146:149], v[138:141], v[134:137]
	v_mfma_f32_16x16x32_bf16 v[134:137], v[150:153], v[142:145], v[134:137]
	v_mfma_f32_16x16x32_bf16 v[130:133], v[158:161], v[142:145], v[130:133]
	v_mfma_f32_16x16x32_bf16 v[130:133], v[154:157], v[138:141], v[130:133]
	v_mfma_f32_16x16x32_bf16 v[114:117], v[154:157], v[180:183], v[114:117]
	v_mfma_f32_16x16x32_bf16 v[114:117], v[158:161], v[184:187], v[114:117]
	v_mfma_f32_16x16x32_bf16 v[118:121], v[150:153], v[184:187], v[118:121]
	v_mfma_f32_16x16x32_bf16 v[118:121], v[146:149], v[180:183], v[118:121]
	v_mfma_f32_16x16x32_bf16 v[102:105], v[146:149], v[216:219], v[102:105]
	v_mfma_f32_16x16x32_bf16 v[102:105], v[150:153], v[220:223], v[102:105]
	v_mfma_f32_16x16x32_bf16 v[98:101], v[158:161], v[220:223], v[98:101]
	v_mfma_f32_16x16x32_bf16 v[98:101], v[154:157], v[216:219], v[98:101]
	v_mfma_f32_16x16x32_bf16 v[82:85], v[154:157], v[224:227], v[82:85]
	v_mfma_f32_16x16x32_bf16 v[82:85], v[158:161], v[228:231], v[82:85]
	v_mfma_f32_16x16x32_bf16 v[86:89], v[150:153], v[228:231], v[86:89]
	v_mfma_f32_16x16x32_bf16 v[86:89], v[146:149], v[224:227], v[86:89]
	s_setprio 0
	v_mfma_f32_16x16x32_bf16 v[74:77], v[174:177], v[224:227], v[74:77]
	v_mfma_f32_16x16x32_bf16 v[74:77], v[162:165], v[228:231], v[74:77]
	s_setprio 1
	v_mfma_f32_16x16x32_bf16 v[122:125], v[162:165], v[142:145], v[122:125]
	v_mfma_f32_16x16x32_bf16 v[122:125], v[174:177], v[138:141], v[122:125]
	v_mfma_f32_16x16x32_bf16 v[126:129], v[166:169], v[138:141], v[126:129]
	v_mfma_f32_16x16x32_bf16 v[126:129], v[170:173], v[142:145], v[126:129]
	v_mfma_f32_16x16x32_bf16 v[110:113], v[170:173], v[184:187], v[110:113]
	v_mfma_f32_16x16x32_bf16 v[110:113], v[166:169], v[180:183], v[110:113]
	v_mfma_f32_16x16x32_bf16 v[106:109], v[174:177], v[180:183], v[106:109]
	v_mfma_f32_16x16x32_bf16 v[106:109], v[162:165], v[184:187], v[106:109]
	v_mfma_f32_16x16x32_bf16 v[90:93], v[162:165], v[220:223], v[90:93]
	v_mfma_f32_16x16x32_bf16 v[90:93], v[174:177], v[216:219], v[90:93]
	v_mfma_f32_16x16x32_bf16 v[94:97], v[166:169], v[216:219], v[94:97]
	v_mfma_f32_16x16x32_bf16 v[94:97], v[170:173], v[220:223], v[94:97]
	v_mfma_f32_16x16x32_bf16 v[78:81], v[170:173], v[228:231], v[78:81]
	v_mfma_f32_16x16x32_bf16 v[78:81], v[166:169], v[224:227], v[78:81]
	s_barrier
; #define PG8_SB(B) __builtin_amdgcn_rcpf(1.f + expneg(B))
; #define PG8_SB(B) __builtin_amdgcn_rcpf(1.f + expneg(B))
; #define PG8_STAGE(bufoff, gbase, voff) do { _Pragma("unroll") for (int _i = 0; _i < 2; ++_i) \
;         __builtin_amdgcn_global_load_lds((const unsigned*)((const char*)(gbase) + (size_t)_i * qstep + (voff)[0]), (PG8_LAS unsigned*)(lds + (bufoff) + ldsw + _i * 8192), 16, 0, 0); } while (0)
; #define PG8_LDA(dst, b, h) do { _Pragma("unroll") for (int m = 0; m < 4; ++m) _Pragma("unroll") for (int k = 0; k < 2; ++k) dst[m][k] = *(const PG8_LAS bf16x8*)(lds + PG8_SA(b, h) + aoff + m * 2048 + k * 1024); } while (0)
; #define PG8_MMA(ai, bj, At, Bt) do { __builtin_amdgcn_s_setprio(1); _Pragma("unroll") for (int m = 0; m < 4; ++m) _Pragma("unroll") for (int n = 0; n < 2; ++n) _Pragma("unroll") for (int k = 0; k < 2; ++k) \
;         acc[ai][bj][m][n] = __builtin_amdgcn_mfma_f32_16x16x32_bf16(Bt[n][k], At[m][k], acc[ai][bj][m][n], 0, 0, 0); __builtin_amdgcn_s_setprio(0); } while (0)
; #define PG8_WAIT_V89() do { if constexpr (SLIVER) PG8_WAIT_V(9); else PG8_WAIT_V(8); } while (0)
; #define PG8_LDS_S(b) do { if constexpr (SLIVER) { Sf[0] = *(const PG8_LAS bf16x8*)(lds + STAGE_BYTES + (b) * 2048 + soff0); Sf[1] = *(const PG8_LAS bf16x8*)(lds + STAGE_BYTES + (b) * 2048 + (soff0 ^ 64)); } } while (0)
; #define PG8_WAIT_L(n) asm volatile("s_waitcnt lgkmcnt(" #n ")" ::: "memory")
; #define PG8_BAR __builtin_amdgcn_s_barrier()
; #define PG8_SCHED __builtin_amdgcn_sched_barrier(0)
; template <class Epi, class Sched, bool ALIGN_EPI = false, bool SP2 = false, bool SLIVER = false>
; __device__ __forceinline__ void gemm_phase(PG8_LAS unsigned char* lds, const Gemm g, const Sched& S, const Epi& E) {
;     ...
;             PG8_LDA(At, 0, 1); PG8_LDS_S(0); PG8_STAGE(PG8_SB(0, 0), b2, voffB); PG8_STAGE(PG8_SB(0, 1), b2 + hstep, voffB); PG8_STAGE(PG8_SA(0, 0), a2, voffA);
;             PG8_WAIT_V89(); PG8_WAIT_L(0); PG8_BAR; PG8_MMA(1, 0, At, B0); PG8_MMA(1, 1, At, B1); PG8_MMA_S(); PG8_BAR; PG8_SCHED;
	s_setprio 0
	s_add_i32 s83, 0, 0x20000
	v_lshl_add_u64 v[202:203], s[78:79], 0, v[190:191]
	s_add_i32 s78, s96, s18
	v_add_u32_e32 v178, s83, v213
	v_add_u32_e32 v184, s83, v214
	s_mov_b32 m0, s78
	ds_read_b128 v[138:141], v215 offset:16384
	ds_read_b128 v[142:145], v215 offset:17408
	ds_read_b128 v[216:219], v215 offset:18432
	ds_read_b128 v[220:223], v215 offset:19456
	ds_read_b128 v[224:227], v215 offset:20480
	ds_read_b128 v[228:231], v215 offset:21504
	ds_read_b128 v[232:235], v215 offset:22528
	ds_read_b128 v[240:243], v215 offset:23552
	ds_read_b128 v[180:183], v178
	ds_read_b128 v[184:187], v184
	global_load_lds_dwordx4 v[202:203], off
	v_lshl_add_u64 v[208:209], v[202:203], 0, s[20:21]
	s_add_i32 m0, s78, 0x2000
	s_add_i32 s77, s77, s18
	global_load_lds_dwordx4 v[208:209], off
	v_lshl_add_u64 v[208:209], v[202:203], 0, s[22:23]
	s_mov_b32 m0, s77
	v_lshl_add_u64 v[210:211], s[40:41], 0, v[188:189]
	global_load_lds_dwordx4 v[208:209], off
	v_lshl_add_u64 v[208:209], v[202:203], 0, s[24:25]
	s_add_i32 m0, s77, 0x2000
	s_nop 0
	global_load_lds_dwordx4 v[208:209], off
	s_mov_b32 m0, s85
	v_lshl_add_u64 v[208:209], v[210:211], 0, s[20:21]
	global_load_lds_dwordx4 v[210:211], off
	s_mov_b32 m0, s19
	s_nop 0
	global_load_lds_dwordx4 v[208:209], off
	s_waitcnt vmcnt(9)
	s_waitcnt lgkmcnt(0)
	s_setprio 1
	s_barrier
	v_mfma_f32_16x16x32_bf16 v[70:73], v[146:149], v[138:141], v[70:73]
	v_mfma_f32_16x16x32_bf16 v[70:73], v[150:153], v[142:145], v[70:73]
	v_mfma_f32_16x16x32_bf16 v[66:69], v[158:161], v[142:145], v[66:69]
	v_mfma_f32_16x16x32_bf16 v[66:69], v[154:157], v[138:141], v[66:69]
	v_mfma_f32_16x16x32_bf16 v[50:53], v[154:157], v[216:219], v[50:53]
	v_mfma_f32_16x16x32_bf16 v[50:53], v[158:161], v[220:223], v[50:53]
	v_mfma_f32_16x16x32_bf16 v[54:57], v[150:153], v[220:223], v[54:57]
	v_mfma_f32_16x16x32_bf16 v[54:57], v[146:149], v[216:219], v[54:57]
	v_mfma_f32_16x16x32_bf16 v[38:41], v[146:149], v[224:227], v[38:41]
	v_mfma_f32_16x16x32_bf16 v[38:41], v[150:153], v[228:231], v[38:41]
	v_mfma_f32_16x16x32_bf16 v[34:37], v[158:161], v[228:231], v[34:37]
	v_mfma_f32_16x16x32_bf16 v[34:37], v[154:157], v[224:227], v[34:37]
	v_mfma_f32_16x16x32_bf16 v[18:21], v[154:157], v[232:235], v[18:21]
	v_mfma_f32_16x16x32_bf16 v[18:21], v[158:161], v[240:243], v[18:21]
	v_mfma_f32_16x16x32_bf16 v[22:25], v[150:153], v[240:243], v[22:25]
	v_mfma_f32_16x16x32_bf16 v[22:25], v[146:149], v[232:235], v[22:25]
	s_setprio 0
	v_mfma_f32_16x16x32_bf16 v[10:13], v[174:177], v[232:235], v[10:13]
	v_mfma_f32_16x16x32_bf16 v[10:13], v[162:165], v[240:243], v[10:13]
	s_setprio 1
	v_mfma_f32_16x16x32_bf16 v[58:61], v[162:165], v[142:145], v[58:61]
	v_mfma_f32_16x16x32_bf16 v[58:61], v[174:177], v[138:141], v[58:61]
	v_mfma_f32_16x16x32_bf16 v[62:65], v[166:169], v[138:141], v[62:65]
	v_mfma_f32_16x16x32_bf16 v[62:65], v[170:173], v[142:145], v[62:65]
	v_mfma_f32_16x16x32_bf16 v[46:49], v[170:173], v[220:223], v[46:49]
	v_mfma_f32_16x16x32_bf16 v[46:49], v[166:169], v[216:219], v[46:49]
	v_mfma_f32_16x16x32_bf16 v[42:45], v[174:177], v[216:219], v[42:45]
	v_mfma_f32_16x16x32_bf16 v[42:45], v[162:165], v[220:223], v[42:45]
	v_mfma_f32_16x16x32_bf16 v[26:29], v[162:165], v[228:231], v[26:29]
	v_mfma_f32_16x16x32_bf16 v[26:29], v[174:177], v[224:227], v[26:29]
	v_mfma_f32_16x16x32_bf16 v[30:33], v[166:169], v[224:227], v[30:33]
	v_mfma_f32_16x16x32_bf16 v[30:33], v[170:173], v[228:231], v[30:33]
	v_mfma_f32_16x16x32_bf16 v[14:17], v[170:173], v[240:243], v[14:17]
	v_mfma_f32_16x16x32_bf16 v[14:17], v[166:169], v[232:235], v[14:17]
	s_setprio 0
	s_setprio 1
	s_and_b64 vcc, exec, s[52:53]
	s_cbranch_vccz .Lslv_b1
	v_mfma_f32_16x16x32_bf16 v[138:141], v[166:169], v[180:183], v[6:9]
	v_mfma_f32_16x16x32_bf16 v[142:145], v[174:177], v[180:183], v[2:5]
	v_mfma_f32_16x16x32_bf16 v[138:141], v[170:173], v[184:187], v[138:141]
	v_mfma_f32_16x16x32_bf16 v[142:145], v[162:165], v[184:187], v[142:145]
	s_branch .LBB0_602

; #define PG8_STAGE(bufoff, gbase, voff) do { _Pragma("unroll") for (int _i = 0; _i < 2; ++_i) \
;         __builtin_amdgcn_global_load_lds((const unsigned*)((const char*)(gbase) + (size_t)_i * qstep + (voff)[0]), (PG8_LAS unsigned*)(lds + (bufoff) + ldsw + _i * 8192), 16, 0, 0); } while (0)
; #define PG8_LDA(dst, b, h) do { _Pragma("unroll") for (int m = 0; m < 4; ++m) _Pragma("unroll") for (int k = 0; k < 2; ++k) dst[m][k] = *(const PG8_LAS bf16x8*)(lds + PG8_SA(b, h) + aoff + m * 2048 + k * 1024); } while (0)
; #define PG8_LDB(dst, b, h) do { _Pragma("unroll") for (int n = 0; n < 2; ++n) _Pragma("unroll") for (int k = 0; k < 2; ++k) dst[n][k] = *(const PG8_LAS bf16x8*)(lds + PG8_SB(b, h) + boff + n * 2048 + k * 1024); } while (0)
; #define PG8_MMA(ai, bj, At, Bt) do { __builtin_amdgcn_s_setprio(1); _Pragma("unroll") for (int m = 0; m < 4; ++m) _Pragma("unroll") for (int n = 0; n < 2; ++n) _Pragma("unroll") for (int k = 0; k < 2; ++k) \
;         acc[ai][bj][m][n] = __builtin_amdgcn_mfma_f32_16x16x32_bf16(Bt[n][k], At[m][k], acc[ai][bj][m][n], 0, 0, 0); __builtin_amdgcn_s_setprio(0); } while (0)
; #define PG8_WAIT_V89() do { if constexpr (SLIVER) PG8_WAIT_V(9); else PG8_WAIT_V(8); } while (0)
; #define PG8_STAGE_S(b, gbase) do { if constexpr (SLIVER) __builtin_amdgcn_global_load_lds((const unsigned*)((const char*)(gbase) + voffS), (PG8_LAS unsigned*)(lds + STAGE_BYTES + (b) * 2048 + wid * 256), 4, 0, 0); } while (0)
; #define PG8_WAIT_L(n) asm volatile("s_waitcnt lgkmcnt(" #n ")" ::: "memory")
; #define PG8_BAR __builtin_amdgcn_s_barrier()
; #define PG8_SCHED __builtin_amdgcn_sched_barrier(0)
; template <class Epi, class Sched, bool ALIGN_EPI = false, bool SP2 = false, bool SLIVER = false>
; __device__ __forceinline__ void gemm_phase(PG8_LAS unsigned char* lds, const Gemm g, const Sched& S, const Epi& E) {
;     ...
;             PG8_WAIT_V89(); PG8_WAIT_L(0); PG8_BAR; PG8_MMA(1, 0, At, B0); PG8_MMA(1, 1, At, B1); PG8_MMA_S(); PG8_BAR; PG8_SCHED;
;             PG8_LDB(B0, 1, 0); PG8_LDB(B1, 1, 1); PG8_SCHED; PG8_LDA(At, 1, 0); PG8_STAGE(PG8_SA(0, 1), a2 + hstep, voffA); PG8_STAGE_S(0, s2);
;             PG8_WAIT_V89(); PG8_WAIT_L(0); PG8_BAR; PG8_MMA(0, 0, At, B0); PG8_MMA(0, 1, At, B1); PG8_BAR; PG8_SCHED;
.LBB0_602:
	s_barrier
	s_setprio 0
	s_add_u32 s77, s94, s62
	s_addc_u32 s78, s95, s63
	s_add_u32 s77, s77, 0x100
	s_addc_u32 s83, s78, 0
	s_and_b64 s[78:79], s[80:81], exec
	s_cselect_b32 s79, s66, s83
	s_cselect_b32 s78, s67, s77
	s_add_i32 s77, 0, 0x18000
	v_add_u32_e32 v2, s77, v212
	s_add_i32 s80, 0, 0x1c000
	ds_read_b128 v[146:149], v2
	ds_read_b128 v[150:153], v2 offset:1024
	ds_read_b128 v[154:157], v2 offset:2048
	ds_read_b128 v[158:161], v2 offset:3072
	v_add_u32_e32 v2, s80, v212
	ds_read_b128 v[166:169], v2
	ds_read_b128 v[170:173], v2 offset:1024
	ds_read_b128 v[174:177], v2 offset:2048
	ds_read_b128 v[162:165], v2 offset:3072
	s_mov_b32 m0, s49
	v_lshl_add_u64 v[208:209], v[210:211], 0, s[22:23]
	ds_read_b128 v[2:5], v215 offset:32768
	ds_read_b128 v[6:9], v215 offset:33792
	ds_read_b128 v[180:183], v215 offset:34816
	ds_read_b128 v[184:187], v215 offset:35840
	ds_read_b128 v[216:219], v215 offset:36864
	ds_read_b128 v[220:223], v215 offset:37888
	ds_read_b128 v[224:227], v215 offset:38912
	ds_read_b128 v[228:231], v215 offset:39936
	global_load_lds_dwordx4 v[208:209], off
	v_lshl_add_u64 v[208:209], v[210:211], 0, s[24:25]
	s_mov_b32 m0, s50
	s_nop 0
	global_load_lds_dwordx4 v[208:209], off
	v_lshl_add_u64 v[208:209], s[78:79], 0, v[192:193]
	s_mov_b32 m0, s51
	s_nop 0
	global_load_lds_dword v[208:209], off
	s_waitcnt vmcnt(9)
	s_waitcnt lgkmcnt(0)
	s_setprio 1
	s_barrier
	v_mfma_f32_16x16x32_bf16 v[134:137], v[146:149], v[2:5], v[134:137]
	v_mfma_f32_16x16x32_bf16 v[134:137], v[150:153], v[6:9], v[134:137]
	v_mfma_f32_16x16x32_bf16 v[130:133], v[158:161], v[6:9], v[130:133]
	v_mfma_f32_16x16x32_bf16 v[130:133], v[154:157], v[2:5], v[130:133]
	v_mfma_f32_16x16x32_bf16 v[114:117], v[154:157], v[180:183], v[114:117]
	v_mfma_f32_16x16x32_bf16 v[114:117], v[158:161], v[184:187], v[114:117]
	v_mfma_f32_16x16x32_bf16 v[118:121], v[150:153], v[184:187], v[118:121]
	v_mfma_f32_16x16x32_bf16 v[118:121], v[146:149], v[180:183], v[118:121]
	v_mfma_f32_16x16x32_bf16 v[102:105], v[146:149], v[216:219], v[102:105]
	v_mfma_f32_16x16x32_bf16 v[102:105], v[150:153], v[220:223], v[102:105]
	v_mfma_f32_16x16x32_bf16 v[98:101], v[158:161], v[220:223], v[98:101]
	v_mfma_f32_16x16x32_bf16 v[98:101], v[154:157], v[216:219], v[98:101]
	v_mfma_f32_16x16x32_bf16 v[82:85], v[154:157], v[224:227], v[82:85]
	v_mfma_f32_16x16x32_bf16 v[82:85], v[158:161], v[228:231], v[82:85]
	v_mfma_f32_16x16x32_bf16 v[86:89], v[150:153], v[228:231], v[86:89]
	v_mfma_f32_16x16x32_bf16 v[86:89], v[146:149], v[224:227], v[86:89]
	s_setprio 0
	v_mfma_f32_16x16x32_bf16 v[126:129], v[166:169], v[2:5], v[126:129]
	v_mfma_f32_16x16x32_bf16 v[126:129], v[170:173], v[6:9], v[126:129]
	s_setprio 1
	v_mfma_f32_16x16x32_bf16 v[2:5], v[174:177], v[2:5], v[122:125]
	v_mfma_f32_16x16x32_bf16 v[122:125], v[162:165], v[6:9], v[2:5]
	v_mfma_f32_16x16x32_bf16 v[2:5], v[166:169], v[180:183], v[110:113]
	v_mfma_f32_16x16x32_bf16 v[110:113], v[170:173], v[184:187], v[2:5]
	v_mfma_f32_16x16x32_bf16 v[2:5], v[174:177], v[180:183], v[106:109]
	v_mfma_f32_16x16x32_bf16 v[106:109], v[162:165], v[184:187], v[2:5]
	v_mfma_f32_16x16x32_bf16 v[2:5], v[166:169], v[216:219], v[94:97]
	v_mfma_f32_16x16x32_bf16 v[94:97], v[170:173], v[220:223], v[2:5]
	v_mfma_f32_16x16x32_bf16 v[2:5], v[174:177], v[216:219], v[90:93]
	v_mfma_f32_16x16x32_bf16 v[90:93], v[162:165], v[220:223], v[2:5]
	v_mfma_f32_16x16x32_bf16 v[2:5], v[166:169], v[224:227], v[78:81]
	v_mfma_f32_16x16x32_bf16 v[78:81], v[170:173], v[228:231], v[2:5]
	v_mfma_f32_16x16x32_bf16 v[2:5], v[174:177], v[224:227], v[74:77]
	v_mfma_f32_16x16x32_bf16 v[74:77], v[162:165], v[228:231], v[2:5]
	s_barrier
; #define PG8_SB(B) __builtin_amdgcn_rcpf(1.f + expneg(B))
; #define PG8_SB(B) __builtin_amdgcn_rcpf(1.f + expneg(B))
; #define PG8_STAGE(bufoff, gbase, voff) do { _Pragma("unroll") for (int _i = 0; _i < 2; ++_i) \
;         __builtin_amdgcn_global_load_lds((const unsigned*)((const char*)(gbase) + (size_t)_i * qstep + (voff)[0]), (PG8_LAS unsigned*)(lds + (bufoff) + ldsw + _i * 8192), 16, 0, 0); } while (0)
; #define PG8_LDA(dst, b, h) do { _Pragma("unroll") for (int m = 0; m < 4; ++m) _Pragma("unroll") for (int k = 0; k < 2; ++k) dst[m][k] = *(const PG8_LAS bf16x8*)(lds + PG8_SA(b, h) + aoff + m * 2048 + k * 1024); } while (0)
; #define PG8_MMA(ai, bj, At, Bt) do { __builtin_amdgcn_s_setprio(1); _Pragma("unroll") for (int m = 0; m < 4; ++m) _Pragma("unroll") for (int n = 0; n < 2; ++n) _Pragma("unroll") for (int k = 0; k < 2; ++k) \
;         acc[ai][bj][m][n] = __builtin_amdgcn_mfma_f32_16x16x32_bf16(Bt[n][k], At[m][k], acc[ai][bj][m][n], 0, 0, 0); __builtin_amdgcn_s_setprio(0); } while (0)
; #define PG8_WAIT_V89() do { if constexpr (SLIVER) PG8_WAIT_V(9); else PG8_WAIT_V(8); } while (0)
; #define PG8_LDS_S(b) do { if constexpr (SLIVER) { Sf[0] = *(const PG8_LAS bf16x8*)(lds + STAGE_BYTES + (b) * 2048 + soff0); Sf[1] = *(const PG8_LAS bf16x8*)(lds + STAGE_BYTES + (b) * 2048 + (soff0 ^ 64)); } } while (0)
; #define PG8_WAIT_L(n) asm volatile("s_waitcnt lgkmcnt(" #n ")" ::: "memory")
; #define PG8_BAR __builtin_amdgcn_s_barrier()
; #define PG8_SCHED __builtin_amdgcn_sched_barrier(0)
; template <class Epi, class Sched, bool ALIGN_EPI = false, bool SP2 = false, bool SLIVER = false>
; __device__ __forceinline__ void gemm_phase(PG8_LAS unsigned char* lds, const Gemm g, const Sched& S, const Epi& E) {
;     ...
;             PG8_LDA(At, 1, 1); PG8_LDS_S(1); PG8_STAGE(PG8_SB(1, 0), b3, voffB); PG8_STAGE(PG8_SB(1, 1), b3 + hstep, voffB); PG8_STAGE(PG8_SA(1, 0), a3, voffA);
;             PG8_WAIT_V89(); PG8_WAIT_L(0); PG8_BAR; PG8_MMA(1, 0, At, B0); PG8_MMA(1, 1, At, B1); PG8_MMA_S(); PG8_BAR; PG8_SCHED;
	s_setprio 0
	s_add_i32 s78, 0, 0x20800
	s_add_i32 s77, s77, s18
	v_add_u32_e32 v178, s78, v213
	v_add_u32_e32 v184, s78, v214
	v_lshl_add_u64 v[208:209], v[202:203], 0, s[26:27]
	s_mov_b32 m0, s77
	ds_read_b128 v[2:5], v215 offset:49152
	ds_read_b128 v[6:9], v215 offset:50176
	ds_read_b128 v[216:219], v215 offset:51200
	ds_read_b128 v[220:223], v215 offset:52224
	ds_read_b128 v[224:227], v215 offset:53248
	ds_read_b128 v[228:231], v215 offset:54272
	ds_read_b128 v[232:235], v215 offset:55296
	ds_read_b128 v[240:243], v215 offset:56320
	ds_read_b128 v[180:183], v178
	ds_read_b128 v[184:187], v184
	global_load_lds_dwordx4 v[208:209], off
	v_lshl_add_u64 v[208:209], v[202:203], 0, s[28:29]
	s_add_i32 m0, s77, 0x2000
	s_add_i32 s77, s80, s18
	global_load_lds_dwordx4 v[208:209], off
	v_lshl_add_u64 v[208:209], v[202:203], 0, s[30:31]
	s_mov_b32 m0, s77
	v_lshl_add_u64 v[202:203], v[202:203], 0, s[34:35]
	global_load_lds_dwordx4 v[208:209], off
	s_add_i32 m0, s77, 0x2000
	s_nop 0
	global_load_lds_dwordx4 v[202:203], off
	v_lshl_add_u64 v[202:203], v[210:211], 0, s[26:27]
	s_mov_b32 m0, s10
	s_nop 0
	global_load_lds_dwordx4 v[202:203], off
	v_lshl_add_u64 v[202:203], v[210:211], 0, s[28:29]
	s_mov_b32 m0, s2
	s_nop 0
	global_load_lds_dwordx4 v[202:203], off
	s_waitcnt vmcnt(9)
	s_waitcnt lgkmcnt(0)
	s_setprio 1
	s_barrier
	v_mfma_f32_16x16x32_bf16 v[70:73], v[146:149], v[2:5], v[70:73]
	v_mfma_f32_16x16x32_bf16 v[70:73], v[150:153], v[6:9], v[70:73]
	v_mfma_f32_16x16x32_bf16 v[66:69], v[158:161], v[6:9], v[66:69]
	v_mfma_f32_16x16x32_bf16 v[66:69], v[154:157], v[2:5], v[66:69]
	v_mfma_f32_16x16x32_bf16 v[50:53], v[154:157], v[216:219], v[50:53]
	v_mfma_f32_16x16x32_bf16 v[50:53], v[158:161], v[220:223], v[50:53]
	v_mfma_f32_16x16x32_bf16 v[54:57], v[150:153], v[220:223], v[54:57]
	v_mfma_f32_16x16x32_bf16 v[54:57], v[146:149], v[216:219], v[54:57]
	v_mfma_f32_16x16x32_bf16 v[38:41], v[146:149], v[224:227], v[38:41]
	v_mfma_f32_16x16x32_bf16 v[38:41], v[150:153], v[228:231], v[38:41]
	v_mfma_f32_16x16x32_bf16 v[34:37], v[158:161], v[228:231], v[34:37]
	v_mfma_f32_16x16x32_bf16 v[34:37], v[154:157], v[224:227], v[34:37]
	v_mfma_f32_16x16x32_bf16 v[18:21], v[154:157], v[232:235], v[18:21]
	v_mfma_f32_16x16x32_bf16 v[18:21], v[158:161], v[240:243], v[18:21]
	v_mfma_f32_16x16x32_bf16 v[22:25], v[150:153], v[240:243], v[22:25]
	v_mfma_f32_16x16x32_bf16 v[22:25], v[146:149], v[232:235], v[22:25]
	s_setprio 0
	v_mfma_f32_16x16x32_bf16 v[62:65], v[166:169], v[2:5], v[62:65]
	v_mfma_f32_16x16x32_bf16 v[62:65], v[170:173], v[6:9], v[62:65]
	s_setprio 1
	v_mfma_f32_16x16x32_bf16 v[2:5], v[174:177], v[2:5], v[58:61]
	v_mfma_f32_16x16x32_bf16 v[58:61], v[162:165], v[6:9], v[2:5]
	v_mfma_f32_16x16x32_bf16 v[2:5], v[166:169], v[216:219], v[46:49]
	v_mfma_f32_16x16x32_bf16 v[46:49], v[170:173], v[220:223], v[2:5]
	v_mfma_f32_16x16x32_bf16 v[2:5], v[174:177], v[216:219], v[42:45]
	v_mfma_f32_16x16x32_bf16 v[42:45], v[162:165], v[220:223], v[2:5]
	v_mfma_f32_16x16x32_bf16 v[2:5], v[166:169], v[224:227], v[30:33]
	v_mfma_f32_16x16x32_bf16 v[30:33], v[170:173], v[228:231], v[2:5]
	v_mfma_f32_16x16x32_bf16 v[2:5], v[174:177], v[224:227], v[26:29]
	v_mfma_f32_16x16x32_bf16 v[26:29], v[162:165], v[228:231], v[2:5]
	v_mfma_f32_16x16x32_bf16 v[2:5], v[166:169], v[232:235], v[14:17]
	v_mfma_f32_16x16x32_bf16 v[14:17], v[170:173], v[240:243], v[2:5]
	v_mfma_f32_16x16x32_bf16 v[2:5], v[174:177], v[232:235], v[10:13]
	v_mfma_f32_16x16x32_bf16 v[10:13], v[162:165], v[240:243], v[2:5]
	s_setprio 0
	s_setprio 1
	s_and_b64 vcc, exec, s[52:53]
	s_cbranch_vccz .Lslv_c1
	v_mfma_f32_16x16x32_bf16 v[2:5], v[166:169], v[180:183], v[138:141]
	v_mfma_f32_16x16x32_bf16 v[6:9], v[170:173], v[184:187], v[2:5]
	v_mfma_f32_16x16x32_bf16 v[2:5], v[174:177], v[180:183], v[142:145]
	v_mfma_f32_16x16x32_bf16 v[2:5], v[162:165], v[184:187], v[2:5]
	s_branch .LBB0_597

; #define PG8_SB(B) __builtin_amdgcn_rcpf(1.f + expneg(B))
; #define PG8_SB(B) __builtin_amdgcn_rcpf(1.f + expneg(B))
; #define PG8_STAGE(bufoff, gbase, voff) do { _Pragma("unroll") for (int _i = 0; _i < 2; ++_i) \
;         __builtin_amdgcn_global_load_lds((const unsigned*)((const char*)(gbase) + (size_t)_i * qstep + (voff)[0]), (PG8_LAS unsigned*)(lds + (bufoff) + ldsw + _i * 8192), 16, 0, 0); } while (0)
; #define PG8_LDA(dst, b, h) do { _Pragma("unroll") for (int m = 0; m < 4; ++m) _Pragma("unroll") for (int k = 0; k < 2; ++k) dst[m][k] = *(const PG8_LAS bf16x8*)(lds + PG8_SA(b, h) + aoff + m * 2048 + k * 1024); } while (0)
; #define PG8_MMA(ai, bj, At, Bt) do { __builtin_amdgcn_s_setprio(1); _Pragma("unroll") for (int m = 0; m < 4; ++m) _Pragma("unroll") for (int n = 0; n < 2; ++n) _Pragma("unroll") for (int k = 0; k < 2; ++k) \
;         acc[ai][bj][m][n] = __builtin_amdgcn_mfma_f32_16x16x32_bf16(Bt[n][k], At[m][k], acc[ai][bj][m][n], 0, 0, 0); __builtin_amdgcn_s_setprio(0); } while (0)
; #define PG8_WAIT_V89() do { if constexpr (SLIVER) PG8_WAIT_V(9); else PG8_WAIT_V(8); } while (0)
; #define PG8_LDS_S(b) do { if constexpr (SLIVER) { Sf[0] = *(const PG8_LAS bf16x8*)(lds + STAGE_BYTES + (b) * 2048 + soff0); Sf[1] = *(const PG8_LAS bf16x8*)(lds + STAGE_BYTES + (b) * 2048 + (soff0 ^ 64)); } } while (0)
; #define PG8_WAIT_L(n) asm volatile("s_waitcnt lgkmcnt(" #n ")" ::: "memory")
; #define PG8_BAR __builtin_amdgcn_s_barrier()
; #define PG8_SCHED __builtin_amdgcn_sched_barrier(0)
; template <class Epi, class Sched, bool ALIGN_EPI = false, bool SP2 = false, bool SLIVER = false>
; __device__ __forceinline__ void gemm_phase(PG8_LAS unsigned char* lds, const Gemm g, const Sched& S, const Epi& E) {
;     ...
;             PG8_WAIT_V89(); PG8_WAIT_L(0); PG8_BAR; PG8_MMA(0, 0, At, B0); PG8_MMA(0, 1, At, B1); PG8_BAR; PG8_SCHED;
;             PG8_LDA(At, 0, 1); PG8_LDS_S(0); PG8_STAGE(PG8_SB(0, 0), b2, voffB); PG8_STAGE(PG8_SB(0, 1), b2 + hstep, voffB); PG8_STAGE(PG8_SA(0, 0), a2, voffA);
;             PG8_WAIT_V89(); PG8_WAIT_L(0); PG8_BAR; PG8_MMA(1, 0, At, B0); PG8_MMA(1, 1, At, B1); PG8_MMA_S(); PG8_BAR; PG8_SCHED;
.Lgup_skipw0:
	s_waitcnt lgkmcnt(0)
	s_setprio 1
	s_barrier
	v_mfma_f32_16x16x32_bf16 v[126:129], v[130:133], v[172:175], v[126:129]
	v_mfma_f32_16x16x32_bf16 v[126:129], v[138:141], v[180:183], v[126:129]
	v_mfma_f32_16x16x32_bf16 v[118:121], v[152:155], v[180:183], v[118:121]
	v_mfma_f32_16x16x32_bf16 v[118:121], v[148:151], v[172:175], v[118:121]
	v_mfma_f32_16x16x32_bf16 v[102:105], v[148:151], v[184:187], v[102:105]
	v_mfma_f32_16x16x32_bf16 v[102:105], v[152:155], v[188:191], v[102:105]
	v_mfma_f32_16x16x32_bf16 v[110:113], v[138:141], v[188:191], v[110:113]
	v_mfma_f32_16x16x32_bf16 v[110:113], v[130:133], v[184:187], v[110:113]
	v_mfma_f32_16x16x32_bf16 v[94:97], v[130:133], v[192:195], v[94:97]
	v_mfma_f32_16x16x32_bf16 v[94:97], v[138:141], v[196:199], v[94:97]
	v_mfma_f32_16x16x32_bf16 v[86:89], v[152:155], v[196:199], v[86:89]
	v_mfma_f32_16x16x32_bf16 v[86:89], v[148:151], v[192:195], v[86:89]
	v_mfma_f32_16x16x32_bf16 v[70:73], v[148:151], v[200:203], v[70:73]
	v_mfma_f32_16x16x32_bf16 v[70:73], v[152:155], v[210:213], v[70:73]
	v_mfma_f32_16x16x32_bf16 v[78:81], v[138:141], v[210:213], v[78:81]
	v_mfma_f32_16x16x32_bf16 v[78:81], v[130:133], v[200:203], v[78:81]
	s_setprio 0
	v_mfma_f32_16x16x32_bf16 v[66:69], v[164:167], v[200:203], v[66:69]
	v_mfma_f32_16x16x32_bf16 v[66:69], v[168:171], v[210:213], v[66:69]
	s_setprio 1
	v_mfma_f32_16x16x32_bf16 v[114:117], v[168:171], v[180:183], v[114:117]
	v_mfma_f32_16x16x32_bf16 v[114:117], v[164:167], v[172:175], v[114:117]
	v_mfma_f32_16x16x32_bf16 v[122:125], v[156:159], v[172:175], v[122:125]
	v_mfma_f32_16x16x32_bf16 v[122:125], v[160:163], v[180:183], v[122:125]
	v_mfma_f32_16x16x32_bf16 v[106:109], v[160:163], v[188:191], v[106:109]
	v_mfma_f32_16x16x32_bf16 v[106:109], v[156:159], v[184:187], v[106:109]
	v_mfma_f32_16x16x32_bf16 v[98:101], v[164:167], v[184:187], v[98:101]
	v_mfma_f32_16x16x32_bf16 v[98:101], v[168:171], v[188:191], v[98:101]
	v_mfma_f32_16x16x32_bf16 v[82:85], v[168:171], v[196:199], v[82:85]
	v_mfma_f32_16x16x32_bf16 v[82:85], v[164:167], v[192:195], v[82:85]
	v_mfma_f32_16x16x32_bf16 v[90:93], v[156:159], v[192:195], v[90:93]
	v_mfma_f32_16x16x32_bf16 v[90:93], v[160:163], v[196:199], v[90:93]
	v_mfma_f32_16x16x32_bf16 v[74:77], v[160:163], v[210:213], v[74:77]
	v_mfma_f32_16x16x32_bf16 v[74:77], v[156:159], v[200:203], v[74:77]
	s_barrier
	s_setprio 0
	s_mov_b64 s[46:47], s[76:77]
	s_add_i32 s76, s78, s88
	s_mov_b32 m0, s76
	ds_read_b128 v[172:175], v147 offset:16384
	ds_read_b128 v[180:183], v147 offset:17408
	ds_read_b128 v[184:187], v147 offset:18432
	ds_read_b128 v[188:191], v147 offset:19456
	ds_read_b128 v[192:195], v147 offset:20480
	ds_read_b128 v[196:199], v147 offset:21504
	ds_read_b128 v[200:203], v147 offset:22528
	ds_read_b128 v[210:213], v147 offset:23552
	global_load_lds_dwordx4 v178, s[46:47]
	s_add_i32 m0, s76, 0x2000
	s_add_i32 s76, s79, s88
	s_add_u32 s58, s46, 0x40000
	s_addc_u32 s59, s47, 0
	global_load_lds_dwordx4 v178, s[58:59]
	s_mov_b32 m0, s76
	s_nop 0
	s_add_u32 s60, s46, 0x80000
	s_addc_u32 s61, s47, 0
	global_load_lds_dwordx4 v178, s[60:61]
	s_add_i32 m0, s76, 0x2000
	s_nop 0
	s_add_u32 s36, s46, 0xc0000
	s_addc_u32 s37, s47, 0
	global_load_lds_dwordx4 v178, s[36:37]
	s_mov_b32 m0, s45
	s_nop 0
	global_load_lds_dwordx4 v134, s[80:81]
	s_mov_b32 m0, s83
	s_nop 0
	s_add_u32 s58, s80, 0x40000
	s_addc_u32 s59, s81, 0
	global_load_lds_dwordx4 v134, s[58:59]
	s_cmp_eq_u32 s69, s101
	s_cbranch_scc1 .Lgup_skipw1
	s_waitcnt vmcnt(8)
.Lgup_skipw1:
	s_waitcnt lgkmcnt(0)
	s_setprio 1
	s_barrier
	v_mfma_f32_16x16x32_bf16 v[62:65], v[130:133], v[172:175], v[62:65]
	v_mfma_f32_16x16x32_bf16 v[62:65], v[138:141], v[180:183], v[62:65]
	v_mfma_f32_16x16x32_bf16 v[54:57], v[152:155], v[180:183], v[54:57]
	v_mfma_f32_16x16x32_bf16 v[54:57], v[148:151], v[172:175], v[54:57]
	v_mfma_f32_16x16x32_bf16 v[38:41], v[148:151], v[184:187], v[38:41]
	v_mfma_f32_16x16x32_bf16 v[38:41], v[152:155], v[188:191], v[38:41]
	v_mfma_f32_16x16x32_bf16 v[46:49], v[138:141], v[188:191], v[46:49]
	v_mfma_f32_16x16x32_bf16 v[46:49], v[130:133], v[184:187], v[46:49]
	v_mfma_f32_16x16x32_bf16 v[30:33], v[130:133], v[192:195], v[30:33]
	v_mfma_f32_16x16x32_bf16 v[30:33], v[138:141], v[196:199], v[30:33]
	v_mfma_f32_16x16x32_bf16 v[22:25], v[152:155], v[196:199], v[22:25]
	v_mfma_f32_16x16x32_bf16 v[22:25], v[148:151], v[192:195], v[22:25]
	v_mfma_f32_16x16x32_bf16 v[6:9], v[148:151], v[200:203], v[6:9]
	v_mfma_f32_16x16x32_bf16 v[6:9], v[152:155], v[210:213], v[6:9]
	v_mfma_f32_16x16x32_bf16 v[14:17], v[138:141], v[210:213], v[14:17]
	v_mfma_f32_16x16x32_bf16 v[14:17], v[130:133], v[200:203], v[14:17]
	s_setprio 0
	v_mfma_f32_16x16x32_bf16 v[2:5], v[164:167], v[200:203], v[2:5]
	v_mfma_f32_16x16x32_bf16 v[2:5], v[168:171], v[210:213], v[2:5]
	s_setprio 1
	v_mfma_f32_16x16x32_bf16 v[50:53], v[168:171], v[180:183], v[50:53]
	v_mfma_f32_16x16x32_bf16 v[50:53], v[164:167], v[172:175], v[50:53]
	v_mfma_f32_16x16x32_bf16 v[58:61], v[156:159], v[172:175], v[58:61]
	v_mfma_f32_16x16x32_bf16 v[58:61], v[160:163], v[180:183], v[58:61]
	v_mfma_f32_16x16x32_bf16 v[42:45], v[160:163], v[188:191], v[42:45]
	v_mfma_f32_16x16x32_bf16 v[42:45], v[156:159], v[184:187], v[42:45]
	v_mfma_f32_16x16x32_bf16 v[34:37], v[164:167], v[184:187], v[34:37]
	v_mfma_f32_16x16x32_bf16 v[34:37], v[168:171], v[188:191], v[34:37]
	v_mfma_f32_16x16x32_bf16 v[18:21], v[168:171], v[196:199], v[18:21]
	v_mfma_f32_16x16x32_bf16 v[18:21], v[164:167], v[192:195], v[18:21]
	v_mfma_f32_16x16x32_bf16 v[26:29], v[156:159], v[192:195], v[26:29]
	v_mfma_f32_16x16x32_bf16 v[26:29], v[160:163], v[196:199], v[26:29]
	v_mfma_f32_16x16x32_bf16 v[10:13], v[160:163], v[210:213], v[10:13]
	v_mfma_f32_16x16x32_bf16 v[10:13], v[156:159], v[200:203], v[10:13]
	s_barrier
; #define PG8_STAGE(bufoff, gbase, voff) do { _Pragma("unroll") for (int _i = 0; _i < 2; ++_i) \
;         __builtin_amdgcn_global_load_lds((const unsigned*)((const char*)(gbase) + (size_t)_i * qstep + (voff)[0]), (PG8_LAS unsigned*)(lds + (bufoff) + ldsw + _i * 8192), 16, 0, 0); } while (0)
; #define PG8_LDA(dst, b, h) do { _Pragma("unroll") for (int m = 0; m < 4; ++m) _Pragma("unroll") for (int k = 0; k < 2; ++k) dst[m][k] = *(const PG8_LAS bf16x8*)(lds + PG8_SA(b, h) + aoff + m * 2048 + k * 1024); } while (0)
; #define PG8_LDB(dst, b, h) do { _Pragma("unroll") for (int n = 0; n < 2; ++n) _Pragma("unroll") for (int k = 0; k < 2; ++k) dst[n][k] = *(const PG8_LAS bf16x8*)(lds + PG8_SB(b, h) + boff + n * 2048 + k * 1024); } while (0)
; #define PG8_MMA(ai, bj, At, Bt) do { __builtin_amdgcn_s_setprio(1); _Pragma("unroll") for (int m = 0; m < 4; ++m) _Pragma("unroll") for (int n = 0; n < 2; ++n) _Pragma("unroll") for (int k = 0; k < 2; ++k) \
;         acc[ai][bj][m][n] = __builtin_amdgcn_mfma_f32_16x16x32_bf16(Bt[n][k], At[m][k], acc[ai][bj][m][n], 0, 0, 0); __builtin_amdgcn_s_setprio(0); } while (0)
; #define PG8_WAIT_V89() do { if constexpr (SLIVER) PG8_WAIT_V(9); else PG8_WAIT_V(8); } while (0)
; #define PG8_STAGE_S(b, gbase) do { if constexpr (SLIVER) __builtin_amdgcn_global_load_lds((const unsigned*)((const char*)(gbase) + voffS), (PG8_LAS unsigned*)(lds + STAGE_BYTES + (b) * 2048 + wid * 256), 4, 0, 0); } while (0)
; #define PG8_WAIT_L(n) asm volatile("s_waitcnt lgkmcnt(" #n ")" ::: "memory")
; #define PG8_BAR __builtin_amdgcn_s_barrier()
; #define PG8_SCHED __builtin_amdgcn_sched_barrier(0)
; template <class Epi, class Sched, bool ALIGN_EPI = false, bool SP2 = false, bool SLIVER = false>
; __device__ __forceinline__ void gemm_phase(PG8_LAS unsigned char* lds, const Gemm g, const Sched& S, const Epi& E) {
;     ...
;             PG8_LDB(B0, 1, 0); PG8_LDB(B1, 1, 1); PG8_SCHED; PG8_LDA(At, 1, 0); PG8_STAGE(PG8_SA(0, 1), a2 + hstep, voffA); PG8_STAGE_S(0, s2);
;             PG8_WAIT_V89(); PG8_WAIT_L(0); PG8_BAR; PG8_MMA(0, 0, At, B0); PG8_MMA(0, 1, At, B1); PG8_BAR; PG8_SCHED;
	s_setprio 0
	s_add_i32 s76, 0, 0x18000
	v_add_u32_e32 v142, s76, v143
	s_add_i32 s77, 0, 0x1c000
	ds_read_b128 v[130:133], v142
	ds_read_b128 v[138:141], v142 offset:1024
	ds_read_b128 v[148:151], v142 offset:2048
	ds_read_b128 v[152:155], v142 offset:3072
	v_add_u32_e32 v142, s77, v143
	ds_read_b128 v[156:159], v142
	ds_read_b128 v[160:163], v142 offset:1024
	ds_read_b128 v[164:167], v142 offset:2048
	ds_read_b128 v[168:171], v142 offset:3072
	s_mov_b32 m0, s90
	ds_read_b128 v[172:175], v147 offset:32768
	ds_read_b128 v[180:183], v147 offset:33792
	ds_read_b128 v[184:187], v147 offset:34816
	ds_read_b128 v[188:191], v147 offset:35840
	ds_read_b128 v[192:195], v147 offset:36864
	ds_read_b128 v[196:199], v147 offset:37888
	ds_read_b128 v[200:203], v147 offset:38912
	ds_read_b128 v[210:213], v147 offset:39936
	s_add_u32 s60, s80, 0x80000
	s_addc_u32 s61, s81, 0
	global_load_lds_dwordx4 v134, s[60:61]
	s_mov_b32 m0, s91
	s_nop 0
	s_add_u32 s36, s80, 0xc0000
	s_addc_u32 s37, s81, 0
	global_load_lds_dwordx4 v134, s[36:37]
	s_waitcnt vmcnt(8)
	s_waitcnt lgkmcnt(0)
	s_setprio 1
	s_barrier
	v_mfma_f32_16x16x32_bf16 v[126:129], v[130:133], v[172:175], v[126:129]
	v_mfma_f32_16x16x32_bf16 v[126:129], v[138:141], v[180:183], v[126:129]
	v_mfma_f32_16x16x32_bf16 v[118:121], v[152:155], v[180:183], v[118:121]
	v_mfma_f32_16x16x32_bf16 v[118:121], v[148:151], v[172:175], v[118:121]
	v_mfma_f32_16x16x32_bf16 v[102:105], v[148:151], v[184:187], v[102:105]
	v_mfma_f32_16x16x32_bf16 v[102:105], v[152:155], v[188:191], v[102:105]
	v_mfma_f32_16x16x32_bf16 v[110:113], v[138:141], v[188:191], v[110:113]
	v_mfma_f32_16x16x32_bf16 v[110:113], v[130:133], v[184:187], v[110:113]
	v_mfma_f32_16x16x32_bf16 v[94:97], v[130:133], v[192:195], v[94:97]
	v_mfma_f32_16x16x32_bf16 v[94:97], v[138:141], v[196:199], v[94:97]
	v_mfma_f32_16x16x32_bf16 v[86:89], v[152:155], v[196:199], v[86:89]
	v_mfma_f32_16x16x32_bf16 v[86:89], v[148:151], v[192:195], v[86:89]
	v_mfma_f32_16x16x32_bf16 v[70:73], v[148:151], v[200:203], v[70:73]
	v_mfma_f32_16x16x32_bf16 v[70:73], v[152:155], v[210:213], v[70:73]
	v_mfma_f32_16x16x32_bf16 v[78:81], v[138:141], v[210:213], v[78:81]
	v_mfma_f32_16x16x32_bf16 v[78:81], v[130:133], v[200:203], v[78:81]
	s_setprio 0
	v_mfma_f32_16x16x32_bf16 v[66:69], v[164:167], v[200:203], v[66:69]
	v_mfma_f32_16x16x32_bf16 v[66:69], v[168:171], v[210:213], v[66:69]
	s_setprio 1
	v_mfma_f32_16x16x32_bf16 v[114:117], v[168:171], v[180:183], v[114:117]
	v_mfma_f32_16x16x32_bf16 v[114:117], v[164:167], v[172:175], v[114:117]
	v_mfma_f32_16x16x32_bf16 v[122:125], v[156:159], v[172:175], v[122:125]
	v_mfma_f32_16x16x32_bf16 v[122:125], v[160:163], v[180:183], v[122:125]
	v_mfma_f32_16x16x32_bf16 v[106:109], v[160:163], v[188:191], v[106:109]
	v_mfma_f32_16x16x32_bf16 v[106:109], v[156:159], v[184:187], v[106:109]
	v_mfma_f32_16x16x32_bf16 v[98:101], v[164:167], v[184:187], v[98:101]
	v_mfma_f32_16x16x32_bf16 v[98:101], v[168:171], v[188:191], v[98:101]
	v_mfma_f32_16x16x32_bf16 v[82:85], v[168:171], v[196:199], v[82:85]
	v_mfma_f32_16x16x32_bf16 v[82:85], v[164:167], v[192:195], v[82:85]
	v_mfma_f32_16x16x32_bf16 v[90:93], v[156:159], v[192:195], v[90:93]
	v_mfma_f32_16x16x32_bf16 v[90:93], v[160:163], v[196:199], v[90:93]
	v_mfma_f32_16x16x32_bf16 v[74:77], v[160:163], v[210:213], v[74:77]
	v_mfma_f32_16x16x32_bf16 v[74:77], v[156:159], v[200:203], v[74:77]
	s_barrier
; #define PG8_SB(B) __builtin_amdgcn_rcpf(1.f + expneg(B))
; #define PG8_SB(B) __builtin_amdgcn_rcpf(1.f + expneg(B))
; #define PG8_STAGE(bufoff, gbase, voff) do { _Pragma("unroll") for (int _i = 0; _i < 2; ++_i) \
;         __builtin_amdgcn_global_load_lds((const unsigned*)((const char*)(gbase) + (size_t)_i * qstep + (voff)[0]), (PG8_LAS unsigned*)(lds + (bufoff) + ldsw + _i * 8192), 16, 0, 0); } while (0)
; #define PG8_WAIT_L(n) asm volatile("s_waitcnt lgkmcnt(" #n ")" ::: "memory")
; template <class Epi, class Sched, bool ALIGN_EPI = false, bool SP2 = false, bool SLIVER = false>
; __device__ __forceinline__ void gemm_phase(PG8_LAS unsigned char* lds, const Gemm g, const Sched& S, const Epi& E) {
;     ...
;         for (int t = 0; t < nt; t += 2) {
;             const bool last = (t == nt - 2);
;             const char* a1 = cA + (size_t)(t + 1) * kstep;
;             const char* a2 = last ? nA : cA + (size_t)(t + 2) * kstep; const char* b2 = last ? nB : cB + (size_t)(t + 2) * kstep;
;             const char* a3 = a2 + kstep; const char* b3 = b2 + kstep;
;             const char* s1 = cS + (size_t)(t + 1) * kstep; const char* s2 = last ? nS : cS + (size_t)(t + 2) * kstep;
;             if (last && has_next) S.a_ready(nxt);
;             if constexpr (SP2) {
;             PG8_LDB(B0, 0, 0); PG8_LDB(B1, 0, 1); PG8_SCHED; PG8_LDA(At, 0, 0); PG8_STAGE(PG8_SA(1, 1), a1 + hstep, voffA); PG8_STAGE_S(1, s1);
;             PG8_WAIT_V89(); PG8_WAIT_L(0); PG8_BAR; PG8_MMA(0, 0, At, B0); PG8_MMA(0, 1, At, B1); PG8_BAR; PG8_SCHED;
;             PG8_LDA(At, 0, 1); PG8_LDS_S(0); PG8_STAGE(PG8_SB(0, 0), b2, voffB); PG8_STAGE(PG8_SB(0, 1), b2 + hstep, voffB); PG8_STAGE(PG8_SA(0, 0), a2, voffA);
;             PG8_WAIT_V89(); PG8_WAIT_L(0); PG8_BAR; PG8_MMA(1, 0, At, B0); PG8_MMA(1, 1, At, B1); PG8_MMA_S(); PG8_BAR; PG8_SCHED;
;             PG8_LDB(B0, 1, 0); PG8_LDB(B1, 1, 1); PG8_SCHED; PG8_LDA(At, 1, 0); PG8_STAGE(PG8_SA(0, 1), a2 + hstep, voffA); PG8_STAGE_S(0, s2);
;             PG8_WAIT_V89(); PG8_WAIT_L(0); PG8_BAR; PG8_MMA(0, 0, At, B0); PG8_MMA(0, 1, At, B1); PG8_BAR; PG8_SCHED;
;             PG8_LDA(At, 1, 1); PG8_LDS_S(1); PG8_STAGE(PG8_SB(1, 0), b3, voffB); PG8_STAGE(PG8_SB(1, 1), b3 + hstep, voffB); PG8_STAGE(PG8_SA(1, 0), a3, voffA);
;             PG8_WAIT_V89(); PG8_WAIT_L(0); PG8_BAR; PG8_MMA(1, 0, At, B0); PG8_MMA(1, 1, At, B1); PG8_MMA_S(); PG8_BAR; PG8_SCHED;
	s_setprio 0
	s_add_i32 s76, s76, s88
	s_mov_b32 m0, s76
	ds_read_b128 v[172:175], v147 offset:49152
	ds_read_b128 v[180:183], v147 offset:50176
	ds_read_b128 v[184:187], v147 offset:51200
	ds_read_b128 v[188:191], v147 offset:52224
	ds_read_b128 v[192:195], v147 offset:53248
	ds_read_b128 v[196:199], v147 offset:54272
	ds_read_b128 v[200:203], v147 offset:55296
	ds_read_b128 v[210:213], v147 offset:56320
	s_add_u32 s58, s46, 0x80
	s_addc_u32 s59, s47, 0
	global_load_lds_dwordx4 v178, s[58:59]
	s_add_i32 m0, s76, 0x2000
	s_add_i32 s76, s77, s88
	s_add_u32 s60, s46, 0x40080
	s_addc_u32 s61, s47, 0
	global_load_lds_dwordx4 v178, s[60:61]
	s_mov_b32 m0, s76
	s_add_u32 s36, s46, 0x80080
	s_addc_u32 s37, s47, 0
	global_load_lds_dwordx4 v178, s[36:37]
	s_add_i32 m0, s76, 0x2000
	s_nop 0
	s_add_u32 s58, s46, 0xc0080
	s_addc_u32 s59, s47, 0
	global_load_lds_dwordx4 v178, s[58:59]
	s_mov_b32 m0, s93
	s_nop 0
	s_add_u32 s60, s80, 0x80
	s_addc_u32 s61, s81, 0
	global_load_lds_dwordx4 v134, s[60:61]
	s_mov_b32 m0, s94
	s_nop 0
	s_add_u32 s36, s80, 0x40080
	s_addc_u32 s37, s81, 0
	global_load_lds_dwordx4 v134, s[36:37]
	s_waitcnt vmcnt(8)
	s_waitcnt lgkmcnt(0)
	s_setprio 1
	s_barrier
	v_mfma_f32_16x16x32_bf16 v[62:65], v[130:133], v[172:175], v[62:65]
	v_mfma_f32_16x16x32_bf16 v[62:65], v[138:141], v[180:183], v[62:65]
	v_mfma_f32_16x16x32_bf16 v[54:57], v[152:155], v[180:183], v[54:57]
	v_mfma_f32_16x16x32_bf16 v[54:57], v[148:151], v[172:175], v[54:57]
	v_mfma_f32_16x16x32_bf16 v[38:41], v[148:151], v[184:187], v[38:41]
	v_mfma_f32_16x16x32_bf16 v[38:41], v[152:155], v[188:191], v[38:41]
	v_mfma_f32_16x16x32_bf16 v[46:49], v[138:141], v[188:191], v[46:49]
	v_mfma_f32_16x16x32_bf16 v[46:49], v[130:133], v[184:187], v[46:49]
	v_mfma_f32_16x16x32_bf16 v[30:33], v[130:133], v[192:195], v[30:33]
	v_mfma_f32_16x16x32_bf16 v[30:33], v[138:141], v[196:199], v[30:33]
	v_mfma_f32_16x16x32_bf16 v[22:25], v[152:155], v[196:199], v[22:25]
	v_mfma_f32_16x16x32_bf16 v[22:25], v[148:151], v[192:195], v[22:25]
	v_mfma_f32_16x16x32_bf16 v[6:9], v[148:151], v[200:203], v[6:9]
	v_mfma_f32_16x16x32_bf16 v[6:9], v[152:155], v[210:213], v[6:9]
	v_mfma_f32_16x16x32_bf16 v[14:17], v[138:141], v[210:213], v[14:17]
	v_mfma_f32_16x16x32_bf16 v[14:17], v[130:133], v[200:203], v[14:17]
	s_setprio 0
	v_mfma_f32_16x16x32_bf16 v[2:5], v[164:167], v[200:203], v[2:5]
	v_mfma_f32_16x16x32_bf16 v[2:5], v[168:171], v[210:213], v[2:5]
	s_setprio 1
	v_mfma_f32_16x16x32_bf16 v[50:53], v[168:171], v[180:183], v[50:53]
	v_mfma_f32_16x16x32_bf16 v[50:53], v[164:167], v[172:175], v[50:53]
	v_mfma_f32_16x16x32_bf16 v[58:61], v[156:159], v[172:175], v[58:61]
	v_mfma_f32_16x16x32_bf16 v[58:61], v[160:163], v[180:183], v[58:61]
	v_mfma_f32_16x16x32_bf16 v[42:45], v[160:163], v[188:191], v[42:45]
	v_mfma_f32_16x16x32_bf16 v[42:45], v[156:159], v[184:187], v[42:45]
	v_mfma_f32_16x16x32_bf16 v[34:37], v[164:167], v[184:187], v[34:37]
	v_mfma_f32_16x16x32_bf16 v[34:37], v[168:171], v[188:191], v[34:37]
	v_mfma_f32_16x16x32_bf16 v[18:21], v[168:171], v[196:199], v[18:21]
	v_mfma_f32_16x16x32_bf16 v[18:21], v[164:167], v[192:195], v[18:21]
	v_mfma_f32_16x16x32_bf16 v[26:29], v[156:159], v[192:195], v[26:29]
	v_mfma_f32_16x16x32_bf16 v[26:29], v[160:163], v[196:199], v[26:29]
	v_mfma_f32_16x16x32_bf16 v[10:13], v[160:163], v[210:213], v[10:13]
	v_mfma_f32_16x16x32_bf16 v[10:13], v[156:159], v[200:203], v[10:13]
	s_barrier
	s_setprio 0
	s_add_i32 s69, s69, 2
	s_add_u32 s62, s62, 0x100
	s_addc_u32 s63, s63, 0
	s_add_u32 s67, s67, 0x100
	s_addc_u32 s68, s68, 0
	s_cmp_gt_u32 s69, 29
	s_cbranch_scc0 .LBB0_705
	s_and_b64 vcc, exec, s[42:43]
	s_cbranch_vccz .LBB0_708
	s_barrier

; #define PG8_STAGE(bufoff, gbase, voff) do { _Pragma("unroll") for (int _i = 0; _i < 2; ++_i) \
;         __builtin_amdgcn_global_load_lds((const unsigned*)((const char*)(gbase) + (size_t)_i * qstep + (voff)[0]), (PG8_LAS unsigned*)(lds + (bufoff) + ldsw + _i * 8192), 16, 0, 0); } while (0)
; #define PG8_LDA(dst, b, h) do { _Pragma("unroll") for (int m = 0; m < 4; ++m) _Pragma("unroll") for (int k = 0; k < 2; ++k) dst[m][k] = *(const PG8_LAS bf16x8*)(lds + PG8_SA(b, h) + aoff + m * 2048 + k * 1024); } while (0)
; #define PG8_LDB(dst, b, h) do { _Pragma("unroll") for (int n = 0; n < 2; ++n) _Pragma("unroll") for (int k = 0; k < 2; ++k) dst[n][k] = *(const PG8_LAS bf16x8*)(lds + PG8_SB(b, h) + boff + n * 2048 + k * 1024); } while (0)
; #define PG8_MMA(ai, bj, At, Bt) do { __builtin_amdgcn_s_setprio(1); _Pragma("unroll") for (int m = 0; m < 4; ++m) _Pragma("unroll") for (int n = 0; n < 2; ++n) _Pragma("unroll") for (int k = 0; k < 2; ++k) \
;         acc[ai][bj][m][n] = __builtin_amdgcn_mfma_f32_16x16x32_bf16(Bt[n][k], At[m][k], acc[ai][bj][m][n], 0, 0, 0); __builtin_amdgcn_s_setprio(0); } while (0)
; #define PG8_WAIT_V89() do { if constexpr (SLIVER) PG8_WAIT_V(9); else PG8_WAIT_V(8); } while (0)
; #define PG8_WAIT_L(n) asm volatile("s_waitcnt lgkmcnt(" #n ")" ::: "memory")
; #define PG8_BAR __builtin_amdgcn_s_barrier()
; #define PG8_SCHED __builtin_amdgcn_sched_barrier(0)
; template <class Epi, class Sched, bool ALIGN_EPI = false, bool SP2 = false, bool SLIVER = false>
; __device__ __forceinline__ void gemm_phase(PG8_LAS unsigned char* lds, const Gemm g, const Sched& S, const Epi& E) {
;     ...
;             const bool last = (t == nt - 2);
;             const char* a1 = cA + (size_t)(t + 1) * kstep;
;             const char* a2 = last ? nA : cA + (size_t)(t + 2) * kstep; const char* b2 = last ? nB : cB + (size_t)(t + 2) * kstep;
;             const char* a3 = a2 + kstep; const char* b3 = b2 + kstep;
;             const char* s1 = cS + (size_t)(t + 1) * kstep; const char* s2 = last ? nS : cS + (size_t)(t + 2) * kstep;
;             if (last && has_next) S.a_ready(nxt);
;             if constexpr (SP2) {
;             PG8_LDB(B0, 0, 0); PG8_LDB(B1, 0, 1); PG8_SCHED; PG8_LDA(At, 0, 0); PG8_STAGE(PG8_SA(1, 1), a1 + hstep, voffA); PG8_STAGE_S(1, s1);
;             PG8_WAIT_V89(); PG8_WAIT_L(0); PG8_BAR; PG8_MMA(0, 0, At, B0); PG8_MMA(0, 1, At, B1); PG8_BAR; PG8_SCHED;
.LBB0_811:
	s_add_u32 s13, s90, s62
	s_addc_u32 s40, s91, s63
	s_add_u32 s13, s13, 0x100
	s_addc_u32 s66, s40, 0
	s_add_u32 s68, s2, s62
	s_addc_u32 s67, s3, s63
	s_add_i32 s69, 0, 0x10000
	s_cmpk_eq_i32 s62, 0x2b00
	s_cselect_b64 s[80:81], -1, 0
	s_and_b64 s[40:41], s[80:81], exec
	s_cselect_b32 s41, s85, s66
	s_cselect_b32 s40, s84, s13
	v_add_u32_e32 v66, s69, v220
	s_cselect_b32 s67, s87, s67
	s_cselect_b32 s66, s86, s68
	s_add_i32 s13, 0, 0x14000
	ds_read_b128 v[154:157], v66
	ds_read_b128 v[158:161], v66 offset:1024
	ds_read_b128 v[162:165], v66 offset:2048
	ds_read_b128 v[174:177], v66 offset:3072
	v_add_u32_e32 v66, s13, v220
	ds_read_b128 v[184:187], v66
	ds_read_b128 v[188:191], v66 offset:1024
	ds_read_b128 v[192:195], v66 offset:2048
	ds_read_b128 v[180:183], v66 offset:3072
	v_lshl_add_u64 v[146:147], v[214:215], 0, s[62:63]
	v_lshl_add_u64 v[148:149], v[146:147], 0, s[8:9]
	s_add_i32 m0, s19, 0xc000
	s_mov_b64 s[94:95], 0x210080
	ds_read_b128 v[66:69], v223
	ds_read_b128 v[70:73], v223 offset:1024
	ds_read_b128 v[74:77], v223 offset:2048
	ds_read_b128 v[78:81], v223 offset:3072
	ds_read_b128 v[216:219], v223 offset:4096
	ds_read_b128 v[224:227], v223 offset:5120
	ds_read_b128 v[228:231], v223 offset:6144
	ds_read_b128 v[232:235], v223 offset:7168
	global_load_lds_dwordx4 v[148:149], off
	v_lshl_add_u64 v[146:147], v[146:147], 0, s[94:95]
	s_add_i32 m0, s19, 0xe000
	s_nop 0
	global_load_lds_dwordx4 v[146:147], off
	v_lshl_add_u64 v[146:147], v[212:213], 0, s[62:63]
	s_add_i32 m0, s96, 0x20800
	s_nop 0
	global_load_lds_dword v[146:147], off
	s_waitcnt vmcnt(9)
	s_waitcnt lgkmcnt(0)
	s_setprio 1
	s_barrier
	v_mfma_f32_16x16x32_bf16 v[146:149], v[154:157], v[66:69], v[170:173]
	v_mfma_f32_16x16x32_bf16 v[146:149], v[158:161], v[70:73], v[146:149]
	v_mfma_f32_16x16x32_bf16 v[150:153], v[162:165], v[66:69], v[166:169]
	v_mfma_f32_16x16x32_bf16 v[150:153], v[174:177], v[70:73], v[150:153]
	v_mfma_f32_16x16x32_bf16 v[134:137], v[154:157], v[74:77], v[134:137]
	v_mfma_f32_16x16x32_bf16 v[134:137], v[158:161], v[78:81], v[134:137]
	v_mfma_f32_16x16x32_bf16 v[130:133], v[162:165], v[74:77], v[130:133]
	v_mfma_f32_16x16x32_bf16 v[130:133], v[174:177], v[78:81], v[130:133]
	v_mfma_f32_16x16x32_bf16 v[118:121], v[154:157], v[216:219], v[118:121]
	v_mfma_f32_16x16x32_bf16 v[118:121], v[158:161], v[224:227], v[118:121]
	v_mfma_f32_16x16x32_bf16 v[114:117], v[162:165], v[216:219], v[114:117]
	v_mfma_f32_16x16x32_bf16 v[114:117], v[174:177], v[224:227], v[114:117]
	v_mfma_f32_16x16x32_bf16 v[102:105], v[154:157], v[228:231], v[102:105]
	v_mfma_f32_16x16x32_bf16 v[102:105], v[158:161], v[232:235], v[102:105]
	v_mfma_f32_16x16x32_bf16 v[98:101], v[162:165], v[228:231], v[98:101]
	v_mfma_f32_16x16x32_bf16 v[98:101], v[174:177], v[232:235], v[98:101]
	s_setprio 0
	v_mfma_f32_16x16x32_bf16 v[142:145], v[184:187], v[66:69], v[142:145]
	v_mfma_f32_16x16x32_bf16 v[142:145], v[188:191], v[70:73], v[142:145]
	s_setprio 1
	v_mfma_f32_16x16x32_bf16 v[66:69], v[192:195], v[66:69], v[138:141]
	v_mfma_f32_16x16x32_bf16 v[138:141], v[180:183], v[70:73], v[66:69]
	v_mfma_f32_16x16x32_bf16 v[66:69], v[184:187], v[74:77], v[126:129]
	v_mfma_f32_16x16x32_bf16 v[126:129], v[188:191], v[78:81], v[66:69]
	v_mfma_f32_16x16x32_bf16 v[66:69], v[192:195], v[74:77], v[122:125]
	v_mfma_f32_16x16x32_bf16 v[122:125], v[180:183], v[78:81], v[66:69]
	v_mfma_f32_16x16x32_bf16 v[66:69], v[184:187], v[216:219], v[110:113]
	v_mfma_f32_16x16x32_bf16 v[110:113], v[188:191], v[224:227], v[66:69]
	v_mfma_f32_16x16x32_bf16 v[66:69], v[192:195], v[216:219], v[106:109]
	v_mfma_f32_16x16x32_bf16 v[106:109], v[180:183], v[224:227], v[66:69]
	v_mfma_f32_16x16x32_bf16 v[66:69], v[184:187], v[228:231], v[94:97]
	v_mfma_f32_16x16x32_bf16 v[94:97], v[188:191], v[232:235], v[66:69]
	v_mfma_f32_16x16x32_bf16 v[66:69], v[192:195], v[228:231], v[90:93]
	v_mfma_f32_16x16x32_bf16 v[90:93], v[180:183], v[232:235], v[66:69]
	s_barrier
; #define PG8_SB(B) __builtin_amdgcn_rcpf(1.f + expneg(B))
; #define PG8_SB(B) __builtin_amdgcn_rcpf(1.f + expneg(B))
; #define PG8_STAGE(bufoff, gbase, voff) do { _Pragma("unroll") for (int _i = 0; _i < 2; ++_i) \
;         __builtin_amdgcn_global_load_lds((const unsigned*)((const char*)(gbase) + (size_t)_i * qstep + (voff)[0]), (PG8_LAS unsigned*)(lds + (bufoff) + ldsw + _i * 8192), 16, 0, 0); } while (0)
; #define PG8_LDA(dst, b, h) do { _Pragma("unroll") for (int m = 0; m < 4; ++m) _Pragma("unroll") for (int k = 0; k < 2; ++k) dst[m][k] = *(const PG8_LAS bf16x8*)(lds + PG8_SA(b, h) + aoff + m * 2048 + k * 1024); } while (0)
; #define PG8_MMA(ai, bj, At, Bt) do { __builtin_amdgcn_s_setprio(1); _Pragma("unroll") for (int m = 0; m < 4; ++m) _Pragma("unroll") for (int n = 0; n < 2; ++n) _Pragma("unroll") for (int k = 0; k < 2; ++k) \
;         acc[ai][bj][m][n] = __builtin_amdgcn_mfma_f32_16x16x32_bf16(Bt[n][k], At[m][k], acc[ai][bj][m][n], 0, 0, 0); __builtin_amdgcn_s_setprio(0); } while (0)
; #define PG8_WAIT_V89() do { if constexpr (SLIVER) PG8_WAIT_V(9); else PG8_WAIT_V(8); } while (0)
; #define PG8_LDS_S(b) do { if constexpr (SLIVER) { Sf[0] = *(const PG8_LAS bf16x8*)(lds + STAGE_BYTES + (b) * 2048 + soff0); Sf[1] = *(const PG8_LAS bf16x8*)(lds + STAGE_BYTES + (b) * 2048 + (soff0 ^ 64)); } } while (0)
; #define PG8_WAIT_L(n) asm volatile("s_waitcnt lgkmcnt(" #n ")" ::: "memory")
; #define PG8_BAR __builtin_amdgcn_s_barrier()
; #define PG8_SCHED __builtin_amdgcn_sched_barrier(0)
; template <class Epi, class Sched, bool ALIGN_EPI = false, bool SP2 = false, bool SLIVER = false>
; __device__ __forceinline__ void gemm_phase(PG8_LAS unsigned char* lds, const Gemm g, const Sched& S, const Epi& E) {
;     ...
;             PG8_LDA(At, 0, 1); PG8_LDS_S(0); PG8_STAGE(PG8_SB(0, 0), b2, voffB); PG8_STAGE(PG8_SB(0, 1), b2 + hstep, voffB); PG8_STAGE(PG8_SA(0, 0), a2, voffA);
;             PG8_WAIT_V89(); PG8_WAIT_L(0); PG8_BAR; PG8_MMA(1, 0, At, B0); PG8_MMA(1, 1, At, B1); PG8_MMA_S(); PG8_BAR; PG8_SCHED;
	s_setprio 0
	s_add_i32 s68, 0, 0x20000
	v_lshl_add_u64 v[216:217], s[66:67], 0, v[198:199]
	s_add_i32 s66, s69, s18
	v_add_u32_e32 v74, s68, v221
	v_add_u32_e32 v75, s68, v222
	s_mov_b32 m0, s66
	ds_read_b128 v[66:69], v223 offset:16384
	ds_read_b128 v[70:73], v223 offset:17408
	ds_read_b128 v[224:227], v223 offset:18432
	ds_read_b128 v[228:231], v223 offset:19456
	ds_read_b128 v[232:235], v223 offset:20480
	ds_read_b128 v[240:243], v223 offset:21504
	ds_read_b128 v[244:247], v223 offset:22528
	ds_read_b128 v[248:251], v223 offset:23552
	ds_read_b128 v[166:169], v74
	ds_read_b128 v[170:173], v75
	global_load_lds_dwordx4 v[216:217], off
	v_lshl_add_u64 v[74:75], v[216:217], 0, s[64:65]
	s_add_i32 m0, s66, 0x2000
	s_add_i32 s13, s13, s18
	global_load_lds_dwordx4 v[74:75], off
	v_lshl_add_u64 v[74:75], v[216:217], 0, s[0:1]
	s_mov_b32 m0, s13
	v_lshl_add_u64 v[218:219], s[40:41], 0, v[196:197]
	global_load_lds_dwordx4 v[74:75], off
	v_lshl_add_u64 v[74:75], v[216:217], 0, s[74:75]
	s_add_i32 m0, s13, 0x2000
	s_nop 0
	global_load_lds_dwordx4 v[74:75], off
	s_mov_b32 m0, s19
	v_lshl_add_u64 v[74:75], v[218:219], 0, s[64:65]
	global_load_lds_dwordx4 v[218:219], off
	s_mov_b32 m0, s52
	s_nop 0
	global_load_lds_dwordx4 v[74:75], off
	s_waitcnt vmcnt(9)
	s_waitcnt lgkmcnt(0)
	s_setprio 1
	s_barrier
	v_mfma_f32_16x16x32_bf16 v[74:77], v[154:157], v[66:69], v[86:89]
	v_mfma_f32_16x16x32_bf16 v[74:77], v[158:161], v[70:73], v[74:77]
	v_mfma_f32_16x16x32_bf16 v[78:81], v[162:165], v[66:69], v[82:85]
	v_mfma_f32_16x16x32_bf16 v[78:81], v[174:177], v[70:73], v[78:81]
	v_mfma_f32_16x16x32_bf16 v[54:57], v[154:157], v[224:227], v[54:57]
	v_mfma_f32_16x16x32_bf16 v[54:57], v[158:161], v[228:231], v[54:57]
	v_mfma_f32_16x16x32_bf16 v[50:53], v[162:165], v[224:227], v[50:53]
	v_mfma_f32_16x16x32_bf16 v[50:53], v[174:177], v[228:231], v[50:53]
	v_mfma_f32_16x16x32_bf16 v[38:41], v[154:157], v[232:235], v[38:41]
	v_mfma_f32_16x16x32_bf16 v[38:41], v[158:161], v[240:243], v[38:41]
	v_mfma_f32_16x16x32_bf16 v[34:37], v[162:165], v[232:235], v[34:37]
	v_mfma_f32_16x16x32_bf16 v[34:37], v[174:177], v[240:243], v[34:37]
	v_mfma_f32_16x16x32_bf16 v[22:25], v[154:157], v[244:247], v[22:25]
	v_mfma_f32_16x16x32_bf16 v[22:25], v[158:161], v[248:251], v[22:25]
	v_mfma_f32_16x16x32_bf16 v[18:21], v[162:165], v[244:247], v[18:21]
	v_mfma_f32_16x16x32_bf16 v[18:21], v[174:177], v[248:251], v[18:21]
	s_setprio 0
	v_mfma_f32_16x16x32_bf16 v[10:13], v[180:183], v[248:251], v[10:13]
	v_mfma_f32_16x16x32_bf16 v[10:13], v[192:195], v[244:247], v[10:13]
	s_setprio 1
	v_mfma_f32_16x16x32_bf16 v[58:61], v[192:195], v[66:69], v[58:61]
	v_mfma_f32_16x16x32_bf16 v[58:61], v[180:183], v[70:73], v[58:61]
	v_mfma_f32_16x16x32_bf16 v[62:65], v[188:191], v[70:73], v[62:65]
	v_mfma_f32_16x16x32_bf16 v[62:65], v[184:187], v[66:69], v[62:65]
	v_mfma_f32_16x16x32_bf16 v[46:49], v[184:187], v[224:227], v[46:49]
	v_mfma_f32_16x16x32_bf16 v[46:49], v[188:191], v[228:231], v[46:49]
	v_mfma_f32_16x16x32_bf16 v[42:45], v[180:183], v[228:231], v[42:45]
	v_mfma_f32_16x16x32_bf16 v[42:45], v[192:195], v[224:227], v[42:45]
	v_mfma_f32_16x16x32_bf16 v[26:29], v[192:195], v[232:235], v[26:29]
	v_mfma_f32_16x16x32_bf16 v[26:29], v[180:183], v[240:243], v[26:29]
	v_mfma_f32_16x16x32_bf16 v[30:33], v[188:191], v[240:243], v[30:33]
	v_mfma_f32_16x16x32_bf16 v[30:33], v[184:187], v[232:235], v[30:33]
	v_mfma_f32_16x16x32_bf16 v[14:17], v[184:187], v[244:247], v[14:17]
	v_mfma_f32_16x16x32_bf16 v[14:17], v[188:191], v[248:251], v[14:17]
	s_setprio 0
	s_setprio 1
	s_and_b64 vcc, exec, s[82:83]
	s_cbranch_vccz .Lslv_b2
	v_mfma_f32_16x16x32_bf16 v[66:69], v[184:187], v[166:169], v[6:9]
	v_mfma_f32_16x16x32_bf16 v[70:73], v[192:195], v[166:169], v[2:5]
	v_mfma_f32_16x16x32_bf16 v[66:69], v[188:191], v[170:173], v[66:69]
	v_mfma_f32_16x16x32_bf16 v[70:73], v[180:183], v[170:173], v[70:73]
	s_branch .LBB0_815

; #define PG8_STAGE(bufoff, gbase, voff) do { _Pragma("unroll") for (int _i = 0; _i < 2; ++_i) \
;         __builtin_amdgcn_global_load_lds((const unsigned*)((const char*)(gbase) + (size_t)_i * qstep + (voff)[0]), (PG8_LAS unsigned*)(lds + (bufoff) + ldsw + _i * 8192), 16, 0, 0); } while (0)
; #define PG8_LDA(dst, b, h) do { _Pragma("unroll") for (int m = 0; m < 4; ++m) _Pragma("unroll") for (int k = 0; k < 2; ++k) dst[m][k] = *(const PG8_LAS bf16x8*)(lds + PG8_SA(b, h) + aoff + m * 2048 + k * 1024); } while (0)
; #define PG8_LDB(dst, b, h) do { _Pragma("unroll") for (int n = 0; n < 2; ++n) _Pragma("unroll") for (int k = 0; k < 2; ++k) dst[n][k] = *(const PG8_LAS bf16x8*)(lds + PG8_SB(b, h) + boff + n * 2048 + k * 1024); } while (0)
; #define PG8_MMA(ai, bj, At, Bt) do { __builtin_amdgcn_s_setprio(1); _Pragma("unroll") for (int m = 0; m < 4; ++m) _Pragma("unroll") for (int n = 0; n < 2; ++n) _Pragma("unroll") for (int k = 0; k < 2; ++k) \
;         acc[ai][bj][m][n] = __builtin_amdgcn_mfma_f32_16x16x32_bf16(Bt[n][k], At[m][k], acc[ai][bj][m][n], 0, 0, 0); __builtin_amdgcn_s_setprio(0); } while (0)
; #define PG8_WAIT_V89() do { if constexpr (SLIVER) PG8_WAIT_V(9); else PG8_WAIT_V(8); } while (0)
; #define PG8_STAGE_S(b, gbase) do { if constexpr (SLIVER) __builtin_amdgcn_global_load_lds((const unsigned*)((const char*)(gbase) + voffS), (PG8_LAS unsigned*)(lds + STAGE_BYTES + (b) * 2048 + wid * 256), 4, 0, 0); } while (0)
; #define PG8_WAIT_L(n) asm volatile("s_waitcnt lgkmcnt(" #n ")" ::: "memory")
; #define PG8_BAR __builtin_amdgcn_s_barrier()
; #define PG8_SCHED __builtin_amdgcn_sched_barrier(0)
; template <class Epi, class Sched, bool ALIGN_EPI = false, bool SP2 = false, bool SLIVER = false>
; __device__ __forceinline__ void gemm_phase(PG8_LAS unsigned char* lds, const Gemm g, const Sched& S, const Epi& E) {
;     ...
;             PG8_LDB(B0, 1, 0); PG8_LDB(B1, 1, 1); PG8_SCHED; PG8_LDA(At, 1, 0); PG8_STAGE(PG8_SA(0, 1), a2 + hstep, voffA); PG8_STAGE_S(0, s2);
;             PG8_WAIT_V89(); PG8_WAIT_L(0); PG8_BAR; PG8_MMA(0, 0, At, B0); PG8_MMA(0, 1, At, B1); PG8_BAR; PG8_SCHED;
.LBB0_815:
	s_barrier
	s_setprio 0
	s_add_u32 s13, s92, s62
	s_addc_u32 s66, s93, s63
	s_add_u32 s13, s13, 0x100
	s_addc_u32 s68, s66, 0
	s_and_b64 s[66:67], s[80:81], exec
	s_cselect_b32 s67, s89, s68
	s_cselect_b32 s66, s88, s13
	s_add_i32 s13, 0, 0x18000
	v_add_u32_e32 v2, s13, v220
	s_add_i32 s68, 0, 0x1c000
	ds_read_b128 v[154:157], v2
	ds_read_b128 v[158:161], v2 offset:1024
	ds_read_b128 v[162:165], v2 offset:2048
	ds_read_b128 v[174:177], v2 offset:3072
	v_add_u32_e32 v2, s68, v220
	ds_read_b128 v[184:187], v2
	ds_read_b128 v[188:191], v2 offset:1024
	ds_read_b128 v[192:195], v2 offset:2048
	ds_read_b128 v[180:183], v2 offset:3072
	s_mov_b32 m0, s53
	v_lshl_add_u64 v[166:167], v[218:219], 0, s[0:1]
	ds_read_b128 v[2:5], v223 offset:32768
	ds_read_b128 v[6:9], v223 offset:33792
	ds_read_b128 v[82:85], v223 offset:34816
	ds_read_b128 v[86:89], v223 offset:35840
	ds_read_b128 v[224:227], v223 offset:36864
	ds_read_b128 v[228:231], v223 offset:37888
	ds_read_b128 v[232:235], v223 offset:38912
	ds_read_b128 v[240:243], v223 offset:39936
	global_load_lds_dwordx4 v[166:167], off
	v_lshl_add_u64 v[166:167], v[218:219], 0, s[74:75]
	s_mov_b32 m0, s54
	s_nop 0
	global_load_lds_dwordx4 v[166:167], off
	v_lshl_add_u64 v[166:167], s[66:67], 0, v[200:201]
	s_mov_b32 m0, s55
	s_nop 0
	global_load_lds_dword v[166:167], off
	s_waitcnt vmcnt(9)
	s_waitcnt lgkmcnt(0)
	s_setprio 1
	s_barrier
	v_mfma_f32_16x16x32_bf16 v[146:149], v[154:157], v[2:5], v[146:149]
	v_mfma_f32_16x16x32_bf16 v[170:173], v[158:161], v[6:9], v[146:149]
	v_mfma_f32_16x16x32_bf16 v[146:149], v[162:165], v[2:5], v[150:153]
	v_mfma_f32_16x16x32_bf16 v[166:169], v[174:177], v[6:9], v[146:149]
	v_mfma_f32_16x16x32_bf16 v[134:137], v[154:157], v[82:85], v[134:137]
	v_mfma_f32_16x16x32_bf16 v[134:137], v[158:161], v[86:89], v[134:137]
	v_mfma_f32_16x16x32_bf16 v[130:133], v[162:165], v[82:85], v[130:133]
	v_mfma_f32_16x16x32_bf16 v[130:133], v[174:177], v[86:89], v[130:133]
	v_mfma_f32_16x16x32_bf16 v[118:121], v[154:157], v[224:227], v[118:121]
	v_mfma_f32_16x16x32_bf16 v[118:121], v[158:161], v[228:231], v[118:121]
	v_mfma_f32_16x16x32_bf16 v[114:117], v[162:165], v[224:227], v[114:117]
	v_mfma_f32_16x16x32_bf16 v[114:117], v[174:177], v[228:231], v[114:117]
	v_mfma_f32_16x16x32_bf16 v[102:105], v[154:157], v[232:235], v[102:105]
	v_mfma_f32_16x16x32_bf16 v[102:105], v[158:161], v[240:243], v[102:105]
	v_mfma_f32_16x16x32_bf16 v[98:101], v[162:165], v[232:235], v[98:101]
	v_mfma_f32_16x16x32_bf16 v[98:101], v[174:177], v[240:243], v[98:101]
	s_setprio 0
	v_mfma_f32_16x16x32_bf16 v[142:145], v[184:187], v[2:5], v[142:145]
	v_mfma_f32_16x16x32_bf16 v[142:145], v[188:191], v[6:9], v[142:145]
	s_setprio 1
	v_mfma_f32_16x16x32_bf16 v[2:5], v[192:195], v[2:5], v[138:141]
	v_mfma_f32_16x16x32_bf16 v[138:141], v[180:183], v[6:9], v[2:5]
	v_mfma_f32_16x16x32_bf16 v[2:5], v[184:187], v[82:85], v[126:129]
	v_mfma_f32_16x16x32_bf16 v[126:129], v[188:191], v[86:89], v[2:5]
	v_mfma_f32_16x16x32_bf16 v[2:5], v[192:195], v[82:85], v[122:125]
	v_mfma_f32_16x16x32_bf16 v[122:125], v[180:183], v[86:89], v[2:5]
	v_mfma_f32_16x16x32_bf16 v[2:5], v[184:187], v[224:227], v[110:113]
	v_mfma_f32_16x16x32_bf16 v[110:113], v[188:191], v[228:231], v[2:5]
	v_mfma_f32_16x16x32_bf16 v[2:5], v[192:195], v[224:227], v[106:109]
	v_mfma_f32_16x16x32_bf16 v[106:109], v[180:183], v[228:231], v[2:5]
	v_mfma_f32_16x16x32_bf16 v[2:5], v[184:187], v[232:235], v[94:97]
	v_mfma_f32_16x16x32_bf16 v[94:97], v[188:191], v[240:243], v[2:5]
	v_mfma_f32_16x16x32_bf16 v[2:5], v[192:195], v[232:235], v[90:93]
	v_mfma_f32_16x16x32_bf16 v[90:93], v[180:183], v[240:243], v[2:5]
	s_barrier
; #define PG8_SB(B) __builtin_amdgcn_rcpf(1.f + expneg(B))
; #define PG8_SB(B) __builtin_amdgcn_rcpf(1.f + expneg(B))
; #define PG8_STAGE(bufoff, gbase, voff) do { _Pragma("unroll") for (int _i = 0; _i < 2; ++_i) \
;         __builtin_amdgcn_global_load_lds((const unsigned*)((const char*)(gbase) + (size_t)_i * qstep + (voff)[0]), (PG8_LAS unsigned*)(lds + (bufoff) + ldsw + _i * 8192), 16, 0, 0); } while (0)
; #define PG8_LDA(dst, b, h) do { _Pragma("unroll") for (int m = 0; m < 4; ++m) _Pragma("unroll") for (int k = 0; k < 2; ++k) dst[m][k] = *(const PG8_LAS bf16x8*)(lds + PG8_SA(b, h) + aoff + m * 2048 + k * 1024); } while (0)
; #define PG8_MMA(ai, bj, At, Bt) do { __builtin_amdgcn_s_setprio(1); _Pragma("unroll") for (int m = 0; m < 4; ++m) _Pragma("unroll") for (int n = 0; n < 2; ++n) _Pragma("unroll") for (int k = 0; k < 2; ++k) \
;         acc[ai][bj][m][n] = __builtin_amdgcn_mfma_f32_16x16x32_bf16(Bt[n][k], At[m][k], acc[ai][bj][m][n], 0, 0, 0); __builtin_amdgcn_s_setprio(0); } while (0)
; #define PG8_WAIT_V89() do { if constexpr (SLIVER) PG8_WAIT_V(9); else PG8_WAIT_V(8); } while (0)
; #define PG8_LDS_S(b) do { if constexpr (SLIVER) { Sf[0] = *(const PG8_LAS bf16x8*)(lds + STAGE_BYTES + (b) * 2048 + soff0); Sf[1] = *(const PG8_LAS bf16x8*)(lds + STAGE_BYTES + (b) * 2048 + (soff0 ^ 64)); } } while (0)
; #define PG8_WAIT_L(n) asm volatile("s_waitcnt lgkmcnt(" #n ")" ::: "memory")
; #define PG8_BAR __builtin_amdgcn_s_barrier()
; #define PG8_SCHED __builtin_amdgcn_sched_barrier(0)
; template <class Epi, class Sched, bool ALIGN_EPI = false, bool SP2 = false, bool SLIVER = false>
; __device__ __forceinline__ void gemm_phase(PG8_LAS unsigned char* lds, const Gemm g, const Sched& S, const Epi& E) {
;     ...
;             PG8_LDA(At, 1, 1); PG8_LDS_S(1); PG8_STAGE(PG8_SB(1, 0), b3, voffB); PG8_STAGE(PG8_SB(1, 1), b3 + hstep, voffB); PG8_STAGE(PG8_SA(1, 0), a3, voffA);
;             PG8_WAIT_V89(); PG8_WAIT_L(0); PG8_BAR; PG8_MMA(1, 0, At, B0); PG8_MMA(1, 1, At, B1); PG8_MMA_S(); PG8_BAR; PG8_SCHED;
	s_setprio 0
	s_add_i32 s66, 0, 0x20800
	v_add_u32_e32 v82, s66, v221
	v_add_u32_e32 v83, s66, v222
	s_add_i32 s13, s13, s18
	ds_read_b128 v[2:5], v223 offset:49152
	ds_read_b128 v[6:9], v223 offset:50176
	ds_read_b128 v[224:227], v223 offset:51200
	ds_read_b128 v[228:231], v223 offset:52224
	ds_read_b128 v[232:235], v223 offset:53248
	ds_read_b128 v[240:243], v223 offset:54272
	ds_read_b128 v[244:247], v223 offset:55296
	ds_read_b128 v[248:251], v223 offset:56320
	ds_read_b128 v[146:149], v82
	ds_read_b128 v[150:153], v83
	v_lshl_add_u64 v[82:83], v[216:217], 0, s[26:27]
	s_mov_b32 m0, s13
	s_mov_b64 s[66:67], 0x210080
	global_load_lds_dwordx4 v[82:83], off
	v_lshl_add_u64 v[82:83], v[216:217], 0, s[60:61]
	s_add_i32 m0, s13, 0x2000
	s_add_i32 s13, s68, s18
	global_load_lds_dwordx4 v[82:83], off
	v_lshl_add_u64 v[82:83], v[216:217], 0, s[8:9]
	s_mov_b32 m0, s13
	s_nop 0
	global_load_lds_dwordx4 v[82:83], off
	v_lshl_add_u64 v[82:83], v[216:217], 0, s[66:67]
	s_add_i32 m0, s13, 0x2000
	s_nop 0
	global_load_lds_dwordx4 v[82:83], off
	v_lshl_add_u64 v[82:83], v[218:219], 0, s[26:27]
	s_mov_b32 m0, s10
	s_nop 0
	global_load_lds_dwordx4 v[82:83], off
	v_lshl_add_u64 v[82:83], v[218:219], 0, s[60:61]
	s_mov_b32 m0, s48
	s_nop 0
	global_load_lds_dwordx4 v[82:83], off
	s_waitcnt vmcnt(9)
	s_waitcnt lgkmcnt(0)
	s_setprio 1
	s_barrier
	v_mfma_f32_16x16x32_bf16 v[74:77], v[154:157], v[2:5], v[74:77]
	v_mfma_f32_16x16x32_bf16 v[86:89], v[158:161], v[6:9], v[74:77]
	v_mfma_f32_16x16x32_bf16 v[74:77], v[162:165], v[2:5], v[78:81]
	v_mfma_f32_16x16x32_bf16 v[82:85], v[174:177], v[6:9], v[74:77]
	v_mfma_f32_16x16x32_bf16 v[54:57], v[154:157], v[224:227], v[54:57]
	v_mfma_f32_16x16x32_bf16 v[54:57], v[158:161], v[228:231], v[54:57]
	v_mfma_f32_16x16x32_bf16 v[50:53], v[162:165], v[224:227], v[50:53]
	v_mfma_f32_16x16x32_bf16 v[50:53], v[174:177], v[228:231], v[50:53]
	v_mfma_f32_16x16x32_bf16 v[38:41], v[154:157], v[232:235], v[38:41]
	v_mfma_f32_16x16x32_bf16 v[38:41], v[158:161], v[240:243], v[38:41]
	v_mfma_f32_16x16x32_bf16 v[34:37], v[162:165], v[232:235], v[34:37]
	v_mfma_f32_16x16x32_bf16 v[34:37], v[174:177], v[240:243], v[34:37]
	v_mfma_f32_16x16x32_bf16 v[22:25], v[154:157], v[244:247], v[22:25]
	v_mfma_f32_16x16x32_bf16 v[22:25], v[158:161], v[248:251], v[22:25]
	v_mfma_f32_16x16x32_bf16 v[18:21], v[162:165], v[244:247], v[18:21]
	v_mfma_f32_16x16x32_bf16 v[18:21], v[174:177], v[248:251], v[18:21]
	s_setprio 0
	v_mfma_f32_16x16x32_bf16 v[62:65], v[184:187], v[2:5], v[62:65]
	v_mfma_f32_16x16x32_bf16 v[62:65], v[188:191], v[6:9], v[62:65]
	s_setprio 1
	v_mfma_f32_16x16x32_bf16 v[2:5], v[192:195], v[2:5], v[58:61]
	v_mfma_f32_16x16x32_bf16 v[58:61], v[180:183], v[6:9], v[2:5]
	v_mfma_f32_16x16x32_bf16 v[2:5], v[184:187], v[224:227], v[46:49]
	v_mfma_f32_16x16x32_bf16 v[46:49], v[188:191], v[228:231], v[2:5]
	v_mfma_f32_16x16x32_bf16 v[2:5], v[192:195], v[224:227], v[42:45]
	v_mfma_f32_16x16x32_bf16 v[42:45], v[180:183], v[228:231], v[2:5]
	v_mfma_f32_16x16x32_bf16 v[2:5], v[184:187], v[232:235], v[30:33]
	v_mfma_f32_16x16x32_bf16 v[30:33], v[188:191], v[240:243], v[2:5]
	v_mfma_f32_16x16x32_bf16 v[2:5], v[192:195], v[232:235], v[26:29]
	v_mfma_f32_16x16x32_bf16 v[26:29], v[180:183], v[240:243], v[2:5]
	v_mfma_f32_16x16x32_bf16 v[2:5], v[184:187], v[244:247], v[14:17]
	v_mfma_f32_16x16x32_bf16 v[14:17], v[188:191], v[248:251], v[2:5]
	v_mfma_f32_16x16x32_bf16 v[2:5], v[192:195], v[244:247], v[10:13]
	v_mfma_f32_16x16x32_bf16 v[10:13], v[180:183], v[248:251], v[2:5]
	s_setprio 0
	s_setprio 1
	s_and_b64 vcc, exec, s[82:83]
	s_cbranch_vccz .Lslv_c2
	v_mfma_f32_16x16x32_bf16 v[2:5], v[184:187], v[146:149], v[66:69]
	v_mfma_f32_16x16x32_bf16 v[6:9], v[188:191], v[150:153], v[2:5]
	v_mfma_f32_16x16x32_bf16 v[2:5], v[192:195], v[146:149], v[70:73]
	v_mfma_f32_16x16x32_bf16 v[2:5], v[180:183], v[150:153], v[2:5]
	s_branch .LBB0_810

; #define PG8_STAGE(bufoff, gbase, voff) do { _Pragma("unroll") for (int _i = 0; _i < 2; ++_i) \
;         __builtin_amdgcn_global_load_lds((const unsigned*)((const char*)(gbase) + (size_t)_i * qstep + (voff)[0]), (PG8_LAS unsigned*)(lds + (bufoff) + ldsw + _i * 8192), 16, 0, 0); } while (0)
; #define PG8_LDA(dst, b, h) do { _Pragma("unroll") for (int m = 0; m < 4; ++m) _Pragma("unroll") for (int k = 0; k < 2; ++k) dst[m][k] = *(const PG8_LAS bf16x8*)(lds + PG8_SA(b, h) + aoff + m * 2048 + k * 1024); } while (0)
; #define PG8_LDB(dst, b, h) do { _Pragma("unroll") for (int n = 0; n < 2; ++n) _Pragma("unroll") for (int k = 0; k < 2; ++k) dst[n][k] = *(const PG8_LAS bf16x8*)(lds + PG8_SB(b, h) + boff + n * 2048 + k * 1024); } while (0)
; #define PG8_MMA(ai, bj, At, Bt) do { __builtin_amdgcn_s_setprio(1); _Pragma("unroll") for (int m = 0; m < 4; ++m) _Pragma("unroll") for (int n = 0; n < 2; ++n) _Pragma("unroll") for (int k = 0; k < 2; ++k) \
;         acc[ai][bj][m][n] = __builtin_amdgcn_mfma_f32_16x16x32_bf16(Bt[n][k], At[m][k], acc[ai][bj][m][n], 0, 0, 0); __builtin_amdgcn_s_setprio(0); } while (0)
; #define PG8_WAIT_V89() do { if constexpr (SLIVER) PG8_WAIT_V(9); else PG8_WAIT_V(8); } while (0)
; #define PG8_WAIT_L(n) asm volatile("s_waitcnt lgkmcnt(" #n ")" ::: "memory")
; #define PG8_BAR __builtin_amdgcn_s_barrier()
; #define PG8_SCHED __builtin_amdgcn_sched_barrier(0)
; template <class Epi, class Sched, bool ALIGN_EPI = false, bool SP2 = false, bool SLIVER = false>
; __device__ __forceinline__ void gemm_phase(PG8_LAS unsigned char* lds, const Gemm g, const Sched& S, const Epi& E) {
;     ...
;             const bool last = (t == nt - 2);
;             const char* a1 = cA + (size_t)(t + 1) * kstep;
;             const char* a2 = last ? nA : cA + (size_t)(t + 2) * kstep; const char* b2 = last ? nB : cB + (size_t)(t + 2) * kstep;
;             const char* a3 = a2 + kstep; const char* b3 = b2 + kstep;
;             const char* s1 = cS + (size_t)(t + 1) * kstep; const char* s2 = last ? nS : cS + (size_t)(t + 2) * kstep;
;             if (last && has_next) S.a_ready(nxt);
;             if constexpr (SP2) {
;             PG8_LDB(B0, 0, 0); PG8_LDB(B1, 0, 1); PG8_SCHED; PG8_LDA(At, 0, 0); PG8_STAGE(PG8_SA(1, 1), a1 + hstep, voffA); PG8_STAGE_S(1, s1);
;             PG8_WAIT_V89(); PG8_WAIT_L(0); PG8_BAR; PG8_MMA(0, 0, At, B0); PG8_MMA(0, 1, At, B1); PG8_BAR; PG8_SCHED;
.LBB0_934:
	s_cmp_eq_u32 s66, s62
	s_cselect_b64 s[80:81], -1, 0
	s_add_u32 s12, s42, s62
	s_addc_u32 s13, s43, s63
	s_add_u32 s40, s12, 0x100
	s_addc_u32 s41, s13, 0
	s_and_b64 s[12:13], s[80:81], exec
	s_cselect_b32 s41, s95, s41
	s_cselect_b32 s40, s94, s40
	s_add_u32 s68, s17, s62
	s_addc_u32 s69, s45, s63
	s_add_i32 s76, 0, 0x10000
	s_and_b64 s[12:13], s[80:81], exec
	v_add_u32_e32 v138, s76, v212
	s_cselect_b32 s13, s97, s69
	s_cselect_b32 s12, s96, s68
	s_add_i32 s68, 0, 0x14000
	ds_read_b128 v[146:149], v138
	ds_read_b128 v[150:153], v138 offset:1024
	ds_read_b128 v[154:157], v138 offset:2048
	ds_read_b128 v[158:161], v138 offset:3072
	v_add_u32_e32 v138, s68, v212
	ds_read_b128 v[166:169], v138
	ds_read_b128 v[170:173], v138 offset:1024
	ds_read_b128 v[174:177], v138 offset:2048
	ds_read_b128 v[162:165], v138 offset:3072
	v_lshl_add_u64 v[202:203], v[198:199], 0, s[62:63]
	s_mov_b64 vcc, 0x90080
	v_lshl_add_u64 v[208:209], v[202:203], 0, vcc
	s_add_i32 m0, s93, 0xc000
	s_mov_b64 vcc, 0xd8080
	ds_read_b128 v[138:141], v215
	ds_read_b128 v[142:145], v215 offset:1024
	ds_read_b128 v[180:183], v215 offset:2048
	ds_read_b128 v[184:187], v215 offset:3072
	ds_read_b128 v[216:219], v215 offset:4096
	ds_read_b128 v[220:223], v215 offset:5120
	ds_read_b128 v[224:227], v215 offset:6144
	ds_read_b128 v[228:231], v215 offset:7168
	global_load_lds_dwordx4 v[208:209], off
	v_lshl_add_u64 v[202:203], v[202:203], 0, vcc
	s_add_i32 m0, s93, 0xe000
	s_nop 0
	global_load_lds_dwordx4 v[202:203], off
	v_lshl_add_u64 v[202:203], v[200:201], 0, s[62:63]
	s_add_i32 m0, s50, 0x20800
	s_nop 0
	global_load_lds_dword v[202:203], off
	s_waitcnt vmcnt(9)
	s_waitcnt lgkmcnt(0)
	s_setprio 1
	s_barrier
	v_mfma_f32_16x16x32_bf16 v[134:137], v[146:149], v[138:141], v[134:137]
	v_mfma_f32_16x16x32_bf16 v[134:137], v[150:153], v[142:145], v[134:137]
	v_mfma_f32_16x16x32_bf16 v[130:133], v[158:161], v[142:145], v[130:133]
	v_mfma_f32_16x16x32_bf16 v[130:133], v[154:157], v[138:141], v[130:133]
	v_mfma_f32_16x16x32_bf16 v[122:125], v[154:157], v[180:183], v[122:125]
	v_mfma_f32_16x16x32_bf16 v[122:125], v[158:161], v[184:187], v[122:125]
	v_mfma_f32_16x16x32_bf16 v[126:129], v[150:153], v[184:187], v[126:129]
	v_mfma_f32_16x16x32_bf16 v[126:129], v[146:149], v[180:183], v[126:129]
	v_mfma_f32_16x16x32_bf16 v[114:117], v[146:149], v[216:219], v[114:117]
	v_mfma_f32_16x16x32_bf16 v[114:117], v[150:153], v[220:223], v[114:117]
	v_mfma_f32_16x16x32_bf16 v[106:109], v[158:161], v[220:223], v[106:109]
	v_mfma_f32_16x16x32_bf16 v[106:109], v[154:157], v[216:219], v[106:109]
	v_mfma_f32_16x16x32_bf16 v[90:93], v[154:157], v[224:227], v[90:93]
	v_mfma_f32_16x16x32_bf16 v[90:93], v[158:161], v[228:231], v[90:93]
	v_mfma_f32_16x16x32_bf16 v[98:101], v[150:153], v[228:231], v[98:101]
	v_mfma_f32_16x16x32_bf16 v[98:101], v[146:149], v[224:227], v[98:101]
	s_setprio 0
	v_mfma_f32_16x16x32_bf16 v[74:77], v[174:177], v[224:227], v[74:77]
	v_mfma_f32_16x16x32_bf16 v[74:77], v[162:165], v[228:231], v[74:77]
	s_setprio 1
	v_mfma_f32_16x16x32_bf16 v[110:113], v[162:165], v[142:145], v[110:113]
	v_mfma_f32_16x16x32_bf16 v[110:113], v[174:177], v[138:141], v[110:113]
	v_mfma_f32_16x16x32_bf16 v[118:121], v[166:169], v[138:141], v[118:121]
	v_mfma_f32_16x16x32_bf16 v[118:121], v[170:173], v[142:145], v[118:121]
	v_mfma_f32_16x16x32_bf16 v[102:105], v[170:173], v[184:187], v[102:105]
	v_mfma_f32_16x16x32_bf16 v[102:105], v[166:169], v[180:183], v[102:105]
	v_mfma_f32_16x16x32_bf16 v[94:97], v[174:177], v[180:183], v[94:97]
	v_mfma_f32_16x16x32_bf16 v[94:97], v[162:165], v[184:187], v[94:97]
	v_mfma_f32_16x16x32_bf16 v[82:85], v[162:165], v[220:223], v[82:85]
	v_mfma_f32_16x16x32_bf16 v[82:85], v[174:177], v[216:219], v[82:85]
	v_mfma_f32_16x16x32_bf16 v[86:89], v[166:169], v[216:219], v[86:89]
	v_mfma_f32_16x16x32_bf16 v[86:89], v[170:173], v[220:223], v[86:89]
	v_mfma_f32_16x16x32_bf16 v[78:81], v[170:173], v[228:231], v[78:81]
	v_mfma_f32_16x16x32_bf16 v[78:81], v[166:169], v[224:227], v[78:81]
	s_barrier
; #define PG8_SB(B) __builtin_amdgcn_rcpf(1.f + expneg(B))
; #define PG8_SB(B) __builtin_amdgcn_rcpf(1.f + expneg(B))
; #define PG8_STAGE(bufoff, gbase, voff) do { _Pragma("unroll") for (int _i = 0; _i < 2; ++_i) \
;         __builtin_amdgcn_global_load_lds((const unsigned*)((const char*)(gbase) + (size_t)_i * qstep + (voff)[0]), (PG8_LAS unsigned*)(lds + (bufoff) + ldsw + _i * 8192), 16, 0, 0); } while (0)
; #define PG8_LDA(dst, b, h) do { _Pragma("unroll") for (int m = 0; m < 4; ++m) _Pragma("unroll") for (int k = 0; k < 2; ++k) dst[m][k] = *(const PG8_LAS bf16x8*)(lds + PG8_SA(b, h) + aoff + m * 2048 + k * 1024); } while (0)
; #define PG8_MMA(ai, bj, At, Bt) do { __builtin_amdgcn_s_setprio(1); _Pragma("unroll") for (int m = 0; m < 4; ++m) _Pragma("unroll") for (int n = 0; n < 2; ++n) _Pragma("unroll") for (int k = 0; k < 2; ++k) \
;         acc[ai][bj][m][n] = __builtin_amdgcn_mfma_f32_16x16x32_bf16(Bt[n][k], At[m][k], acc[ai][bj][m][n], 0, 0, 0); __builtin_amdgcn_s_setprio(0); } while (0)
; #define PG8_WAIT_V89() do { if constexpr (SLIVER) PG8_WAIT_V(9); else PG8_WAIT_V(8); } while (0)
; #define PG8_LDS_S(b) do { if constexpr (SLIVER) { Sf[0] = *(const PG8_LAS bf16x8*)(lds + STAGE_BYTES + (b) * 2048 + soff0); Sf[1] = *(const PG8_LAS bf16x8*)(lds + STAGE_BYTES + (b) * 2048 + (soff0 ^ 64)); } } while (0)
; #define PG8_WAIT_L(n) asm volatile("s_waitcnt lgkmcnt(" #n ")" ::: "memory")
; #define PG8_BAR __builtin_amdgcn_s_barrier()
; #define PG8_SCHED __builtin_amdgcn_sched_barrier(0)
; template <class Epi, class Sched, bool ALIGN_EPI = false, bool SP2 = false, bool SLIVER = false>
; __device__ __forceinline__ void gemm_phase(PG8_LAS unsigned char* lds, const Gemm g, const Sched& S, const Epi& E) {
;     ...
;             PG8_LDA(At, 0, 1); PG8_LDS_S(0); PG8_STAGE(PG8_SB(0, 0), b2, voffB); PG8_STAGE(PG8_SB(0, 1), b2 + hstep, voffB); PG8_STAGE(PG8_SA(0, 0), a2, voffA);
;             PG8_WAIT_V89(); PG8_WAIT_L(0); PG8_BAR; PG8_MMA(1, 0, At, B0); PG8_MMA(1, 1, At, B1); PG8_MMA_S(); PG8_BAR; PG8_SCHED;
	s_setprio 0
	s_add_i32 s69, 0, 0x20000
	v_lshl_add_u64 v[202:203], s[12:13], 0, v[190:191]
	s_add_i32 s12, s76, s92
	v_add_u32_e32 v178, s69, v213
	v_add_u32_e32 v184, s69, v214
	s_mov_b32 m0, s12
	ds_read_b128 v[138:141], v215 offset:16384
	ds_read_b128 v[142:145], v215 offset:17408
	ds_read_b128 v[216:219], v215 offset:18432
	ds_read_b128 v[220:223], v215 offset:19456
	ds_read_b128 v[224:227], v215 offset:20480
	ds_read_b128 v[228:231], v215 offset:21504
	ds_read_b128 v[232:235], v215 offset:22528
	ds_read_b128 v[240:243], v215 offset:23552
	ds_read_b128 v[180:183], v178
	ds_read_b128 v[184:187], v184
	global_load_lds_dwordx4 v[202:203], off
	v_lshl_add_u64 v[208:209], v[202:203], 0, s[70:71]
	s_add_i32 m0, s12, 0x2000
	s_add_i32 s12, s68, s92
	global_load_lds_dwordx4 v[208:209], off
	v_lshl_add_u64 v[208:209], v[202:203], 0, s[46:47]
	s_mov_b32 m0, s12
	v_lshl_add_u64 v[210:211], s[40:41], 0, v[188:189]
	global_load_lds_dwordx4 v[208:209], off
	v_lshl_add_u64 v[208:209], v[202:203], 0, s[6:7]
	s_add_i32 m0, s12, 0x2000
	s_nop 0
	global_load_lds_dwordx4 v[208:209], off
	s_mov_b32 m0, s93
	v_lshl_add_u64 v[208:209], v[210:211], 0, s[70:71]
	global_load_lds_dwordx4 v[210:211], off
	s_mov_b32 m0, s48
	s_nop 0
	global_load_lds_dwordx4 v[208:209], off
	s_waitcnt vmcnt(9)
	s_waitcnt lgkmcnt(0)
	s_setprio 1
	s_barrier
	v_mfma_f32_16x16x32_bf16 v[70:73], v[146:149], v[138:141], v[70:73]
	v_mfma_f32_16x16x32_bf16 v[70:73], v[150:153], v[142:145], v[70:73]
	v_mfma_f32_16x16x32_bf16 v[66:69], v[158:161], v[142:145], v[66:69]
	v_mfma_f32_16x16x32_bf16 v[66:69], v[154:157], v[138:141], v[66:69]
	v_mfma_f32_16x16x32_bf16 v[58:61], v[154:157], v[216:219], v[58:61]
	v_mfma_f32_16x16x32_bf16 v[58:61], v[158:161], v[220:223], v[58:61]
	v_mfma_f32_16x16x32_bf16 v[62:65], v[150:153], v[220:223], v[62:65]
	v_mfma_f32_16x16x32_bf16 v[62:65], v[146:149], v[216:219], v[62:65]
	v_mfma_f32_16x16x32_bf16 v[50:53], v[146:149], v[224:227], v[50:53]
	v_mfma_f32_16x16x32_bf16 v[50:53], v[150:153], v[228:231], v[50:53]
	v_mfma_f32_16x16x32_bf16 v[42:45], v[158:161], v[228:231], v[42:45]
	v_mfma_f32_16x16x32_bf16 v[42:45], v[154:157], v[224:227], v[42:45]
	v_mfma_f32_16x16x32_bf16 v[26:29], v[154:157], v[232:235], v[26:29]
	v_mfma_f32_16x16x32_bf16 v[26:29], v[158:161], v[240:243], v[26:29]
	v_mfma_f32_16x16x32_bf16 v[34:37], v[150:153], v[240:243], v[34:37]
	v_mfma_f32_16x16x32_bf16 v[34:37], v[146:149], v[232:235], v[34:37]
	s_setprio 0
	v_mfma_f32_16x16x32_bf16 v[10:13], v[174:177], v[232:235], v[10:13]
	v_mfma_f32_16x16x32_bf16 v[10:13], v[162:165], v[240:243], v[10:13]
	s_setprio 1
	v_mfma_f32_16x16x32_bf16 v[46:49], v[162:165], v[142:145], v[46:49]
	v_mfma_f32_16x16x32_bf16 v[46:49], v[174:177], v[138:141], v[46:49]
	v_mfma_f32_16x16x32_bf16 v[54:57], v[166:169], v[138:141], v[54:57]
	v_mfma_f32_16x16x32_bf16 v[54:57], v[170:173], v[142:145], v[54:57]
	v_mfma_f32_16x16x32_bf16 v[38:41], v[170:173], v[220:223], v[38:41]
	v_mfma_f32_16x16x32_bf16 v[38:41], v[166:169], v[216:219], v[38:41]
	v_mfma_f32_16x16x32_bf16 v[30:33], v[174:177], v[216:219], v[30:33]
	v_mfma_f32_16x16x32_bf16 v[30:33], v[162:165], v[220:223], v[30:33]
	v_mfma_f32_16x16x32_bf16 v[18:21], v[162:165], v[228:231], v[18:21]
	v_mfma_f32_16x16x32_bf16 v[18:21], v[174:177], v[224:227], v[18:21]
	v_mfma_f32_16x16x32_bf16 v[22:25], v[166:169], v[224:227], v[22:25]
	v_mfma_f32_16x16x32_bf16 v[22:25], v[170:173], v[228:231], v[22:25]
	v_mfma_f32_16x16x32_bf16 v[14:17], v[170:173], v[240:243], v[14:17]
	v_mfma_f32_16x16x32_bf16 v[14:17], v[166:169], v[232:235], v[14:17]
	s_setprio 0
	s_setprio 1
	s_and_b64 vcc, exec, s[90:91]
	s_cbranch_vccz .Lslv_b3
	v_mfma_f32_16x16x32_bf16 v[138:141], v[166:169], v[180:183], v[6:9]
	v_mfma_f32_16x16x32_bf16 v[142:145], v[174:177], v[180:183], v[2:5]
	v_mfma_f32_16x16x32_bf16 v[138:141], v[170:173], v[184:187], v[138:141]
	v_mfma_f32_16x16x32_bf16 v[142:145], v[162:165], v[184:187], v[142:145]
	s_branch .LBB0_938

; #define PG8_STAGE(bufoff, gbase, voff) do { _Pragma("unroll") for (int _i = 0; _i < 2; ++_i) \
;         __builtin_amdgcn_global_load_lds((const unsigned*)((const char*)(gbase) + (size_t)_i * qstep + (voff)[0]), (PG8_LAS unsigned*)(lds + (bufoff) + ldsw + _i * 8192), 16, 0, 0); } while (0)
; #define PG8_LDA(dst, b, h) do { _Pragma("unroll") for (int m = 0; m < 4; ++m) _Pragma("unroll") for (int k = 0; k < 2; ++k) dst[m][k] = *(const PG8_LAS bf16x8*)(lds + PG8_SA(b, h) + aoff + m * 2048 + k * 1024); } while (0)
; #define PG8_LDB(dst, b, h) do { _Pragma("unroll") for (int n = 0; n < 2; ++n) _Pragma("unroll") for (int k = 0; k < 2; ++k) dst[n][k] = *(const PG8_LAS bf16x8*)(lds + PG8_SB(b, h) + boff + n * 2048 + k * 1024); } while (0)
; #define PG8_MMA(ai, bj, At, Bt) do { __builtin_amdgcn_s_setprio(1); _Pragma("unroll") for (int m = 0; m < 4; ++m) _Pragma("unroll") for (int n = 0; n < 2; ++n) _Pragma("unroll") for (int k = 0; k < 2; ++k) \
;         acc[ai][bj][m][n] = __builtin_amdgcn_mfma_f32_16x16x32_bf16(Bt[n][k], At[m][k], acc[ai][bj][m][n], 0, 0, 0); __builtin_amdgcn_s_setprio(0); } while (0)
; #define PG8_WAIT_V89() do { if constexpr (SLIVER) PG8_WAIT_V(9); else PG8_WAIT_V(8); } while (0)
; #define PG8_STAGE_S(b, gbase) do { if constexpr (SLIVER) __builtin_amdgcn_global_load_lds((const unsigned*)((const char*)(gbase) + voffS), (PG8_LAS unsigned*)(lds + STAGE_BYTES + (b) * 2048 + wid * 256), 4, 0, 0); } while (0)
; #define PG8_WAIT_L(n) asm volatile("s_waitcnt lgkmcnt(" #n ")" ::: "memory")
; #define PG8_BAR __builtin_amdgcn_s_barrier()
; #define PG8_SCHED __builtin_amdgcn_sched_barrier(0)
; template <class Epi, class Sched, bool ALIGN_EPI = false, bool SP2 = false, bool SLIVER = false>
; __device__ __forceinline__ void gemm_phase(PG8_LAS unsigned char* lds, const Gemm g, const Sched& S, const Epi& E) {
;     ...
;             PG8_LDB(B0, 1, 0); PG8_LDB(B1, 1, 1); PG8_SCHED; PG8_LDA(At, 1, 0); PG8_STAGE(PG8_SA(0, 1), a2 + hstep, voffA); PG8_STAGE_S(0, s2);
;             PG8_WAIT_V89(); PG8_WAIT_L(0); PG8_BAR; PG8_MMA(0, 0, At, B0); PG8_MMA(0, 1, At, B1); PG8_BAR; PG8_SCHED;
.LBB0_938:
	s_barrier
	s_setprio 0
	s_add_u32 s12, s54, s62
	s_addc_u32 s13, s55, s63
	s_add_u32 s68, s12, 0x100
	s_addc_u32 s69, s13, 0
	s_and_b64 s[12:13], s[80:81], exec
	s_cselect_b32 s13, s19, s69
	s_cselect_b32 s12, s18, s68
	s_add_i32 s68, 0, 0x18000
	v_add_u32_e32 v2, s68, v212
	s_add_i32 s69, 0, 0x1c000
	ds_read_b128 v[146:149], v2
	ds_read_b128 v[150:153], v2 offset:1024
	ds_read_b128 v[154:157], v2 offset:2048
	ds_read_b128 v[158:161], v2 offset:3072
	v_add_u32_e32 v2, s69, v212
	ds_read_b128 v[166:169], v2
	ds_read_b128 v[170:173], v2 offset:1024
	ds_read_b128 v[174:177], v2 offset:2048
	ds_read_b128 v[162:165], v2 offset:3072
	s_mov_b32 m0, s49
	v_lshl_add_u64 v[208:209], v[210:211], 0, s[46:47]
	ds_read_b128 v[2:5], v215 offset:32768
	ds_read_b128 v[6:9], v215 offset:33792
	ds_read_b128 v[180:183], v215 offset:34816
	ds_read_b128 v[184:187], v215 offset:35840
	ds_read_b128 v[216:219], v215 offset:36864
	ds_read_b128 v[220:223], v215 offset:37888
	ds_read_b128 v[224:227], v215 offset:38912
	ds_read_b128 v[228:231], v215 offset:39936
	global_load_lds_dwordx4 v[208:209], off
	v_lshl_add_u64 v[208:209], v[210:211], 0, s[6:7]
	s_mov_b32 m0, s88
	s_nop 0
	global_load_lds_dwordx4 v[208:209], off
	v_lshl_add_u64 v[208:209], s[12:13], 0, v[192:193]
	s_mov_b32 m0, s89
	s_nop 0
	global_load_lds_dword v[208:209], off
	s_waitcnt vmcnt(9)
	s_waitcnt lgkmcnt(0)
	s_setprio 1
	s_barrier
	v_mfma_f32_16x16x32_bf16 v[134:137], v[146:149], v[2:5], v[134:137]
	v_mfma_f32_16x16x32_bf16 v[134:137], v[150:153], v[6:9], v[134:137]
	v_mfma_f32_16x16x32_bf16 v[130:133], v[158:161], v[6:9], v[130:133]
	v_mfma_f32_16x16x32_bf16 v[130:133], v[154:157], v[2:5], v[130:133]
	v_mfma_f32_16x16x32_bf16 v[122:125], v[154:157], v[180:183], v[122:125]
	v_mfma_f32_16x16x32_bf16 v[122:125], v[158:161], v[184:187], v[122:125]
	v_mfma_f32_16x16x32_bf16 v[126:129], v[150:153], v[184:187], v[126:129]
	v_mfma_f32_16x16x32_bf16 v[126:129], v[146:149], v[180:183], v[126:129]
	v_mfma_f32_16x16x32_bf16 v[114:117], v[146:149], v[216:219], v[114:117]
	v_mfma_f32_16x16x32_bf16 v[114:117], v[150:153], v[220:223], v[114:117]
	v_mfma_f32_16x16x32_bf16 v[106:109], v[158:161], v[220:223], v[106:109]
	v_mfma_f32_16x16x32_bf16 v[106:109], v[154:157], v[216:219], v[106:109]
	v_mfma_f32_16x16x32_bf16 v[90:93], v[154:157], v[224:227], v[90:93]
	v_mfma_f32_16x16x32_bf16 v[90:93], v[158:161], v[228:231], v[90:93]
	v_mfma_f32_16x16x32_bf16 v[98:101], v[150:153], v[228:231], v[98:101]
	v_mfma_f32_16x16x32_bf16 v[98:101], v[146:149], v[224:227], v[98:101]
	s_setprio 0
	v_mfma_f32_16x16x32_bf16 v[118:121], v[166:169], v[2:5], v[118:121]
	v_mfma_f32_16x16x32_bf16 v[118:121], v[170:173], v[6:9], v[118:121]
	s_setprio 1
	v_mfma_f32_16x16x32_bf16 v[2:5], v[174:177], v[2:5], v[110:113]
	v_mfma_f32_16x16x32_bf16 v[110:113], v[162:165], v[6:9], v[2:5]
	v_mfma_f32_16x16x32_bf16 v[2:5], v[166:169], v[180:183], v[102:105]
	v_mfma_f32_16x16x32_bf16 v[102:105], v[170:173], v[184:187], v[2:5]
	v_mfma_f32_16x16x32_bf16 v[2:5], v[174:177], v[180:183], v[94:97]
	v_mfma_f32_16x16x32_bf16 v[94:97], v[162:165], v[184:187], v[2:5]
	v_mfma_f32_16x16x32_bf16 v[2:5], v[166:169], v[216:219], v[86:89]
	v_mfma_f32_16x16x32_bf16 v[86:89], v[170:173], v[220:223], v[2:5]
	v_mfma_f32_16x16x32_bf16 v[2:5], v[174:177], v[216:219], v[82:85]
	v_mfma_f32_16x16x32_bf16 v[82:85], v[162:165], v[220:223], v[2:5]
	v_mfma_f32_16x16x32_bf16 v[2:5], v[166:169], v[224:227], v[78:81]
	v_mfma_f32_16x16x32_bf16 v[78:81], v[170:173], v[228:231], v[2:5]
	v_mfma_f32_16x16x32_bf16 v[2:5], v[174:177], v[224:227], v[74:77]
	v_mfma_f32_16x16x32_bf16 v[74:77], v[162:165], v[228:231], v[2:5]
	s_barrier
; #define PG8_SB(B) __builtin_amdgcn_rcpf(1.f + expneg(B))
; #define PG8_SB(B) __builtin_amdgcn_rcpf(1.f + expneg(B))
; #define PG8_STAGE(bufoff, gbase, voff) do { _Pragma("unroll") for (int _i = 0; _i < 2; ++_i) \
;         __builtin_amdgcn_global_load_lds((const unsigned*)((const char*)(gbase) + (size_t)_i * qstep + (voff)[0]), (PG8_LAS unsigned*)(lds + (bufoff) + ldsw + _i * 8192), 16, 0, 0); } while (0)
; #define PG8_LDA(dst, b, h) do { _Pragma("unroll") for (int m = 0; m < 4; ++m) _Pragma("unroll") for (int k = 0; k < 2; ++k) dst[m][k] = *(const PG8_LAS bf16x8*)(lds + PG8_SA(b, h) + aoff + m * 2048 + k * 1024); } while (0)
; #define PG8_MMA(ai, bj, At, Bt) do { __builtin_amdgcn_s_setprio(1); _Pragma("unroll") for (int m = 0; m < 4; ++m) _Pragma("unroll") for (int n = 0; n < 2; ++n) _Pragma("unroll") for (int k = 0; k < 2; ++k) \
;         acc[ai][bj][m][n] = __builtin_amdgcn_mfma_f32_16x16x32_bf16(Bt[n][k], At[m][k], acc[ai][bj][m][n], 0, 0, 0); __builtin_amdgcn_s_setprio(0); } while (0)
; #define PG8_WAIT_V89() do { if constexpr (SLIVER) PG8_WAIT_V(9); else PG8_WAIT_V(8); } while (0)
; #define PG8_LDS_S(b) do { if constexpr (SLIVER) { Sf[0] = *(const PG8_LAS bf16x8*)(lds + STAGE_BYTES + (b) * 2048 + soff0); Sf[1] = *(const PG8_LAS bf16x8*)(lds + STAGE_BYTES + (b) * 2048 + (soff0 ^ 64)); } } while (0)
; #define PG8_WAIT_L(n) asm volatile("s_waitcnt lgkmcnt(" #n ")" ::: "memory")
; #define PG8_BAR __builtin_amdgcn_s_barrier()
; #define PG8_SCHED __builtin_amdgcn_sched_barrier(0)
; template <class Epi, class Sched, bool ALIGN_EPI = false, bool SP2 = false, bool SLIVER = false>
; __device__ __forceinline__ void gemm_phase(PG8_LAS unsigned char* lds, const Gemm g, const Sched& S, const Epi& E) {
;     ...
;             PG8_LDA(At, 1, 1); PG8_LDS_S(1); PG8_STAGE(PG8_SB(1, 0), b3, voffB); PG8_STAGE(PG8_SB(1, 1), b3 + hstep, voffB); PG8_STAGE(PG8_SA(1, 0), a3, voffA);
;             PG8_WAIT_V89(); PG8_WAIT_L(0); PG8_BAR; PG8_MMA(1, 0, At, B0); PG8_MMA(1, 1, At, B1); PG8_MMA_S(); PG8_BAR; PG8_SCHED;
	s_setprio 0
	s_add_i32 s12, 0, 0x20800
	v_add_u32_e32 v178, s12, v213
	v_add_u32_e32 v184, s12, v214
	s_add_i32 s12, s68, s92
	v_lshl_add_u64 v[208:209], v[202:203], 0, s[26:27]
	s_mov_b32 m0, s12
	ds_read_b128 v[2:5], v215 offset:49152
	ds_read_b128 v[6:9], v215 offset:50176
	ds_read_b128 v[216:219], v215 offset:51200
	ds_read_b128 v[220:223], v215 offset:52224
	ds_read_b128 v[224:227], v215 offset:53248
	ds_read_b128 v[228:231], v215 offset:54272
	ds_read_b128 v[232:235], v215 offset:55296
	ds_read_b128 v[240:243], v215 offset:56320
	ds_read_b128 v[180:183], v178
	ds_read_b128 v[184:187], v184
	global_load_lds_dwordx4 v[208:209], off
	v_lshl_add_u64 v[208:209], v[202:203], 0, s[58:59]
	s_add_i32 m0, s12, 0x2000
	s_mov_b64 s[12:13], 0x90080
	global_load_lds_dwordx4 v[208:209], off
	v_lshl_add_u64 v[208:209], v[202:203], 0, s[12:13]
	s_add_i32 s12, s69, s92
	s_mov_b32 m0, s12
	s_mov_b64 s[68:69], 0xd8080
	global_load_lds_dwordx4 v[208:209], off
	v_lshl_add_u64 v[202:203], v[202:203], 0, s[68:69]
	s_add_i32 m0, s12, 0x2000
	s_nop 0
	global_load_lds_dwordx4 v[202:203], off
	v_lshl_add_u64 v[202:203], v[210:211], 0, s[26:27]
	s_mov_b32 m0, s51
	s_nop 0
	global_load_lds_dwordx4 v[202:203], off
	v_lshl_add_u64 v[202:203], v[210:211], 0, s[58:59]
	s_mov_b32 m0, s53
	s_nop 0
	global_load_lds_dwordx4 v[202:203], off
	s_waitcnt vmcnt(9)
	s_waitcnt lgkmcnt(0)
	s_setprio 1
	s_barrier
	v_mfma_f32_16x16x32_bf16 v[70:73], v[146:149], v[2:5], v[70:73]
	v_mfma_f32_16x16x32_bf16 v[70:73], v[150:153], v[6:9], v[70:73]
	v_mfma_f32_16x16x32_bf16 v[66:69], v[158:161], v[6:9], v[66:69]
	v_mfma_f32_16x16x32_bf16 v[66:69], v[154:157], v[2:5], v[66:69]
	v_mfma_f32_16x16x32_bf16 v[58:61], v[154:157], v[216:219], v[58:61]
	v_mfma_f32_16x16x32_bf16 v[58:61], v[158:161], v[220:223], v[58:61]
	v_mfma_f32_16x16x32_bf16 v[62:65], v[150:153], v[220:223], v[62:65]
	v_mfma_f32_16x16x32_bf16 v[62:65], v[146:149], v[216:219], v[62:65]
	v_mfma_f32_16x16x32_bf16 v[50:53], v[146:149], v[224:227], v[50:53]
	v_mfma_f32_16x16x32_bf16 v[50:53], v[150:153], v[228:231], v[50:53]
	v_mfma_f32_16x16x32_bf16 v[42:45], v[158:161], v[228:231], v[42:45]
	v_mfma_f32_16x16x32_bf16 v[42:45], v[154:157], v[224:227], v[42:45]
	v_mfma_f32_16x16x32_bf16 v[26:29], v[154:157], v[232:235], v[26:29]
	v_mfma_f32_16x16x32_bf16 v[26:29], v[158:161], v[240:243], v[26:29]
	v_mfma_f32_16x16x32_bf16 v[34:37], v[150:153], v[240:243], v[34:37]
	v_mfma_f32_16x16x32_bf16 v[34:37], v[146:149], v[232:235], v[34:37]
	s_setprio 0
	v_mfma_f32_16x16x32_bf16 v[54:57], v[166:169], v[2:5], v[54:57]
	v_mfma_f32_16x16x32_bf16 v[54:57], v[170:173], v[6:9], v[54:57]
	s_setprio 1
	v_mfma_f32_16x16x32_bf16 v[2:5], v[174:177], v[2:5], v[46:49]
	v_mfma_f32_16x16x32_bf16 v[46:49], v[162:165], v[6:9], v[2:5]
	v_mfma_f32_16x16x32_bf16 v[2:5], v[166:169], v[216:219], v[38:41]
	v_mfma_f32_16x16x32_bf16 v[38:41], v[170:173], v[220:223], v[2:5]
	v_mfma_f32_16x16x32_bf16 v[2:5], v[174:177], v[216:219], v[30:33]
	v_mfma_f32_16x16x32_bf16 v[30:33], v[162:165], v[220:223], v[2:5]
	v_mfma_f32_16x16x32_bf16 v[2:5], v[166:169], v[224:227], v[22:25]
	v_mfma_f32_16x16x32_bf16 v[22:25], v[170:173], v[228:231], v[2:5]
	v_mfma_f32_16x16x32_bf16 v[2:5], v[174:177], v[224:227], v[18:21]
	v_mfma_f32_16x16x32_bf16 v[18:21], v[162:165], v[228:231], v[2:5]
	v_mfma_f32_16x16x32_bf16 v[2:5], v[166:169], v[232:235], v[14:17]
	v_mfma_f32_16x16x32_bf16 v[14:17], v[170:173], v[240:243], v[2:5]
	v_mfma_f32_16x16x32_bf16 v[2:5], v[174:177], v[232:235], v[10:13]
	v_mfma_f32_16x16x32_bf16 v[10:13], v[162:165], v[240:243], v[2:5]
	s_setprio 0
	s_setprio 1
	s_and_b64 vcc, exec, s[90:91]
	s_cbranch_vccz .Lslv_c3
	v_mfma_f32_16x16x32_bf16 v[2:5], v[166:169], v[180:183], v[138:141]
	v_mfma_f32_16x16x32_bf16 v[6:9], v[170:173], v[184:187], v[2:5]
	v_mfma_f32_16x16x32_bf16 v[2:5], v[174:177], v[180:183], v[142:145]
	v_mfma_f32_16x16x32_bf16 v[2:5], v[162:165], v[184:187], v[2:5]
	s_branch .LBB0_933
